# GEMM K-loops: LDS-DMA loads use SGPR-base form where the address is not reused (removes 64-bit VALU adds)
# speedup vs baseline: 1.0113x; 1.0069x over previous
.LBB0_297:
	s_add_u32 s22, s20, 0xfffc0080
	s_addc_u32 s23, s21, -1
	s_add_i32 s49, 0, 0x10000
	v_add_u32_e32 v145, s49, v142
	ds_read_b128 v[146:149], v145
	ds_read_b128 v[150:153], v145 offset:1024
	ds_read_b128 v[154:157], v145 offset:2048
	ds_read_b128 v[158:161], v145 offset:3072
	s_cmp_eq_u32 s48, 12
	s_cselect_b32 s25, s9, s23
	s_cselect_b32 s24, s44, s22
	s_cselect_b32 s23, s7, s47
	s_cselect_b32 s22, s45, s46
	s_add_i32 m0, s19, 0xc000
	ds_read_b128 v[162:165], v144
	ds_read_b128 v[166:169], v144 offset:1024
	ds_read_b128 v[170:173], v144 offset:2048
	ds_read_b128 v[174:177], v144 offset:3072
	ds_read_b128 v[190:193], v144 offset:4096
	ds_read_b128 v[194:197], v144 offset:5120
	ds_read_b128 v[198:201], v144 offset:6144
	ds_read_b128 v[202:205], v144 offset:7168
	global_load_lds_dwordx4 v138, s[20:21]
	s_add_i32 m0, s19, 0xe000
	s_nop 0
	global_load_lds_dwordx4 v140, s[20:21]
	s_waitcnt lgkmcnt(8)
	s_barrier
	s_waitcnt lgkmcnt(0)
	s_setprio 1
	s_waitcnt lgkmcnt(0)
	v_mfma_f32_16x16x32_bf16 v[126:129], v[146:149], v[162:165], v[126:129]
	v_mfma_f32_16x16x32_bf16 v[118:121], v[154:157], v[162:165], v[118:121]
	v_mfma_f32_16x16x32_bf16 v[110:113], v[146:149], v[170:173], v[110:113]
	v_mfma_f32_16x16x32_bf16 v[102:105], v[154:157], v[170:173], v[102:105]
	v_mfma_f32_16x16x32_bf16 v[94:97], v[146:149], v[190:193], v[94:97]
	v_mfma_f32_16x16x32_bf16 v[86:89], v[154:157], v[190:193], v[86:89]
	v_mfma_f32_16x16x32_bf16 v[78:81], v[146:149], v[198:201], v[78:81]
	v_mfma_f32_16x16x32_bf16 v[70:73], v[154:157], v[198:201], v[70:73]
	v_mfma_f32_16x16x32_bf16 v[126:129], v[150:153], v[166:169], v[126:129]
	v_mfma_f32_16x16x32_bf16 v[118:121], v[158:161], v[166:169], v[118:121]
	v_mfma_f32_16x16x32_bf16 v[110:113], v[150:153], v[174:177], v[110:113]
	v_mfma_f32_16x16x32_bf16 v[102:105], v[158:161], v[174:177], v[102:105]
	v_mfma_f32_16x16x32_bf16 v[94:97], v[150:153], v[194:197], v[94:97]
	v_mfma_f32_16x16x32_bf16 v[86:89], v[158:161], v[194:197], v[86:89]
	v_mfma_f32_16x16x32_bf16 v[78:81], v[150:153], v[202:205], v[78:81]
	v_mfma_f32_16x16x32_bf16 v[70:73], v[158:161], v[202:205], v[70:73]
	s_setprio 0
	s_barrier
	s_add_i32 s54, 0, 0x14000
	s_add_i32 s49, s49, s35
	v_add_u32_e32 v145, s54, v142
	v_lshl_add_u64 v[186:187], s[22:23], 0, v[134:135]
	s_mov_b32 m0, s49
	ds_read_b128 v[206:209], v145
	ds_read_b128 v[210:213], v145 offset:1024
	ds_read_b128 v[214:217], v145 offset:2048
	ds_read_b128 v[218:221], v145 offset:3072
	global_load_lds_dwordx4 v[186:187], off
	v_lshl_add_u64 v[188:189], s[22:23], 0, v[130:131]
	s_add_i32 m0, s49, 0x2000
	s_nop 0
	global_load_lds_dwordx4 v[188:189], off
	s_barrier
	s_waitcnt lgkmcnt(0)
	s_setprio 1
	s_waitcnt lgkmcnt(0)
	v_mfma_f32_16x16x32_bf16 v[122:125], v[206:209], v[162:165], v[122:125]
	v_mfma_f32_16x16x32_bf16 v[114:117], v[214:217], v[162:165], v[114:117]
	v_mfma_f32_16x16x32_bf16 v[106:109], v[206:209], v[170:173], v[106:109]
	v_mfma_f32_16x16x32_bf16 v[98:101], v[214:217], v[170:173], v[98:101]
	v_mfma_f32_16x16x32_bf16 v[90:93], v[206:209], v[190:193], v[90:93]
	v_mfma_f32_16x16x32_bf16 v[82:85], v[214:217], v[190:193], v[82:85]
	v_mfma_f32_16x16x32_bf16 v[74:77], v[206:209], v[198:201], v[74:77]
	v_mfma_f32_16x16x32_bf16 v[66:69], v[214:217], v[198:201], v[66:69]
	v_mfma_f32_16x16x32_bf16 v[122:125], v[210:213], v[166:169], v[122:125]
	v_mfma_f32_16x16x32_bf16 v[114:117], v[218:221], v[166:169], v[114:117]
	v_mfma_f32_16x16x32_bf16 v[106:109], v[210:213], v[174:177], v[106:109]
	v_mfma_f32_16x16x32_bf16 v[98:101], v[218:221], v[174:177], v[98:101]
	v_mfma_f32_16x16x32_bf16 v[90:93], v[210:213], v[194:197], v[90:93]
	v_mfma_f32_16x16x32_bf16 v[82:85], v[218:221], v[194:197], v[82:85]
	v_mfma_f32_16x16x32_bf16 v[74:77], v[210:213], v[202:205], v[74:77]
	v_mfma_f32_16x16x32_bf16 v[66:69], v[218:221], v[202:205], v[66:69]
	s_setprio 0
	s_mov_b32 m0, s19
	v_lshl_add_u64 v[222:223], s[24:25], 0, v[136:137]
	s_barrier
	ds_read_b128 v[162:165], v144 offset:16384
	ds_read_b128 v[166:169], v144 offset:17408
	ds_read_b128 v[170:173], v144 offset:18432
	ds_read_b128 v[174:177], v144 offset:19456
	ds_read_b128 v[190:193], v144 offset:20480
	ds_read_b128 v[194:197], v144 offset:21504
	ds_read_b128 v[198:201], v144 offset:22528
	ds_read_b128 v[202:205], v144 offset:23552
	global_load_lds_dwordx4 v[222:223], off
	v_lshl_add_u64 v[224:225], s[24:25], 0, v[132:133]
	s_mov_b32 m0, s36
	s_nop 0
	global_load_lds_dwordx4 v[224:225], off
	s_barrier
	s_waitcnt lgkmcnt(0)
	s_setprio 1
	s_waitcnt lgkmcnt(0)
	v_mfma_f32_16x16x32_bf16 v[62:65], v[146:149], v[162:165], v[62:65]
	v_mfma_f32_16x16x32_bf16 v[54:57], v[154:157], v[162:165], v[54:57]
	v_mfma_f32_16x16x32_bf16 v[46:49], v[146:149], v[170:173], v[46:49]
	v_mfma_f32_16x16x32_bf16 v[38:41], v[154:157], v[170:173], v[38:41]
	v_mfma_f32_16x16x32_bf16 v[30:33], v[146:149], v[190:193], v[30:33]
	v_mfma_f32_16x16x32_bf16 v[22:25], v[154:157], v[190:193], v[22:25]
	v_mfma_f32_16x16x32_bf16 v[14:17], v[146:149], v[198:201], v[14:17]
	v_mfma_f32_16x16x32_bf16 v[6:9], v[154:157], v[198:201], v[6:9]
	v_mfma_f32_16x16x32_bf16 v[62:65], v[150:153], v[166:169], v[62:65]
	v_mfma_f32_16x16x32_bf16 v[54:57], v[158:161], v[166:169], v[54:57]
	v_mfma_f32_16x16x32_bf16 v[46:49], v[150:153], v[174:177], v[46:49]
	v_mfma_f32_16x16x32_bf16 v[38:41], v[158:161], v[174:177], v[38:41]
	v_mfma_f32_16x16x32_bf16 v[30:33], v[150:153], v[194:197], v[30:33]
	v_mfma_f32_16x16x32_bf16 v[22:25], v[158:161], v[194:197], v[22:25]
	v_mfma_f32_16x16x32_bf16 v[14:17], v[150:153], v[202:205], v[14:17]
	v_mfma_f32_16x16x32_bf16 v[6:9], v[158:161], v[202:205], v[6:9]
	s_setprio 0
	s_barrier
	s_add_u32 s50, s22, 0x40000
	s_addc_u32 s51, s23, 0
	s_add_i32 s49, s54, s35
	s_mov_b32 m0, s49
	s_nop 0
	global_load_lds_dwordx4 v134, s[50:51]
	s_add_i32 m0, s49, 0x2000
	s_nop 0
	global_load_lds_dwordx4 v130, s[50:51]
	s_waitcnt vmcnt(6)
	s_barrier
	s_setprio 1
	v_mfma_f32_16x16x32_bf16 v[58:61], v[206:209], v[162:165], v[58:61]
	v_mfma_f32_16x16x32_bf16 v[50:53], v[214:217], v[162:165], v[50:53]
	v_mfma_f32_16x16x32_bf16 v[42:45], v[206:209], v[170:173], v[42:45]
	v_mfma_f32_16x16x32_bf16 v[34:37], v[214:217], v[170:173], v[34:37]
	v_mfma_f32_16x16x32_bf16 v[26:29], v[206:209], v[190:193], v[26:29]
	v_mfma_f32_16x16x32_bf16 v[18:21], v[214:217], v[190:193], v[18:21]
	v_mfma_f32_16x16x32_bf16 v[10:13], v[206:209], v[198:201], v[10:13]
	v_mfma_f32_16x16x32_bf16 v[2:5], v[214:217], v[198:201], v[2:5]
	v_mfma_f32_16x16x32_bf16 v[58:61], v[210:213], v[166:169], v[58:61]
	v_mfma_f32_16x16x32_bf16 v[50:53], v[218:221], v[166:169], v[50:53]
	v_mfma_f32_16x16x32_bf16 v[42:45], v[210:213], v[174:177], v[42:45]
	v_mfma_f32_16x16x32_bf16 v[34:37], v[218:221], v[174:177], v[34:37]
	v_mfma_f32_16x16x32_bf16 v[26:29], v[210:213], v[194:197], v[26:29]
	v_mfma_f32_16x16x32_bf16 v[18:21], v[218:221], v[194:197], v[18:21]
	v_mfma_f32_16x16x32_bf16 v[10:13], v[210:213], v[202:205], v[10:13]
	v_mfma_f32_16x16x32_bf16 v[2:5], v[218:221], v[202:205], v[2:5]
	s_setprio 0
	s_add_i32 s49, 0, 0x18000
	v_add_u32_e32 v145, s49, v142
	s_barrier
	ds_read_b128 v[146:149], v145
	ds_read_b128 v[150:153], v145 offset:1024
	ds_read_b128 v[154:157], v145 offset:2048
	ds_read_b128 v[158:161], v145 offset:3072
	s_add_u32 s24, s24, 0x40000
	s_addc_u32 s25, s25, 0
	s_mov_b32 m0, s37
	ds_read_b128 v[162:165], v144 offset:32768
	ds_read_b128 v[166:169], v144 offset:33792
	ds_read_b128 v[170:173], v144 offset:34816
	ds_read_b128 v[174:177], v144 offset:35840
	ds_read_b128 v[190:193], v144 offset:36864
	ds_read_b128 v[194:197], v144 offset:37888
	ds_read_b128 v[198:201], v144 offset:38912
	ds_read_b128 v[202:205], v144 offset:39936
	global_load_lds_dwordx4 v136, s[24:25]
	s_mov_b32 m0, s38
	s_nop 0
	global_load_lds_dwordx4 v132, s[24:25]
	s_waitcnt lgkmcnt(8)
	s_barrier
	s_waitcnt lgkmcnt(0)
	s_setprio 1
	s_waitcnt lgkmcnt(0)
	v_mfma_f32_16x16x32_bf16 v[126:129], v[146:149], v[162:165], v[126:129]
	v_mfma_f32_16x16x32_bf16 v[118:121], v[154:157], v[162:165], v[118:121]
	v_mfma_f32_16x16x32_bf16 v[110:113], v[146:149], v[170:173], v[110:113]
	v_mfma_f32_16x16x32_bf16 v[102:105], v[154:157], v[170:173], v[102:105]
	v_mfma_f32_16x16x32_bf16 v[94:97], v[146:149], v[190:193], v[94:97]
	v_mfma_f32_16x16x32_bf16 v[86:89], v[154:157], v[190:193], v[86:89]
	v_mfma_f32_16x16x32_bf16 v[78:81], v[146:149], v[198:201], v[78:81]
	v_mfma_f32_16x16x32_bf16 v[70:73], v[154:157], v[198:201], v[70:73]
	v_mfma_f32_16x16x32_bf16 v[126:129], v[150:153], v[166:169], v[126:129]
	v_mfma_f32_16x16x32_bf16 v[118:121], v[158:161], v[166:169], v[118:121]
	v_mfma_f32_16x16x32_bf16 v[110:113], v[150:153], v[174:177], v[110:113]
	v_mfma_f32_16x16x32_bf16 v[102:105], v[158:161], v[174:177], v[102:105]
	v_mfma_f32_16x16x32_bf16 v[94:97], v[150:153], v[194:197], v[94:97]
	v_mfma_f32_16x16x32_bf16 v[86:89], v[158:161], v[194:197], v[86:89]
	v_mfma_f32_16x16x32_bf16 v[78:81], v[150:153], v[202:205], v[78:81]
	v_mfma_f32_16x16x32_bf16 v[70:73], v[158:161], v[202:205], v[70:73]
	s_setprio 0
	s_barrier
	s_add_i32 s24, 0, 0x1c000
	s_add_i32 s25, s49, s35
	v_add_u32_e32 v145, s24, v142
	v_lshl_add_u64 v[186:187], v[186:187], 0, s[0:1]
	s_mov_b32 m0, s25
	ds_read_b128 v[206:209], v145
	ds_read_b128 v[210:213], v145 offset:1024
	ds_read_b128 v[214:217], v145 offset:2048
	ds_read_b128 v[218:221], v145 offset:3072
	global_load_lds_dwordx4 v[186:187], off
	v_lshl_add_u64 v[186:187], v[188:189], 0, s[0:1]
	s_add_i32 m0, s25, 0x2000
	s_nop 0
	global_load_lds_dwordx4 v[186:187], off
	s_barrier
	s_waitcnt lgkmcnt(0)
	s_setprio 1
	s_waitcnt lgkmcnt(0)
	v_mfma_f32_16x16x32_bf16 v[122:125], v[206:209], v[162:165], v[122:125]
	v_mfma_f32_16x16x32_bf16 v[114:117], v[214:217], v[162:165], v[114:117]
	v_mfma_f32_16x16x32_bf16 v[106:109], v[206:209], v[170:173], v[106:109]
	v_mfma_f32_16x16x32_bf16 v[98:101], v[214:217], v[170:173], v[98:101]
	v_mfma_f32_16x16x32_bf16 v[90:93], v[206:209], v[190:193], v[90:93]
	v_mfma_f32_16x16x32_bf16 v[82:85], v[214:217], v[190:193], v[82:85]
	v_mfma_f32_16x16x32_bf16 v[74:77], v[206:209], v[198:201], v[74:77]
	v_mfma_f32_16x16x32_bf16 v[66:69], v[214:217], v[198:201], v[66:69]
	v_mfma_f32_16x16x32_bf16 v[122:125], v[210:213], v[166:169], v[122:125]
	v_mfma_f32_16x16x32_bf16 v[114:117], v[218:221], v[166:169], v[114:117]
	v_mfma_f32_16x16x32_bf16 v[106:109], v[210:213], v[174:177], v[106:109]
	v_mfma_f32_16x16x32_bf16 v[98:101], v[218:221], v[174:177], v[98:101]
	v_mfma_f32_16x16x32_bf16 v[90:93], v[210:213], v[194:197], v[90:93]
	v_mfma_f32_16x16x32_bf16 v[82:85], v[218:221], v[194:197], v[82:85]
	v_mfma_f32_16x16x32_bf16 v[74:77], v[210:213], v[202:205], v[74:77]
	v_mfma_f32_16x16x32_bf16 v[66:69], v[218:221], v[202:205], v[66:69]
	s_setprio 0
	s_mov_b32 m0, s39
	v_lshl_add_u64 v[186:187], v[222:223], 0, s[0:1]
	s_barrier
	ds_read_b128 v[162:165], v144 offset:49152
	ds_read_b128 v[166:169], v144 offset:50176
	ds_read_b128 v[170:173], v144 offset:51200
	ds_read_b128 v[174:177], v144 offset:52224
	ds_read_b128 v[190:193], v144 offset:53248
	ds_read_b128 v[194:197], v144 offset:54272
	ds_read_b128 v[198:201], v144 offset:55296
	ds_read_b128 v[202:205], v144 offset:56320
	global_load_lds_dwordx4 v[186:187], off
	v_lshl_add_u64 v[186:187], v[224:225], 0, s[0:1]
	s_mov_b32 m0, s40
	s_nop 0
	global_load_lds_dwordx4 v[186:187], off
	s_barrier
	s_waitcnt lgkmcnt(0)
	s_setprio 1
	s_waitcnt lgkmcnt(0)
	v_mfma_f32_16x16x32_bf16 v[62:65], v[146:149], v[162:165], v[62:65]
	v_mfma_f32_16x16x32_bf16 v[54:57], v[154:157], v[162:165], v[54:57]
	v_mfma_f32_16x16x32_bf16 v[46:49], v[146:149], v[170:173], v[46:49]
	v_mfma_f32_16x16x32_bf16 v[38:41], v[154:157], v[170:173], v[38:41]
	v_mfma_f32_16x16x32_bf16 v[30:33], v[146:149], v[190:193], v[30:33]
	v_mfma_f32_16x16x32_bf16 v[22:25], v[154:157], v[190:193], v[22:25]
	v_mfma_f32_16x16x32_bf16 v[14:17], v[146:149], v[198:201], v[14:17]
	v_mfma_f32_16x16x32_bf16 v[6:9], v[154:157], v[198:201], v[6:9]
	v_mfma_f32_16x16x32_bf16 v[62:65], v[150:153], v[166:169], v[62:65]
	v_mfma_f32_16x16x32_bf16 v[54:57], v[158:161], v[166:169], v[54:57]
	v_mfma_f32_16x16x32_bf16 v[46:49], v[150:153], v[174:177], v[46:49]
	v_mfma_f32_16x16x32_bf16 v[38:41], v[158:161], v[174:177], v[38:41]
	v_mfma_f32_16x16x32_bf16 v[30:33], v[150:153], v[194:197], v[30:33]
	v_mfma_f32_16x16x32_bf16 v[22:25], v[158:161], v[194:197], v[22:25]
	v_mfma_f32_16x16x32_bf16 v[14:17], v[150:153], v[202:205], v[14:17]
	v_mfma_f32_16x16x32_bf16 v[6:9], v[158:161], v[202:205], v[6:9]
	s_setprio 0
	s_barrier
	s_add_u32 s22, s22, 0x40080
	s_addc_u32 s23, s23, 0
	s_add_i32 s24, s24, s35
	s_mov_b32 m0, s24
	s_nop 0
	global_load_lds_dwordx4 v134, s[22:23]
	s_add_i32 m0, s24, 0x2000
	s_nop 0
	global_load_lds_dwordx4 v130, s[22:23]
	s_waitcnt vmcnt(6)
	s_barrier
	s_setprio 1
	v_mfma_f32_16x16x32_bf16 v[58:61], v[206:209], v[162:165], v[58:61]
	v_mfma_f32_16x16x32_bf16 v[50:53], v[214:217], v[162:165], v[50:53]
	v_mfma_f32_16x16x32_bf16 v[42:45], v[206:209], v[170:173], v[42:45]
	v_mfma_f32_16x16x32_bf16 v[34:37], v[214:217], v[170:173], v[34:37]
	v_mfma_f32_16x16x32_bf16 v[26:29], v[206:209], v[190:193], v[26:29]
	v_mfma_f32_16x16x32_bf16 v[18:21], v[214:217], v[190:193], v[18:21]
	v_mfma_f32_16x16x32_bf16 v[10:13], v[206:209], v[198:201], v[10:13]
	v_mfma_f32_16x16x32_bf16 v[2:5], v[214:217], v[198:201], v[2:5]
	v_mfma_f32_16x16x32_bf16 v[58:61], v[210:213], v[166:169], v[58:61]
	v_mfma_f32_16x16x32_bf16 v[50:53], v[218:221], v[166:169], v[50:53]
	v_mfma_f32_16x16x32_bf16 v[42:45], v[210:213], v[174:177], v[42:45]
	v_mfma_f32_16x16x32_bf16 v[34:37], v[218:221], v[174:177], v[34:37]
	v_mfma_f32_16x16x32_bf16 v[26:29], v[210:213], v[194:197], v[26:29]
	v_mfma_f32_16x16x32_bf16 v[18:21], v[218:221], v[194:197], v[18:21]
	v_mfma_f32_16x16x32_bf16 v[10:13], v[210:213], v[202:205], v[10:13]
	v_mfma_f32_16x16x32_bf16 v[2:5], v[218:221], v[202:205], v[2:5]
	s_setprio 0
	s_add_i32 s48, s48, 2
	s_add_u32 s20, s20, 0x100
	s_addc_u32 s21, s21, 0
	s_add_u32 s46, s46, 0x100
	s_addc_u32 s47, s47, 0
	s_cmp_gt_u32 s48, 13
	s_barrier
	s_cbranch_scc0 .LBB0_297
	v_mul_f32_e32 v148, 0xbfb8aa3b, v126
	v_mul_f32_e32 v149, 0xbfb8aa3b, v127
	v_exp_f32_e32 v148, v148
	v_exp_f32_e32 v149, v149
	v_lshl_or_b32 v146, s43, 7, v143
	v_lshl_add_u32 v145, s18, 8, v1
	v_add_f32_e32 v148, 1.0, v148
	v_add_f32_e32 v149, 1.0, v149
	v_rcp_f32_e32 v148, v148
	v_rcp_f32_e32 v149, v149
	v_ashrrev_i32_e32 v147, 31, v146
	s_movk_i32 s7, 0x1700
	s_and_b64 vcc, exec, s[4:5]
	v_pk_mul_f32 v[126:127], v[126:127], v[148:149]
	s_mov_b32 s43, s6
	v_pk_mul_f32 v[122:123], v[126:127], v[122:123]
	v_mul_f32_e32 v126, 0xbfb8aa3b, v128
	v_mul_f32_e32 v127, 0xbfb8aa3b, v129
	v_exp_f32_e32 v126, v126
	v_exp_f32_e32 v127, v127
	s_mov_b32 s18, s8
	s_mov_b64 s[22:23], s[14:15]
	v_add_f32_e32 v126, 1.0, v126
	v_add_f32_e32 v127, 1.0, v127
	v_rcp_f32_e32 v126, v126
	v_rcp_f32_e32 v127, v127
	s_nop 0
	v_pk_mul_f32 v[126:127], v[128:129], v[126:127]
	s_nop 0
	v_pk_mul_f32 v[124:125], v[126:127], v[124:125]
	v_mul_f32_e32 v126, 0xbfb8aa3b, v118
	v_mul_f32_e32 v127, 0xbfb8aa3b, v119
	v_exp_f32_e32 v126, v126
	v_exp_f32_e32 v127, v127
	v_add_f32_e32 v126, 1.0, v126
	v_add_f32_e32 v127, 1.0, v127
	v_rcp_f32_e32 v126, v126
	v_rcp_f32_e32 v127, v127
	s_nop 0
	v_pk_mul_f32 v[118:119], v[118:119], v[126:127]
	s_nop 0
	v_pk_mul_f32 v[114:115], v[118:119], v[114:115]
	v_mul_f32_e32 v118, 0xbfb8aa3b, v120
	v_mul_f32_e32 v119, 0xbfb8aa3b, v121
	v_exp_f32_e32 v118, v118
	v_exp_f32_e32 v119, v119
	v_add_f32_e32 v118, 1.0, v118
	v_add_f32_e32 v119, 1.0, v119
	v_rcp_f32_e32 v118, v118
	v_rcp_f32_e32 v119, v119
	s_nop 0
	v_pk_mul_f32 v[118:119], v[120:121], v[118:119]
	s_nop 0
	v_pk_mul_f32 v[116:117], v[118:119], v[116:117]
	v_cvt_pk_bf16_f32 v120, v114, v115
	v_mov_b64_e32 v[114:115], s[2:3]
	v_cvt_pk_bf16_f32 v118, v122, v123
	v_cvt_pk_bf16_f32 v121, v116, v117
	v_mad_i64_i32 v[122:123], s[20:21], v145, s7, v[114:115]
	v_lshlrev_b64 v[116:117], 1, v[146:147]
	v_cvt_pk_bf16_f32 v119, v124, v125
	v_lshl_add_u64 v[122:123], v[122:123], 0, v[116:117]
	global_store_dwordx4 v[122:123], v[118:121], off
	s_nop 1
	v_mul_f32_e32 v118, 0xbfb8aa3b, v110
	v_mul_f32_e32 v119, 0xbfb8aa3b, v111
	v_exp_f32_e32 v118, v118
	v_exp_f32_e32 v119, v119
	v_add_f32_e32 v118, 1.0, v118
	v_add_f32_e32 v119, 1.0, v119
	v_rcp_f32_e32 v118, v118
	v_rcp_f32_e32 v119, v119
	s_nop 0
	v_pk_mul_f32 v[110:111], v[110:111], v[118:119]
	s_nop 0
	v_pk_mul_f32 v[106:107], v[110:111], v[106:107]
	v_mul_f32_e32 v110, 0xbfb8aa3b, v112
	v_mul_f32_e32 v111, 0xbfb8aa3b, v113
	v_exp_f32_e32 v110, v110
	v_exp_f32_e32 v111, v111
	v_add_f32_e32 v110, 1.0, v110
	v_add_f32_e32 v111, 1.0, v111
	v_rcp_f32_e32 v110, v110
	v_rcp_f32_e32 v111, v111
	s_nop 0
	v_pk_mul_f32 v[110:111], v[112:113], v[110:111]
	s_nop 0
	v_pk_mul_f32 v[108:109], v[110:111], v[108:109]
	v_mul_f32_e32 v110, 0xbfb8aa3b, v102
	v_mul_f32_e32 v111, 0xbfb8aa3b, v103
	v_exp_f32_e32 v110, v110
	v_exp_f32_e32 v111, v111
	v_add_f32_e32 v110, 1.0, v110
	v_add_f32_e32 v111, 1.0, v111
	v_rcp_f32_e32 v110, v110
	v_rcp_f32_e32 v111, v111
	s_nop 0
	v_pk_mul_f32 v[102:103], v[102:103], v[110:111]
	s_nop 0
	v_pk_mul_f32 v[102:103], v[102:103], v[98:99]
	v_mul_f32_e32 v98, 0xbfb8aa3b, v104
	v_mul_f32_e32 v99, 0xbfb8aa3b, v105
	v_exp_f32_e32 v98, v98
	v_exp_f32_e32 v99, v99
	v_add_f32_e32 v98, 1.0, v98
	v_add_f32_e32 v99, 1.0, v99
	v_rcp_f32_e32 v98, v98
	v_rcp_f32_e32 v99, v99
	s_nop 0
	v_pk_mul_f32 v[98:99], v[104:105], v[98:99]
	s_nop 0
	v_pk_mul_f32 v[104:105], v[98:99], v[100:101]
	v_cvt_pk_bf16_f32 v100, v102, v103
	v_or_b32_e32 v102, 16, v145
	v_mad_i64_i32 v[102:103], s[20:21], v102, s7, v[114:115]
	v_cvt_pk_bf16_f32 v98, v106, v107
	v_cvt_pk_bf16_f32 v99, v108, v109
	v_cvt_pk_bf16_f32 v101, v104, v105
	v_lshl_add_u64 v[102:103], v[102:103], 0, v[116:117]
	global_store_dwordx4 v[102:103], v[98:101], off
	s_nop 1
	v_mul_f32_e32 v98, 0xbfb8aa3b, v94
	v_mul_f32_e32 v99, 0xbfb8aa3b, v95
	v_exp_f32_e32 v98, v98
	v_exp_f32_e32 v99, v99
	v_add_f32_e32 v98, 1.0, v98
	v_add_f32_e32 v99, 1.0, v99
	v_rcp_f32_e32 v98, v98
	v_rcp_f32_e32 v99, v99
	s_nop 0
	v_pk_mul_f32 v[94:95], v[94:95], v[98:99]
	s_nop 0
	v_pk_mul_f32 v[90:91], v[94:95], v[90:91]
	v_mul_f32_e32 v94, 0xbfb8aa3b, v96
	v_mul_f32_e32 v95, 0xbfb8aa3b, v97
	v_exp_f32_e32 v94, v94
	v_exp_f32_e32 v95, v95
	v_add_f32_e32 v94, 1.0, v94
	v_add_f32_e32 v95, 1.0, v95
	v_rcp_f32_e32 v94, v94
	v_rcp_f32_e32 v95, v95
	s_nop 0
	v_pk_mul_f32 v[94:95], v[96:97], v[94:95]
	s_nop 0
	v_pk_mul_f32 v[92:93], v[94:95], v[92:93]
	v_mul_f32_e32 v94, 0xbfb8aa3b, v86
	v_mul_f32_e32 v95, 0xbfb8aa3b, v87
	v_exp_f32_e32 v94, v94
	v_exp_f32_e32 v95, v95
	v_add_f32_e32 v94, 1.0, v94
	v_add_f32_e32 v95, 1.0, v95
	v_rcp_f32_e32 v94, v94
	v_rcp_f32_e32 v95, v95
	s_nop 0
	v_pk_mul_f32 v[86:87], v[86:87], v[94:95]
	s_nop 0
	v_pk_mul_f32 v[86:87], v[86:87], v[82:83]
	v_mul_f32_e32 v82, 0xbfb8aa3b, v88
	v_mul_f32_e32 v83, 0xbfb8aa3b, v89
	v_exp_f32_e32 v82, v82
	v_exp_f32_e32 v83, v83
	v_add_f32_e32 v82, 1.0, v82
	v_add_f32_e32 v83, 1.0, v83
	v_rcp_f32_e32 v82, v82
	v_rcp_f32_e32 v83, v83
	s_nop 0
	v_pk_mul_f32 v[82:83], v[88:89], v[82:83]
	s_nop 0
	v_pk_mul_f32 v[88:89], v[82:83], v[84:85]
	v_cvt_pk_bf16_f32 v84, v86, v87
	v_or_b32_e32 v86, 32, v145
	v_mad_i64_i32 v[86:87], s[20:21], v86, s7, v[114:115]
	v_cvt_pk_bf16_f32 v82, v90, v91
	v_cvt_pk_bf16_f32 v83, v92, v93
	v_cvt_pk_bf16_f32 v85, v88, v89
	v_lshl_add_u64 v[86:87], v[86:87], 0, v[116:117]
	global_store_dwordx4 v[86:87], v[82:85], off
	s_nop 1
	v_mul_f32_e32 v82, 0xbfb8aa3b, v78
	v_mul_f32_e32 v83, 0xbfb8aa3b, v79
	v_exp_f32_e32 v82, v82
	v_exp_f32_e32 v83, v83
	v_add_f32_e32 v82, 1.0, v82
	v_add_f32_e32 v83, 1.0, v83
	v_rcp_f32_e32 v82, v82
	v_rcp_f32_e32 v83, v83
	s_nop 0
	v_pk_mul_f32 v[78:79], v[78:79], v[82:83]
	s_nop 0
	v_pk_mul_f32 v[74:75], v[78:79], v[74:75]
	v_mul_f32_e32 v78, 0xbfb8aa3b, v80
	v_mul_f32_e32 v79, 0xbfb8aa3b, v81
	v_exp_f32_e32 v78, v78
	v_exp_f32_e32 v79, v79
	v_add_f32_e32 v78, 1.0, v78
	v_add_f32_e32 v79, 1.0, v79
	v_rcp_f32_e32 v78, v78
	v_rcp_f32_e32 v79, v79
	s_nop 0
	v_pk_mul_f32 v[78:79], v[80:81], v[78:79]
	s_nop 0
	v_pk_mul_f32 v[76:77], v[78:79], v[76:77]
	v_mul_f32_e32 v78, 0xbfb8aa3b, v70
	v_mul_f32_e32 v79, 0xbfb8aa3b, v71
	v_exp_f32_e32 v78, v78
	v_exp_f32_e32 v79, v79
	v_add_f32_e32 v78, 1.0, v78
	v_add_f32_e32 v79, 1.0, v79
	v_rcp_f32_e32 v78, v78
	v_rcp_f32_e32 v79, v79
	s_nop 0
	v_pk_mul_f32 v[70:71], v[70:71], v[78:79]
	s_nop 0
	v_pk_mul_f32 v[70:71], v[70:71], v[66:67]
	v_mul_f32_e32 v66, 0xbfb8aa3b, v72
	v_mul_f32_e32 v67, 0xbfb8aa3b, v73
	v_exp_f32_e32 v66, v66
	v_exp_f32_e32 v67, v67
	v_add_f32_e32 v66, 1.0, v66
	v_add_f32_e32 v67, 1.0, v67
	v_rcp_f32_e32 v66, v66
	v_rcp_f32_e32 v67, v67
	s_nop 0
	v_pk_mul_f32 v[66:67], v[72:73], v[66:67]
	s_nop 0
	v_pk_mul_f32 v[72:73], v[66:67], v[68:69]
	v_cvt_pk_bf16_f32 v68, v70, v71
	v_or_b32_e32 v70, 48, v145
	v_mad_i64_i32 v[70:71], s[20:21], v70, s7, v[114:115]
	v_cvt_pk_bf16_f32 v66, v74, v75
	v_cvt_pk_bf16_f32 v67, v76, v77
	v_cvt_pk_bf16_f32 v69, v72, v73
	v_lshl_add_u64 v[70:71], v[70:71], 0, v[116:117]
	global_store_dwordx4 v[70:71], v[66:69], off
	s_nop 1
	v_mul_f32_e32 v66, 0xbfb8aa3b, v62
	v_mul_f32_e32 v67, 0xbfb8aa3b, v63
	v_exp_f32_e32 v66, v66
	v_exp_f32_e32 v67, v67
	v_add_u32_e32 v68, 0x80, v145
	v_add_f32_e32 v66, 1.0, v66
	v_add_f32_e32 v67, 1.0, v67
	v_rcp_f32_e32 v66, v66
	v_rcp_f32_e32 v67, v67
	s_nop 0
	v_pk_mul_f32 v[62:63], v[62:63], v[66:67]
	s_nop 0
	v_pk_mul_f32 v[58:59], v[62:63], v[58:59]
	v_mul_f32_e32 v62, 0xbfb8aa3b, v64
	v_mul_f32_e32 v63, 0xbfb8aa3b, v65
	v_exp_f32_e32 v62, v62
	v_exp_f32_e32 v63, v63
	v_add_f32_e32 v62, 1.0, v62
	v_add_f32_e32 v63, 1.0, v63
	v_rcp_f32_e32 v62, v62
	v_rcp_f32_e32 v63, v63
	s_nop 0
	v_pk_mul_f32 v[62:63], v[64:65], v[62:63]
	s_nop 0
	v_pk_mul_f32 v[60:61], v[62:63], v[60:61]
	v_mul_f32_e32 v62, 0xbfb8aa3b, v54
	v_mul_f32_e32 v63, 0xbfb8aa3b, v55
	v_exp_f32_e32 v62, v62
	v_exp_f32_e32 v63, v63
	v_add_f32_e32 v62, 1.0, v62
	v_add_f32_e32 v63, 1.0, v63
	v_rcp_f32_e32 v62, v62
	v_rcp_f32_e32 v63, v63
	s_nop 0
	v_pk_mul_f32 v[54:55], v[54:55], v[62:63]
	s_nop 0
	v_pk_mul_f32 v[54:55], v[54:55], v[50:51]
	v_mul_f32_e32 v50, 0xbfb8aa3b, v56
	v_mul_f32_e32 v51, 0xbfb8aa3b, v57
	v_exp_f32_e32 v50, v50
	v_exp_f32_e32 v51, v51
	v_add_f32_e32 v50, 1.0, v50
	v_add_f32_e32 v51, 1.0, v51
	v_rcp_f32_e32 v50, v50
	v_rcp_f32_e32 v51, v51
	s_nop 0
	v_pk_mul_f32 v[50:51], v[56:57], v[50:51]
	s_nop 0
	v_pk_mul_f32 v[56:57], v[50:51], v[52:53]
	v_cvt_pk_bf16_f32 v52, v54, v55
	v_mad_i64_i32 v[54:55], s[20:21], v68, s7, v[114:115]
	v_cvt_pk_bf16_f32 v50, v58, v59
	v_cvt_pk_bf16_f32 v51, v60, v61
	v_cvt_pk_bf16_f32 v53, v56, v57
	v_lshl_add_u64 v[54:55], v[54:55], 0, v[116:117]
	global_store_dwordx4 v[54:55], v[50:53], off
	s_nop 1
	v_mul_f32_e32 v50, 0xbfb8aa3b, v46
	v_mul_f32_e32 v51, 0xbfb8aa3b, v47
	v_exp_f32_e32 v50, v50
	v_exp_f32_e32 v51, v51
	v_add_f32_e32 v50, 1.0, v50
	v_add_f32_e32 v51, 1.0, v51
	v_rcp_f32_e32 v50, v50
	v_rcp_f32_e32 v51, v51
	s_nop 0
	v_pk_mul_f32 v[46:47], v[46:47], v[50:51]
	s_nop 0
	v_pk_mul_f32 v[42:43], v[46:47], v[42:43]
	v_mul_f32_e32 v46, 0xbfb8aa3b, v48
	v_mul_f32_e32 v47, 0xbfb8aa3b, v49
	v_exp_f32_e32 v46, v46
	v_exp_f32_e32 v47, v47
	v_add_f32_e32 v46, 1.0, v46
	v_add_f32_e32 v47, 1.0, v47
	v_rcp_f32_e32 v46, v46
	v_rcp_f32_e32 v47, v47
	s_nop 0
	v_pk_mul_f32 v[46:47], v[48:49], v[46:47]
	s_nop 0
	v_pk_mul_f32 v[44:45], v[46:47], v[44:45]
	v_mul_f32_e32 v46, 0xbfb8aa3b, v38
	v_mul_f32_e32 v47, 0xbfb8aa3b, v39
	v_exp_f32_e32 v46, v46
	v_exp_f32_e32 v47, v47
	v_add_f32_e32 v46, 1.0, v46
	v_add_f32_e32 v47, 1.0, v47
	v_rcp_f32_e32 v46, v46
	v_rcp_f32_e32 v47, v47
	s_nop 0
	v_pk_mul_f32 v[38:39], v[38:39], v[46:47]
	s_nop 0
	v_pk_mul_f32 v[38:39], v[38:39], v[34:35]
	v_mul_f32_e32 v34, 0xbfb8aa3b, v40
	v_mul_f32_e32 v35, 0xbfb8aa3b, v41
	v_exp_f32_e32 v34, v34
	v_exp_f32_e32 v35, v35
	v_add_f32_e32 v34, 1.0, v34
	v_add_f32_e32 v35, 1.0, v35
	v_rcp_f32_e32 v34, v34
	v_rcp_f32_e32 v35, v35
	s_nop 0
	v_pk_mul_f32 v[34:35], v[40:41], v[34:35]
	s_nop 0
	v_pk_mul_f32 v[40:41], v[34:35], v[36:37]
	v_cvt_pk_bf16_f32 v36, v38, v39
	v_add_u32_e32 v38, 0x90, v145
	v_mad_i64_i32 v[38:39], s[20:21], v38, s7, v[114:115]
	v_cvt_pk_bf16_f32 v34, v42, v43
	v_cvt_pk_bf16_f32 v35, v44, v45
	v_cvt_pk_bf16_f32 v37, v40, v41
	v_lshl_add_u64 v[38:39], v[38:39], 0, v[116:117]
	global_store_dwordx4 v[38:39], v[34:37], off
	s_nop 1
	v_mul_f32_e32 v34, 0xbfb8aa3b, v30
	v_mul_f32_e32 v35, 0xbfb8aa3b, v31
	v_exp_f32_e32 v34, v34
	v_exp_f32_e32 v35, v35
	v_add_f32_e32 v34, 1.0, v34
	v_add_f32_e32 v35, 1.0, v35
	v_rcp_f32_e32 v34, v34
	v_rcp_f32_e32 v35, v35
	s_nop 0
	v_pk_mul_f32 v[30:31], v[30:31], v[34:35]
	s_nop 0
	v_pk_mul_f32 v[26:27], v[30:31], v[26:27]
	v_mul_f32_e32 v30, 0xbfb8aa3b, v32
	v_mul_f32_e32 v31, 0xbfb8aa3b, v33
	v_exp_f32_e32 v30, v30
	v_exp_f32_e32 v31, v31
	v_add_f32_e32 v30, 1.0, v30
	v_add_f32_e32 v31, 1.0, v31
	v_rcp_f32_e32 v30, v30
	v_rcp_f32_e32 v31, v31
	s_nop 0
	v_pk_mul_f32 v[30:31], v[32:33], v[30:31]
	s_nop 0
	v_pk_mul_f32 v[28:29], v[30:31], v[28:29]
	v_mul_f32_e32 v30, 0xbfb8aa3b, v22
	v_mul_f32_e32 v31, 0xbfb8aa3b, v23
	v_exp_f32_e32 v30, v30
	v_exp_f32_e32 v31, v31
	v_add_f32_e32 v30, 1.0, v30
	v_add_f32_e32 v31, 1.0, v31
	v_rcp_f32_e32 v30, v30
	v_rcp_f32_e32 v31, v31
	s_nop 0
	v_pk_mul_f32 v[22:23], v[22:23], v[30:31]
	s_nop 0
	v_pk_mul_f32 v[22:23], v[22:23], v[18:19]
	v_mul_f32_e32 v18, 0xbfb8aa3b, v24
	v_mul_f32_e32 v19, 0xbfb8aa3b, v25
	v_exp_f32_e32 v18, v18
	v_exp_f32_e32 v19, v19
	v_add_f32_e32 v18, 1.0, v18
	v_add_f32_e32 v19, 1.0, v19
	v_rcp_f32_e32 v18, v18
	v_rcp_f32_e32 v19, v19
	s_nop 0
	v_pk_mul_f32 v[18:19], v[24:25], v[18:19]
	s_nop 0
	v_pk_mul_f32 v[24:25], v[18:19], v[20:21]
	v_cvt_pk_bf16_f32 v20, v22, v23
	v_add_u32_e32 v22, 0xa0, v145
	v_mad_i64_i32 v[22:23], s[20:21], v22, s7, v[114:115]
	v_cvt_pk_bf16_f32 v18, v26, v27
	v_cvt_pk_bf16_f32 v19, v28, v29
	v_cvt_pk_bf16_f32 v21, v24, v25
	v_lshl_add_u64 v[22:23], v[22:23], 0, v[116:117]
	global_store_dwordx4 v[22:23], v[18:21], off
	s_nop 1
	v_mul_f32_e32 v18, 0xbfb8aa3b, v14
	v_mul_f32_e32 v19, 0xbfb8aa3b, v15
	v_exp_f32_e32 v18, v18
	v_exp_f32_e32 v19, v19
	v_add_f32_e32 v18, 1.0, v18
	v_add_f32_e32 v19, 1.0, v19
	v_rcp_f32_e32 v18, v18
	v_rcp_f32_e32 v19, v19
	s_nop 0
	v_pk_mul_f32 v[14:15], v[14:15], v[18:19]
	s_nop 0
	v_pk_mul_f32 v[10:11], v[14:15], v[10:11]
	v_mul_f32_e32 v14, 0xbfb8aa3b, v16
	v_mul_f32_e32 v15, 0xbfb8aa3b, v17
	v_exp_f32_e32 v14, v14
	v_exp_f32_e32 v15, v15
	v_add_f32_e32 v14, 1.0, v14
	v_add_f32_e32 v15, 1.0, v15
	v_rcp_f32_e32 v14, v14
	v_rcp_f32_e32 v15, v15
	s_nop 0
	v_pk_mul_f32 v[14:15], v[16:17], v[14:15]
	s_nop 0
	v_pk_mul_f32 v[12:13], v[14:15], v[12:13]
	v_mul_f32_e32 v14, 0xbfb8aa3b, v6
	v_mul_f32_e32 v15, 0xbfb8aa3b, v7
	v_exp_f32_e32 v14, v14
	v_exp_f32_e32 v15, v15
	v_add_f32_e32 v14, 1.0, v14
	v_add_f32_e32 v15, 1.0, v15
	v_rcp_f32_e32 v14, v14
	v_rcp_f32_e32 v15, v15
	s_nop 0
	v_pk_mul_f32 v[6:7], v[6:7], v[14:15]
	s_nop 0
	v_pk_mul_f32 v[6:7], v[6:7], v[2:3]
	v_mul_f32_e32 v2, 0xbfb8aa3b, v8
	v_mul_f32_e32 v3, 0xbfb8aa3b, v9
	v_exp_f32_e32 v2, v2
	v_exp_f32_e32 v3, v3
	v_add_f32_e32 v2, 1.0, v2
	v_add_f32_e32 v3, 1.0, v3
	v_rcp_f32_e32 v2, v2
	v_rcp_f32_e32 v3, v3
	s_nop 0
	v_pk_mul_f32 v[2:3], v[8:9], v[2:3]
	s_nop 0
	v_pk_mul_f32 v[8:9], v[2:3], v[4:5]
	v_cvt_pk_bf16_f32 v4, v6, v7
	v_add_u32_e32 v6, 0xb0, v145
	v_mad_i64_i32 v[6:7], s[20:21], v6, s7, v[114:115]
	v_cvt_pk_bf16_f32 v2, v10, v11
	v_cvt_pk_bf16_f32 v3, v12, v13
	v_cvt_pk_bf16_f32 v5, v8, v9
	v_lshl_add_u64 v[6:7], v[6:7], 0, v[116:117]
	s_mov_b64 s[20:21], s[12:13]
	global_store_dwordx4 v[6:7], v[2:5], off
	s_cbranch_vccz .LBB0_294
	s_waitcnt vmcnt(0)
	s_cmpk_gt_u32 s28, 0xff
	s_cbranch_scc1 .LBB0_301
	s_barrier

.LBB0_374:
	s_add_u32 s16, s14, 0x100
	s_addc_u32 s17, s15, 0
	s_add_i32 s49, 0, 0x10000
	v_add_u32_e32 v154, s49, v164
	ds_read_b128 v[142:145], v154
	ds_read_b128 v[146:149], v154 offset:1024
	ds_read_b128 v[150:153], v154 offset:2048
	ds_read_b128 v[154:157], v154 offset:3072
	s_cmp_eq_u32 s48, 40
	s_cselect_b32 s21, s7, s17
	s_cselect_b32 s20, s6, s16
	s_cselect_b32 s19, s9, s47
	s_cselect_b32 s18, s8, s46
	v_lshl_add_u64 v[162:163], s[14:15], 0, v[138:139]
	s_add_i32 m0, s35, 0xc000
	ds_read_b128 v[158:161], v166
	ds_read_b128 v[168:171], v166 offset:1024
	ds_read_b128 v[172:175], v166 offset:2048
	ds_read_b128 v[190:193], v166 offset:3072
	ds_read_b128 v[194:197], v166 offset:4096
	ds_read_b128 v[198:201], v166 offset:5120
	ds_read_b128 v[202:205], v166 offset:6144
	ds_read_b128 v[206:209], v166 offset:7168
	global_load_lds_dwordx4 v[162:163], off
	v_lshl_add_u64 v[162:163], s[14:15], 0, v[140:141]
	s_add_i32 m0, s35, 0xe000
	s_nop 0
	global_load_lds_dwordx4 v[162:163], off
	s_waitcnt lgkmcnt(8)
	s_barrier
	s_waitcnt lgkmcnt(0)
	s_setprio 1
	s_waitcnt lgkmcnt(0)
	v_mfma_f32_16x16x32_bf16 v[126:129], v[142:145], v[158:161], v[126:129]
	v_mfma_f32_16x16x32_bf16 v[122:125], v[150:153], v[158:161], v[122:125]
	v_mfma_f32_16x16x32_bf16 v[110:113], v[142:145], v[172:175], v[110:113]
	v_mfma_f32_16x16x32_bf16 v[106:109], v[150:153], v[172:175], v[106:109]
	v_mfma_f32_16x16x32_bf16 v[94:97], v[142:145], v[194:197], v[94:97]
	v_mfma_f32_16x16x32_bf16 v[90:93], v[150:153], v[194:197], v[90:93]
	v_mfma_f32_16x16x32_bf16 v[78:81], v[142:145], v[202:205], v[78:81]
	v_mfma_f32_16x16x32_bf16 v[74:77], v[150:153], v[202:205], v[74:77]
	v_mfma_f32_16x16x32_bf16 v[126:129], v[146:149], v[168:171], v[126:129]
	v_mfma_f32_16x16x32_bf16 v[122:125], v[154:157], v[168:171], v[122:125]
	v_mfma_f32_16x16x32_bf16 v[110:113], v[146:149], v[190:193], v[110:113]
	v_mfma_f32_16x16x32_bf16 v[106:109], v[154:157], v[190:193], v[106:109]
	v_mfma_f32_16x16x32_bf16 v[94:97], v[146:149], v[198:201], v[94:97]
	v_mfma_f32_16x16x32_bf16 v[90:93], v[154:157], v[198:201], v[90:93]
	v_mfma_f32_16x16x32_bf16 v[78:81], v[146:149], v[206:209], v[78:81]
	v_mfma_f32_16x16x32_bf16 v[74:77], v[154:157], v[206:209], v[74:77]
	s_setprio 0
	s_barrier
	s_add_i32 s50, 0, 0x14000
	v_add_u32_e32 v162, s50, v164
	s_add_i32 s14, s49, s34
	ds_read_b128 v[210:213], v162
	ds_read_b128 v[214:217], v162 offset:1024
	ds_read_b128 v[218:221], v162 offset:2048
	ds_read_b128 v[222:225], v162 offset:3072
	v_lshl_add_u64 v[162:163], s[18:19], 0, v[132:133]
	s_mov_b32 m0, s14
	v_lshl_add_u64 v[176:177], s[18:19], 0, v[136:137]
	global_load_lds_dwordx4 v[162:163], off
	s_add_i32 m0, s14, 0x2000
	s_nop 0
	global_load_lds_dwordx4 v[176:177], off
	s_barrier
	s_waitcnt lgkmcnt(0)
	s_setprio 1
	s_waitcnt lgkmcnt(0)
	v_mfma_f32_16x16x32_bf16 v[118:121], v[210:213], v[158:161], v[118:121]
	v_mfma_f32_16x16x32_bf16 v[114:117], v[218:221], v[158:161], v[114:117]
	v_mfma_f32_16x16x32_bf16 v[102:105], v[210:213], v[172:175], v[102:105]
	v_mfma_f32_16x16x32_bf16 v[98:101], v[218:221], v[172:175], v[98:101]
	v_mfma_f32_16x16x32_bf16 v[86:89], v[210:213], v[194:197], v[86:89]
	v_mfma_f32_16x16x32_bf16 v[82:85], v[218:221], v[194:197], v[82:85]
	v_mfma_f32_16x16x32_bf16 v[70:73], v[210:213], v[202:205], v[70:73]
	v_mfma_f32_16x16x32_bf16 v[66:69], v[218:221], v[202:205], v[66:69]
	v_mfma_f32_16x16x32_bf16 v[118:121], v[214:217], v[168:171], v[118:121]
	v_mfma_f32_16x16x32_bf16 v[114:117], v[222:225], v[168:171], v[114:117]
	v_mfma_f32_16x16x32_bf16 v[102:105], v[214:217], v[190:193], v[102:105]
	v_mfma_f32_16x16x32_bf16 v[98:101], v[222:225], v[190:193], v[98:101]
	v_mfma_f32_16x16x32_bf16 v[86:89], v[214:217], v[198:201], v[86:89]
	v_mfma_f32_16x16x32_bf16 v[82:85], v[222:225], v[198:201], v[82:85]
	v_mfma_f32_16x16x32_bf16 v[70:73], v[214:217], v[206:209], v[70:73]
	v_mfma_f32_16x16x32_bf16 v[66:69], v[222:225], v[206:209], v[66:69]
	s_setprio 0
	s_mov_b32 m0, s35
	v_lshl_add_u64 v[186:187], s[20:21], 0, v[130:131]
	s_barrier
	ds_read_b128 v[158:161], v166 offset:16384
	ds_read_b128 v[168:171], v166 offset:17408
	ds_read_b128 v[172:175], v166 offset:18432
	ds_read_b128 v[190:193], v166 offset:19456
	ds_read_b128 v[194:197], v166 offset:20480
	ds_read_b128 v[198:201], v166 offset:21504
	ds_read_b128 v[202:205], v166 offset:22528
	ds_read_b128 v[206:209], v166 offset:23552
	global_load_lds_dwordx4 v[186:187], off
	v_lshl_add_u64 v[188:189], s[20:21], 0, v[134:135]
	s_mov_b32 m0, s36
	s_nop 0
	global_load_lds_dwordx4 v[188:189], off
	s_barrier
	s_waitcnt lgkmcnt(0)
	s_setprio 1
	s_waitcnt lgkmcnt(0)
	v_mfma_f32_16x16x32_bf16 v[62:65], v[142:145], v[158:161], v[62:65]
	v_mfma_f32_16x16x32_bf16 v[58:61], v[150:153], v[158:161], v[58:61]
	v_mfma_f32_16x16x32_bf16 v[46:49], v[142:145], v[172:175], v[46:49]
	v_mfma_f32_16x16x32_bf16 v[42:45], v[150:153], v[172:175], v[42:45]
	v_mfma_f32_16x16x32_bf16 v[30:33], v[142:145], v[194:197], v[30:33]
	v_mfma_f32_16x16x32_bf16 v[26:29], v[150:153], v[194:197], v[26:29]
	v_mfma_f32_16x16x32_bf16 v[14:17], v[142:145], v[202:205], v[14:17]
	v_mfma_f32_16x16x32_bf16 v[10:13], v[150:153], v[202:205], v[10:13]
	v_mfma_f32_16x16x32_bf16 v[62:65], v[146:149], v[168:171], v[62:65]
	v_mfma_f32_16x16x32_bf16 v[58:61], v[154:157], v[168:171], v[58:61]
	v_mfma_f32_16x16x32_bf16 v[46:49], v[146:149], v[190:193], v[46:49]
	v_mfma_f32_16x16x32_bf16 v[42:45], v[154:157], v[190:193], v[42:45]
	v_mfma_f32_16x16x32_bf16 v[30:33], v[146:149], v[198:201], v[30:33]
	v_mfma_f32_16x16x32_bf16 v[26:29], v[154:157], v[198:201], v[26:29]
	v_mfma_f32_16x16x32_bf16 v[14:17], v[146:149], v[206:209], v[14:17]
	v_mfma_f32_16x16x32_bf16 v[10:13], v[154:157], v[206:209], v[10:13]
	s_setprio 0
	s_barrier
	s_add_u32 s14, s18, 0xb0000
	s_addc_u32 s15, s19, 0
	s_add_i32 s49, s50, s34
	s_mov_b32 m0, s49
	s_nop 0
	global_load_lds_dwordx4 v132, s[14:15]
	s_add_i32 m0, s49, 0x2000
	s_nop 0
	global_load_lds_dwordx4 v136, s[14:15]
	s_waitcnt vmcnt(6)
	s_barrier
	s_setprio 1
	v_mfma_f32_16x16x32_bf16 v[54:57], v[210:213], v[158:161], v[54:57]
	v_mfma_f32_16x16x32_bf16 v[50:53], v[218:221], v[158:161], v[50:53]
	v_mfma_f32_16x16x32_bf16 v[38:41], v[210:213], v[172:175], v[38:41]
	v_mfma_f32_16x16x32_bf16 v[34:37], v[218:221], v[172:175], v[34:37]
	v_mfma_f32_16x16x32_bf16 v[22:25], v[210:213], v[194:197], v[22:25]
	v_mfma_f32_16x16x32_bf16 v[18:21], v[218:221], v[194:197], v[18:21]
	v_mfma_f32_16x16x32_bf16 v[6:9], v[210:213], v[202:205], v[6:9]
	v_mfma_f32_16x16x32_bf16 v[2:5], v[218:221], v[202:205], v[2:5]
	v_mfma_f32_16x16x32_bf16 v[54:57], v[214:217], v[168:171], v[54:57]
	v_mfma_f32_16x16x32_bf16 v[50:53], v[222:225], v[168:171], v[50:53]
	v_mfma_f32_16x16x32_bf16 v[38:41], v[214:217], v[190:193], v[38:41]
	v_mfma_f32_16x16x32_bf16 v[34:37], v[222:225], v[190:193], v[34:37]
	v_mfma_f32_16x16x32_bf16 v[22:25], v[214:217], v[198:201], v[22:25]
	v_mfma_f32_16x16x32_bf16 v[18:21], v[222:225], v[198:201], v[18:21]
	v_mfma_f32_16x16x32_bf16 v[6:9], v[214:217], v[206:209], v[6:9]
	v_mfma_f32_16x16x32_bf16 v[2:5], v[222:225], v[206:209], v[2:5]
	s_setprio 0
	s_add_i32 s49, 0, 0x18000
	v_add_u32_e32 v154, s49, v164
	s_barrier
	ds_read_b128 v[142:145], v154
	ds_read_b128 v[146:149], v154 offset:1024
	ds_read_b128 v[150:153], v154 offset:2048
	ds_read_b128 v[154:157], v154 offset:3072
	s_add_u32 s14, s20, 0xb8000
	s_addc_u32 s15, s21, 0
	s_mov_b32 m0, s37
	ds_read_b128 v[158:161], v166 offset:32768
	ds_read_b128 v[168:171], v166 offset:33792
	ds_read_b128 v[172:175], v166 offset:34816
	ds_read_b128 v[190:193], v166 offset:35840
	ds_read_b128 v[194:197], v166 offset:36864
	ds_read_b128 v[198:201], v166 offset:37888
	ds_read_b128 v[202:205], v166 offset:38912
	ds_read_b128 v[206:209], v166 offset:39936
	global_load_lds_dwordx4 v130, s[14:15]
	s_mov_b32 m0, s38
	s_nop 0
	global_load_lds_dwordx4 v134, s[14:15]
	s_waitcnt lgkmcnt(8)
	s_barrier
	s_waitcnt lgkmcnt(0)
	s_setprio 1
	s_waitcnt lgkmcnt(0)
	v_mfma_f32_16x16x32_bf16 v[126:129], v[142:145], v[158:161], v[126:129]
	v_mfma_f32_16x16x32_bf16 v[122:125], v[150:153], v[158:161], v[122:125]
	v_mfma_f32_16x16x32_bf16 v[110:113], v[142:145], v[172:175], v[110:113]
	v_mfma_f32_16x16x32_bf16 v[106:109], v[150:153], v[172:175], v[106:109]
	v_mfma_f32_16x16x32_bf16 v[94:97], v[142:145], v[194:197], v[94:97]
	v_mfma_f32_16x16x32_bf16 v[90:93], v[150:153], v[194:197], v[90:93]
	v_mfma_f32_16x16x32_bf16 v[78:81], v[142:145], v[202:205], v[78:81]
	v_mfma_f32_16x16x32_bf16 v[74:77], v[150:153], v[202:205], v[74:77]
	v_mfma_f32_16x16x32_bf16 v[126:129], v[146:149], v[168:171], v[126:129]
	v_mfma_f32_16x16x32_bf16 v[122:125], v[154:157], v[168:171], v[122:125]
	v_mfma_f32_16x16x32_bf16 v[110:113], v[146:149], v[190:193], v[110:113]
	v_mfma_f32_16x16x32_bf16 v[106:109], v[154:157], v[190:193], v[106:109]
	v_mfma_f32_16x16x32_bf16 v[94:97], v[146:149], v[198:201], v[94:97]
	v_mfma_f32_16x16x32_bf16 v[90:93], v[154:157], v[198:201], v[90:93]
	v_mfma_f32_16x16x32_bf16 v[78:81], v[146:149], v[206:209], v[78:81]
	v_mfma_f32_16x16x32_bf16 v[74:77], v[154:157], v[206:209], v[74:77]
	s_setprio 0
	s_barrier
	s_add_i32 s20, 0, 0x1c000
	s_add_i32 s14, s49, s34
	v_add_u32_e32 v167, s20, v164
	v_lshl_add_u64 v[162:163], v[162:163], 0, s[0:1]
	s_mov_b32 m0, s14
	ds_read_b128 v[210:213], v167
	ds_read_b128 v[214:217], v167 offset:1024
	ds_read_b128 v[218:221], v167 offset:2048
	ds_read_b128 v[222:225], v167 offset:3072
	global_load_lds_dwordx4 v[162:163], off
	v_lshl_add_u64 v[162:163], v[176:177], 0, s[0:1]
	s_add_i32 m0, s14, 0x2000
	s_nop 0
	global_load_lds_dwordx4 v[162:163], off
	s_barrier
	s_waitcnt lgkmcnt(0)
	s_setprio 1
	s_waitcnt lgkmcnt(0)
	v_mfma_f32_16x16x32_bf16 v[118:121], v[210:213], v[158:161], v[118:121]
	v_mfma_f32_16x16x32_bf16 v[114:117], v[218:221], v[158:161], v[114:117]
	v_mfma_f32_16x16x32_bf16 v[102:105], v[210:213], v[172:175], v[102:105]
	v_mfma_f32_16x16x32_bf16 v[98:101], v[218:221], v[172:175], v[98:101]
	v_mfma_f32_16x16x32_bf16 v[86:89], v[210:213], v[194:197], v[86:89]
	v_mfma_f32_16x16x32_bf16 v[82:85], v[218:221], v[194:197], v[82:85]
	v_mfma_f32_16x16x32_bf16 v[70:73], v[210:213], v[202:205], v[70:73]
	v_mfma_f32_16x16x32_bf16 v[66:69], v[218:221], v[202:205], v[66:69]
	v_mfma_f32_16x16x32_bf16 v[118:121], v[214:217], v[168:171], v[118:121]
	v_mfma_f32_16x16x32_bf16 v[114:117], v[222:225], v[168:171], v[114:117]
	v_mfma_f32_16x16x32_bf16 v[102:105], v[214:217], v[190:193], v[102:105]
	v_mfma_f32_16x16x32_bf16 v[98:101], v[222:225], v[190:193], v[98:101]
	v_mfma_f32_16x16x32_bf16 v[86:89], v[214:217], v[198:201], v[86:89]
	v_mfma_f32_16x16x32_bf16 v[82:85], v[222:225], v[198:201], v[82:85]
	v_mfma_f32_16x16x32_bf16 v[70:73], v[214:217], v[206:209], v[70:73]
	v_mfma_f32_16x16x32_bf16 v[66:69], v[222:225], v[206:209], v[66:69]
	s_setprio 0
	s_mov_b32 m0, s39
	v_lshl_add_u64 v[162:163], v[186:187], 0, s[0:1]
	s_barrier
	ds_read_b128 v[158:161], v166 offset:49152
	ds_read_b128 v[168:171], v166 offset:50176
	ds_read_b128 v[172:175], v166 offset:51200
	ds_read_b128 v[190:193], v166 offset:52224
	ds_read_b128 v[194:197], v166 offset:53248
	ds_read_b128 v[198:201], v166 offset:54272
	ds_read_b128 v[202:205], v166 offset:55296
	ds_read_b128 v[206:209], v166 offset:56320
	global_load_lds_dwordx4 v[162:163], off
	v_lshl_add_u64 v[162:163], v[188:189], 0, s[0:1]
	s_mov_b32 m0, s40
	s_nop 0
	global_load_lds_dwordx4 v[162:163], off
	s_barrier
	s_waitcnt lgkmcnt(0)
	s_setprio 1
	s_waitcnt lgkmcnt(0)
	v_mfma_f32_16x16x32_bf16 v[62:65], v[142:145], v[158:161], v[62:65]
	v_mfma_f32_16x16x32_bf16 v[58:61], v[150:153], v[158:161], v[58:61]
	v_mfma_f32_16x16x32_bf16 v[46:49], v[142:145], v[172:175], v[46:49]
	v_mfma_f32_16x16x32_bf16 v[42:45], v[150:153], v[172:175], v[42:45]
	v_mfma_f32_16x16x32_bf16 v[30:33], v[142:145], v[194:197], v[30:33]
	v_mfma_f32_16x16x32_bf16 v[26:29], v[150:153], v[194:197], v[26:29]
	v_mfma_f32_16x16x32_bf16 v[14:17], v[142:145], v[202:205], v[14:17]
	v_mfma_f32_16x16x32_bf16 v[10:13], v[150:153], v[202:205], v[10:13]
	v_mfma_f32_16x16x32_bf16 v[62:65], v[146:149], v[168:171], v[62:65]
	v_mfma_f32_16x16x32_bf16 v[58:61], v[154:157], v[168:171], v[58:61]
	v_mfma_f32_16x16x32_bf16 v[46:49], v[146:149], v[190:193], v[46:49]
	v_mfma_f32_16x16x32_bf16 v[42:45], v[154:157], v[190:193], v[42:45]
	v_mfma_f32_16x16x32_bf16 v[30:33], v[146:149], v[198:201], v[30:33]
	v_mfma_f32_16x16x32_bf16 v[26:29], v[154:157], v[198:201], v[26:29]
	v_mfma_f32_16x16x32_bf16 v[14:17], v[146:149], v[206:209], v[14:17]
	v_mfma_f32_16x16x32_bf16 v[10:13], v[154:157], v[206:209], v[10:13]
	s_setprio 0
	s_barrier
	s_add_u32 s14, s18, 0xb0080
	s_addc_u32 s15, s19, 0
	s_add_i32 s18, s20, s34
	s_mov_b32 m0, s18
	s_nop 0
	global_load_lds_dwordx4 v132, s[14:15]
	s_add_i32 m0, s18, 0x2000
	s_nop 0
	global_load_lds_dwordx4 v136, s[14:15]
	s_waitcnt vmcnt(6)
	s_barrier
	s_setprio 1
	v_mfma_f32_16x16x32_bf16 v[54:57], v[210:213], v[158:161], v[54:57]
	v_mfma_f32_16x16x32_bf16 v[50:53], v[218:221], v[158:161], v[50:53]
	v_mfma_f32_16x16x32_bf16 v[38:41], v[210:213], v[172:175], v[38:41]
	v_mfma_f32_16x16x32_bf16 v[34:37], v[218:221], v[172:175], v[34:37]
	v_mfma_f32_16x16x32_bf16 v[22:25], v[210:213], v[194:197], v[22:25]
	v_mfma_f32_16x16x32_bf16 v[18:21], v[218:221], v[194:197], v[18:21]
	v_mfma_f32_16x16x32_bf16 v[6:9], v[210:213], v[202:205], v[6:9]
	v_mfma_f32_16x16x32_bf16 v[2:5], v[218:221], v[202:205], v[2:5]
	v_mfma_f32_16x16x32_bf16 v[54:57], v[214:217], v[168:171], v[54:57]
	v_mfma_f32_16x16x32_bf16 v[50:53], v[222:225], v[168:171], v[50:53]
	v_mfma_f32_16x16x32_bf16 v[38:41], v[214:217], v[190:193], v[38:41]
	v_mfma_f32_16x16x32_bf16 v[34:37], v[222:225], v[190:193], v[34:37]
	v_mfma_f32_16x16x32_bf16 v[22:25], v[214:217], v[198:201], v[22:25]
	v_mfma_f32_16x16x32_bf16 v[18:21], v[222:225], v[198:201], v[18:21]
	v_mfma_f32_16x16x32_bf16 v[6:9], v[214:217], v[206:209], v[6:9]
	v_mfma_f32_16x16x32_bf16 v[2:5], v[222:225], v[206:209], v[2:5]
	s_setprio 0
	s_add_i32 s48, s48, 2
	s_add_u32 s46, s46, 0x100
	s_addc_u32 s47, s47, 0
	s_cmp_gt_u32 s48, 41
	s_mov_b64 s[14:15], s[16:17]
	s_barrier
	s_cbranch_scc0 .LBB0_374
	s_ashr_i32 s14, s33, 5
	s_mul_hi_i32 s15, s14, 0x9000
	s_mul_i32 s14, s14, 0x9000
	v_lshl_or_b32 v158, s45, 8, v165
	s_add_u32 s14, s26, s14
	s_addc_u32 s15, s27, s15
	v_ashrrev_i32_e32 v159, 31, v158
	v_lshl_add_u64 v[160:161], v[158:159], 2, s[14:15]
	global_load_dwordx4 v[142:145], v[160:161], off offset:16
	global_load_dwordx4 v[146:149], v[160:161], off
	v_lshl_add_u32 v162, s33, 8, v1
	v_ashrrev_i32_e32 v163, 31, v162
	s_mov_b64 s[14:15], 0x80000
	s_and_b64 vcc, exec, s[4:5]
	s_mov_b32 s45, s43
	s_mov_b32 s33, s44
	s_mov_b64 s[16:17], s[8:9]
	s_waitcnt vmcnt(0)
	v_pk_add_f32 v[144:145], v[144:145], 1.0 op_sel_hi:[1,0]
	v_pk_add_f32 v[148:149], v[148:149], 1.0 op_sel_hi:[1,0]
	v_pk_add_f32 v[146:147], v[146:147], 1.0 op_sel_hi:[1,0]
	v_pk_add_f32 v[142:143], v[142:143], 1.0 op_sel_hi:[1,0]
	v_pk_mul_f32 v[152:153], v[148:149], 0.5 op_sel_hi:[1,0]
	v_pk_mul_f32 v[156:157], v[146:147], 0.5 op_sel_hi:[1,0]
	v_pk_mul_f32 v[150:151], v[144:145], 0.5 op_sel_hi:[1,0]
	v_pk_mul_f32 v[154:155], v[142:143], 0.5 op_sel_hi:[1,0]
	global_load_dwordx4 v[142:145], v[160:161], off offset:528
	global_load_dwordx4 v[146:149], v[160:161], off offset:512
	s_waitcnt vmcnt(0)
	v_pk_add_f32 v[144:145], v[144:145], 1.0 op_sel_hi:[1,0]
	v_pk_add_f32 v[148:149], v[148:149], 1.0 op_sel_hi:[1,0]
	v_pk_add_f32 v[160:161], v[146:147], 1.0 op_sel_hi:[1,0]
	v_pk_mul_f32 v[146:147], v[148:149], 0.5 op_sel_hi:[1,0]
	v_pk_mul_f32 v[148:149], v[160:161], 0.5 op_sel_hi:[1,0]
	v_pk_add_f32 v[160:161], v[142:143], 1.0 op_sel_hi:[1,0]
	v_pk_mul_f32 v[142:143], v[144:145], 0.5 op_sel_hi:[1,0]
	v_pk_mul_f32 v[144:145], v[160:161], 0.5 op_sel_hi:[1,0]
	v_lshlrev_b64 v[160:161], 12, v[162:163]
	v_lshl_add_u64 v[168:169], s[12:13], 0, v[160:161]
	v_lshlrev_b64 v[160:161], 1, v[158:159]
	v_lshl_add_u64 v[158:159], v[168:169], 0, v[160:161]
	global_load_dwordx4 v[168:171], v[158:159], off offset:2048
	s_waitcnt vmcnt(0)
	v_lshlrev_b32_e32 v172, 16, v168
	v_and_b32_e32 v173, 0xffff0000, v168
	v_lshlrev_b32_e32 v168, 16, v169
	v_and_b32_e32 v169, 0xffff0000, v169
	v_pk_fma_f32 v[128:129], v[128:129], v[152:153], v[168:169]
	v_lshlrev_b32_e32 v168, 16, v170
	v_and_b32_e32 v169, 0xffff0000, v170
	v_pk_fma_f32 v[168:169], v[122:123], v[154:155], v[168:169]
	v_lshlrev_b32_e32 v122, 16, v171
	v_and_b32_e32 v123, 0xffff0000, v171
	v_pk_fma_f32 v[126:127], v[126:127], v[156:157], v[172:173]
	v_pk_fma_f32 v[170:171], v[124:125], v[150:151], v[122:123]
	v_cvt_pk_bf16_f32 v122, v126, v127
	v_cvt_pk_bf16_f32 v123, v128, v129
	v_cvt_pk_bf16_f32 v124, v168, v169
	v_cvt_pk_bf16_f32 v125, v170, v171
	global_store_dwordx4 v[158:159], v[122:125], off offset:2048
	global_load_dwordx4 v[122:125], v[158:159], off offset:2304
	s_waitcnt vmcnt(0)
	v_lshlrev_b32_e32 v126, 16, v122
	v_and_b32_e32 v127, 0xffff0000, v122
	v_lshlrev_b32_e32 v122, 16, v123
	v_and_b32_e32 v123, 0xffff0000, v123
	v_pk_fma_f32 v[120:121], v[120:121], v[146:147], v[122:123]
	v_lshlrev_b32_e32 v122, 16, v124
	v_and_b32_e32 v123, 0xffff0000, v124
	v_pk_fma_f32 v[122:123], v[114:115], v[144:145], v[122:123]
	v_lshlrev_b32_e32 v114, 16, v125
	v_and_b32_e32 v115, 0xffff0000, v125
	v_pk_fma_f32 v[118:119], v[118:119], v[148:149], v[126:127]
	v_pk_fma_f32 v[124:125], v[116:117], v[142:143], v[114:115]
	v_cvt_pk_bf16_f32 v114, v118, v119
	v_cvt_pk_bf16_f32 v115, v120, v121
	v_cvt_pk_bf16_f32 v116, v122, v123
	v_cvt_pk_bf16_f32 v117, v124, v125
	global_store_dwordx4 v[158:159], v[114:117], off offset:2304
	s_nop 1
	v_or_b32_e32 v114, 16, v162
	v_ashrrev_i32_e32 v115, 31, v114
	v_lshlrev_b64 v[114:115], 12, v[114:115]
	v_lshl_add_u64 v[114:115], s[12:13], 0, v[114:115]
	v_lshl_add_u64 v[118:119], v[114:115], 0, v[160:161]
	global_load_dwordx4 v[114:117], v[118:119], off offset:2048
	s_waitcnt vmcnt(0)
	v_lshlrev_b32_e32 v120, 16, v114
	v_and_b32_e32 v121, 0xffff0000, v114
	v_lshlrev_b32_e32 v114, 16, v115
	v_and_b32_e32 v115, 0xffff0000, v115
	v_pk_fma_f32 v[112:113], v[112:113], v[152:153], v[114:115]
	v_lshlrev_b32_e32 v114, 16, v116
	v_and_b32_e32 v115, 0xffff0000, v116
	v_pk_fma_f32 v[114:115], v[106:107], v[154:155], v[114:115]
	v_lshlrev_b32_e32 v106, 16, v117
	v_and_b32_e32 v107, 0xffff0000, v117
	v_pk_fma_f32 v[110:111], v[110:111], v[156:157], v[120:121]
	v_pk_fma_f32 v[116:117], v[108:109], v[150:151], v[106:107]
	v_cvt_pk_bf16_f32 v106, v110, v111
	v_cvt_pk_bf16_f32 v107, v112, v113
	v_cvt_pk_bf16_f32 v108, v114, v115
	v_cvt_pk_bf16_f32 v109, v116, v117
	global_store_dwordx4 v[118:119], v[106:109], off offset:2048
	global_load_dwordx4 v[106:109], v[118:119], off offset:2304
	s_waitcnt vmcnt(0)
	v_lshlrev_b32_e32 v110, 16, v106
	v_and_b32_e32 v111, 0xffff0000, v106
	v_lshlrev_b32_e32 v106, 16, v107
	v_and_b32_e32 v107, 0xffff0000, v107
	v_pk_fma_f32 v[104:105], v[104:105], v[146:147], v[106:107]
	v_lshlrev_b32_e32 v106, 16, v108
	v_and_b32_e32 v107, 0xffff0000, v108
	v_pk_fma_f32 v[106:107], v[98:99], v[144:145], v[106:107]
	v_lshlrev_b32_e32 v98, 16, v109
	v_and_b32_e32 v99, 0xffff0000, v109
	v_pk_fma_f32 v[102:103], v[102:103], v[148:149], v[110:111]
	v_pk_fma_f32 v[108:109], v[100:101], v[142:143], v[98:99]
	v_cvt_pk_bf16_f32 v98, v102, v103
	v_cvt_pk_bf16_f32 v99, v104, v105
	v_cvt_pk_bf16_f32 v100, v106, v107
	v_cvt_pk_bf16_f32 v101, v108, v109
	global_store_dwordx4 v[118:119], v[98:101], off offset:2304
	s_nop 1
	v_or_b32_e32 v98, 32, v162
	v_ashrrev_i32_e32 v99, 31, v98
	v_lshlrev_b64 v[98:99], 12, v[98:99]
	v_lshl_add_u64 v[98:99], s[12:13], 0, v[98:99]
	v_lshl_add_u64 v[102:103], v[98:99], 0, v[160:161]
	global_load_dwordx4 v[98:101], v[102:103], off offset:2048
	s_waitcnt vmcnt(0)
	v_lshlrev_b32_e32 v104, 16, v98
	v_and_b32_e32 v105, 0xffff0000, v98
	v_lshlrev_b32_e32 v98, 16, v99
	v_and_b32_e32 v99, 0xffff0000, v99
	v_pk_fma_f32 v[96:97], v[96:97], v[152:153], v[98:99]
	v_lshlrev_b32_e32 v98, 16, v100
	v_and_b32_e32 v99, 0xffff0000, v100
	v_pk_fma_f32 v[98:99], v[90:91], v[154:155], v[98:99]
	v_lshlrev_b32_e32 v90, 16, v101
	v_and_b32_e32 v91, 0xffff0000, v101
	v_pk_fma_f32 v[94:95], v[94:95], v[156:157], v[104:105]
	v_pk_fma_f32 v[100:101], v[92:93], v[150:151], v[90:91]
	v_cvt_pk_bf16_f32 v90, v94, v95
	v_cvt_pk_bf16_f32 v91, v96, v97
	v_cvt_pk_bf16_f32 v92, v98, v99
	v_cvt_pk_bf16_f32 v93, v100, v101
	global_store_dwordx4 v[102:103], v[90:93], off offset:2048
	global_load_dwordx4 v[90:93], v[102:103], off offset:2304
	s_waitcnt vmcnt(0)
	v_lshlrev_b32_e32 v94, 16, v90
	v_and_b32_e32 v95, 0xffff0000, v90
	v_lshlrev_b32_e32 v90, 16, v91
	v_and_b32_e32 v91, 0xffff0000, v91
	v_pk_fma_f32 v[88:89], v[88:89], v[146:147], v[90:91]
	v_lshlrev_b32_e32 v90, 16, v92
	v_and_b32_e32 v91, 0xffff0000, v92
	v_pk_fma_f32 v[90:91], v[82:83], v[144:145], v[90:91]
	v_lshlrev_b32_e32 v82, 16, v93
	v_and_b32_e32 v83, 0xffff0000, v93
	v_pk_fma_f32 v[86:87], v[86:87], v[148:149], v[94:95]
	v_pk_fma_f32 v[92:93], v[84:85], v[142:143], v[82:83]
	v_cvt_pk_bf16_f32 v82, v86, v87
	v_cvt_pk_bf16_f32 v83, v88, v89
	v_cvt_pk_bf16_f32 v84, v90, v91
	v_cvt_pk_bf16_f32 v85, v92, v93
	global_store_dwordx4 v[102:103], v[82:85], off offset:2304
	s_nop 1
	v_or_b32_e32 v82, 48, v162
	v_ashrrev_i32_e32 v83, 31, v82
	v_lshlrev_b64 v[82:83], 12, v[82:83]
	v_lshl_add_u64 v[82:83], s[12:13], 0, v[82:83]
	v_lshl_add_u64 v[82:83], v[82:83], 0, v[160:161]
	global_load_dwordx4 v[84:87], v[82:83], off offset:2048
	s_waitcnt vmcnt(0)
	v_lshlrev_b32_e32 v88, 16, v84
	v_and_b32_e32 v89, 0xffff0000, v84
	v_lshlrev_b32_e32 v84, 16, v85
	v_and_b32_e32 v85, 0xffff0000, v85
	v_pk_fma_f32 v[80:81], v[80:81], v[152:153], v[84:85]
	v_lshlrev_b32_e32 v84, 16, v86
	v_and_b32_e32 v85, 0xffff0000, v86
	v_pk_fma_f32 v[84:85], v[74:75], v[154:155], v[84:85]
	v_lshlrev_b32_e32 v74, 16, v87
	v_and_b32_e32 v75, 0xffff0000, v87
	v_pk_fma_f32 v[78:79], v[78:79], v[156:157], v[88:89]
	v_pk_fma_f32 v[86:87], v[76:77], v[150:151], v[74:75]
	v_cvt_pk_bf16_f32 v74, v78, v79
	v_cvt_pk_bf16_f32 v75, v80, v81
	v_cvt_pk_bf16_f32 v76, v84, v85
	v_cvt_pk_bf16_f32 v77, v86, v87
	global_store_dwordx4 v[82:83], v[74:77], off offset:2048
	global_load_dwordx4 v[74:77], v[82:83], off offset:2304
	s_waitcnt vmcnt(0)
	v_lshlrev_b32_e32 v78, 16, v74
	v_and_b32_e32 v79, 0xffff0000, v74
	v_lshlrev_b32_e32 v74, 16, v75
	v_and_b32_e32 v75, 0xffff0000, v75
	v_pk_fma_f32 v[72:73], v[72:73], v[146:147], v[74:75]
	v_lshlrev_b32_e32 v74, 16, v76
	v_and_b32_e32 v75, 0xffff0000, v76
	v_pk_fma_f32 v[74:75], v[66:67], v[144:145], v[74:75]
	v_lshlrev_b32_e32 v66, 16, v77
	v_and_b32_e32 v67, 0xffff0000, v77
	v_pk_fma_f32 v[70:71], v[70:71], v[148:149], v[78:79]
	v_pk_fma_f32 v[76:77], v[68:69], v[142:143], v[66:67]
	v_cvt_pk_bf16_f32 v66, v70, v71
	v_cvt_pk_bf16_f32 v67, v72, v73
	v_cvt_pk_bf16_f32 v68, v74, v75
	v_cvt_pk_bf16_f32 v69, v76, v77
	v_lshl_add_u64 v[70:71], v[158:159], 0, s[14:15]
	global_store_dwordx4 v[82:83], v[66:69], off offset:2304
	global_load_dwordx4 v[66:69], v[70:71], off offset:2048
	s_mov_b64 s[14:15], 0x90000
	s_waitcnt vmcnt(0)
	v_lshlrev_b32_e32 v72, 16, v66
	v_and_b32_e32 v73, 0xffff0000, v66
	v_lshlrev_b32_e32 v66, 16, v67
	v_and_b32_e32 v67, 0xffff0000, v67
	v_pk_fma_f32 v[64:65], v[64:65], v[152:153], v[66:67]
	v_lshlrev_b32_e32 v66, 16, v68
	v_and_b32_e32 v67, 0xffff0000, v68
	v_pk_fma_f32 v[66:67], v[58:59], v[154:155], v[66:67]
	v_lshlrev_b32_e32 v58, 16, v69
	v_and_b32_e32 v59, 0xffff0000, v69
	v_pk_fma_f32 v[62:63], v[62:63], v[156:157], v[72:73]
	v_pk_fma_f32 v[68:69], v[60:61], v[150:151], v[58:59]
	v_cvt_pk_bf16_f32 v58, v62, v63
	v_cvt_pk_bf16_f32 v59, v64, v65
	v_cvt_pk_bf16_f32 v60, v66, v67
	v_cvt_pk_bf16_f32 v61, v68, v69
	global_store_dwordx4 v[70:71], v[58:61], off offset:2048
	global_load_dwordx4 v[58:61], v[70:71], off offset:2304
	s_waitcnt vmcnt(0)
	v_lshlrev_b32_e32 v62, 16, v58
	v_and_b32_e32 v63, 0xffff0000, v58
	v_lshlrev_b32_e32 v58, 16, v59
	v_and_b32_e32 v59, 0xffff0000, v59
	v_pk_fma_f32 v[56:57], v[56:57], v[146:147], v[58:59]
	v_lshlrev_b32_e32 v58, 16, v60
	v_and_b32_e32 v59, 0xffff0000, v60
	v_pk_fma_f32 v[58:59], v[50:51], v[144:145], v[58:59]
	v_lshlrev_b32_e32 v50, 16, v61
	v_and_b32_e32 v51, 0xffff0000, v61
	v_pk_fma_f32 v[54:55], v[54:55], v[148:149], v[62:63]
	v_pk_fma_f32 v[60:61], v[52:53], v[142:143], v[50:51]
	v_cvt_pk_bf16_f32 v50, v54, v55
	v_cvt_pk_bf16_f32 v51, v56, v57
	v_cvt_pk_bf16_f32 v52, v58, v59
	v_cvt_pk_bf16_f32 v53, v60, v61
	v_lshl_add_u64 v[54:55], v[158:159], 0, s[14:15]
	global_store_dwordx4 v[70:71], v[50:53], off offset:2304
	global_load_dwordx4 v[50:53], v[54:55], off offset:2048
	s_mov_b64 s[14:15], 0xa0000
	s_waitcnt vmcnt(0)
	v_lshlrev_b32_e32 v56, 16, v50
	v_and_b32_e32 v57, 0xffff0000, v50
	v_lshlrev_b32_e32 v50, 16, v51
	v_and_b32_e32 v51, 0xffff0000, v51
	v_pk_fma_f32 v[48:49], v[48:49], v[152:153], v[50:51]
	v_lshlrev_b32_e32 v50, 16, v52
	v_and_b32_e32 v51, 0xffff0000, v52
	v_pk_fma_f32 v[50:51], v[42:43], v[154:155], v[50:51]
	v_lshlrev_b32_e32 v42, 16, v53
	v_and_b32_e32 v43, 0xffff0000, v53
	v_pk_fma_f32 v[46:47], v[46:47], v[156:157], v[56:57]
	v_pk_fma_f32 v[52:53], v[44:45], v[150:151], v[42:43]
	v_cvt_pk_bf16_f32 v42, v46, v47
	v_cvt_pk_bf16_f32 v43, v48, v49
	v_cvt_pk_bf16_f32 v44, v50, v51
	v_cvt_pk_bf16_f32 v45, v52, v53
	global_store_dwordx4 v[54:55], v[42:45], off offset:2048
	global_load_dwordx4 v[42:45], v[54:55], off offset:2304
	s_waitcnt vmcnt(0)
	v_lshlrev_b32_e32 v46, 16, v42
	v_and_b32_e32 v47, 0xffff0000, v42
	v_lshlrev_b32_e32 v42, 16, v43
	v_and_b32_e32 v43, 0xffff0000, v43
	v_pk_fma_f32 v[40:41], v[40:41], v[146:147], v[42:43]
	v_lshlrev_b32_e32 v42, 16, v44
	v_and_b32_e32 v43, 0xffff0000, v44
	v_pk_fma_f32 v[42:43], v[34:35], v[144:145], v[42:43]
	v_lshlrev_b32_e32 v34, 16, v45
	v_and_b32_e32 v35, 0xffff0000, v45
	v_pk_fma_f32 v[38:39], v[38:39], v[148:149], v[46:47]
	v_pk_fma_f32 v[44:45], v[36:37], v[142:143], v[34:35]
	v_cvt_pk_bf16_f32 v34, v38, v39
	v_cvt_pk_bf16_f32 v35, v40, v41
	v_cvt_pk_bf16_f32 v36, v42, v43
	v_cvt_pk_bf16_f32 v37, v44, v45
	v_lshl_add_u64 v[38:39], v[158:159], 0, s[14:15]
	global_store_dwordx4 v[54:55], v[34:37], off offset:2304
	global_load_dwordx4 v[34:37], v[38:39], off offset:2048
	s_mov_b64 s[14:15], 0xb0000
	s_waitcnt vmcnt(0)
	v_lshlrev_b32_e32 v40, 16, v34
	v_and_b32_e32 v41, 0xffff0000, v34
	v_lshlrev_b32_e32 v34, 16, v35
	v_and_b32_e32 v35, 0xffff0000, v35
	v_pk_fma_f32 v[32:33], v[32:33], v[152:153], v[34:35]
	v_lshlrev_b32_e32 v34, 16, v36
	v_and_b32_e32 v35, 0xffff0000, v36
	v_pk_fma_f32 v[34:35], v[26:27], v[154:155], v[34:35]
	v_lshlrev_b32_e32 v26, 16, v37
	v_and_b32_e32 v27, 0xffff0000, v37
	v_pk_fma_f32 v[30:31], v[30:31], v[156:157], v[40:41]
	v_pk_fma_f32 v[36:37], v[28:29], v[150:151], v[26:27]
	v_cvt_pk_bf16_f32 v26, v30, v31
	v_cvt_pk_bf16_f32 v27, v32, v33
	v_cvt_pk_bf16_f32 v28, v34, v35
	v_cvt_pk_bf16_f32 v29, v36, v37
	global_store_dwordx4 v[38:39], v[26:29], off offset:2048
	global_load_dwordx4 v[26:29], v[38:39], off offset:2304
	s_waitcnt vmcnt(0)
	v_lshlrev_b32_e32 v30, 16, v26
	v_and_b32_e32 v31, 0xffff0000, v26
	v_lshlrev_b32_e32 v26, 16, v27
	v_and_b32_e32 v27, 0xffff0000, v27
	v_pk_fma_f32 v[24:25], v[24:25], v[146:147], v[26:27]
	v_lshlrev_b32_e32 v26, 16, v28
	v_and_b32_e32 v27, 0xffff0000, v28
	v_pk_fma_f32 v[26:27], v[18:19], v[144:145], v[26:27]
	v_lshlrev_b32_e32 v18, 16, v29
	v_and_b32_e32 v19, 0xffff0000, v29
	v_pk_fma_f32 v[22:23], v[22:23], v[148:149], v[30:31]
	v_pk_fma_f32 v[28:29], v[20:21], v[142:143], v[18:19]
	v_cvt_pk_bf16_f32 v18, v22, v23
	v_cvt_pk_bf16_f32 v19, v24, v25
	v_cvt_pk_bf16_f32 v20, v26, v27
	v_cvt_pk_bf16_f32 v21, v28, v29
	global_store_dwordx4 v[38:39], v[18:21], off offset:2304
	s_nop 1
	v_lshl_add_u64 v[18:19], v[158:159], 0, s[14:15]
	global_load_dwordx4 v[20:23], v[18:19], off offset:2048
	s_mov_b64 s[14:15], s[6:7]
	s_waitcnt vmcnt(0)
	v_lshlrev_b32_e32 v24, 16, v20
	v_and_b32_e32 v25, 0xffff0000, v20
	v_lshlrev_b32_e32 v20, 16, v21
	v_and_b32_e32 v21, 0xffff0000, v21
	v_pk_fma_f32 v[16:17], v[16:17], v[152:153], v[20:21]
	v_lshlrev_b32_e32 v20, 16, v22
	v_and_b32_e32 v21, 0xffff0000, v22
	v_pk_fma_f32 v[20:21], v[10:11], v[154:155], v[20:21]
	v_lshlrev_b32_e32 v10, 16, v23
	v_and_b32_e32 v11, 0xffff0000, v23
	v_pk_fma_f32 v[14:15], v[14:15], v[156:157], v[24:25]
	v_pk_fma_f32 v[22:23], v[12:13], v[150:151], v[10:11]
	v_cvt_pk_bf16_f32 v10, v14, v15
	v_cvt_pk_bf16_f32 v11, v16, v17
	v_cvt_pk_bf16_f32 v12, v20, v21
	v_cvt_pk_bf16_f32 v13, v22, v23
	global_store_dwordx4 v[18:19], v[10:13], off offset:2048
	global_load_dwordx4 v[10:13], v[18:19], off offset:2304
	s_waitcnt vmcnt(0)
	v_lshlrev_b32_e32 v14, 16, v10
	v_and_b32_e32 v15, 0xffff0000, v10
	v_lshlrev_b32_e32 v10, 16, v11
	v_and_b32_e32 v11, 0xffff0000, v11
	v_pk_fma_f32 v[8:9], v[8:9], v[146:147], v[10:11]
	v_lshlrev_b32_e32 v10, 16, v12
	v_and_b32_e32 v11, 0xffff0000, v12
	v_pk_fma_f32 v[10:11], v[2:3], v[144:145], v[10:11]
	v_lshlrev_b32_e32 v2, 16, v13
	v_and_b32_e32 v3, 0xffff0000, v13
	v_pk_fma_f32 v[6:7], v[6:7], v[148:149], v[14:15]
	v_pk_fma_f32 v[12:13], v[4:5], v[142:143], v[2:3]
	v_cvt_pk_bf16_f32 v2, v6, v7
	v_cvt_pk_bf16_f32 v3, v8, v9
	v_cvt_pk_bf16_f32 v4, v10, v11
	v_cvt_pk_bf16_f32 v5, v12, v13
	global_store_dwordx4 v[18:19], v[2:5], off offset:2304
	s_cbranch_vccz .LBB0_363
	s_waitcnt vmcnt(0)
	s_cmpk_gt_u32 s30, 0xff
	s_cbranch_scc1 .LBB0_378
	s_barrier

.LBB0_400:
	s_add_u32 s16, s14, 0x100
	s_addc_u32 s17, s15, 0
	s_add_i32 s49, 0, 0x10000
	v_add_u32_e32 v154, s49, v164
	ds_read_b128 v[142:145], v154
	ds_read_b128 v[146:149], v154 offset:1024
	ds_read_b128 v[150:153], v154 offset:2048
	ds_read_b128 v[154:157], v154 offset:3072
	s_cmp_eq_u32 s48, 40
	s_cselect_b32 s21, s7, s17
	s_cselect_b32 s20, s6, s16
	s_cselect_b32 s19, s9, s47
	s_cselect_b32 s18, s8, s46
	v_lshl_add_u64 v[162:163], s[14:15], 0, v[138:139]
	s_add_i32 m0, s34, 0xc000
	ds_read_b128 v[158:161], v166
	ds_read_b128 v[168:171], v166 offset:1024
	ds_read_b128 v[172:175], v166 offset:2048
	ds_read_b128 v[190:193], v166 offset:3072
	ds_read_b128 v[194:197], v166 offset:4096
	ds_read_b128 v[198:201], v166 offset:5120
	ds_read_b128 v[202:205], v166 offset:6144
	ds_read_b128 v[206:209], v166 offset:7168
	global_load_lds_dwordx4 v[162:163], off
	v_lshl_add_u64 v[162:163], s[14:15], 0, v[140:141]
	s_add_i32 m0, s34, 0xe000
	s_nop 0
	global_load_lds_dwordx4 v[162:163], off
	s_waitcnt lgkmcnt(8)
	s_barrier
	s_waitcnt lgkmcnt(0)
	s_setprio 1
	s_waitcnt lgkmcnt(0)
	v_mfma_f32_16x16x32_bf16 v[126:129], v[142:145], v[158:161], v[126:129]
	v_mfma_f32_16x16x32_bf16 v[122:125], v[150:153], v[158:161], v[122:125]
	v_mfma_f32_16x16x32_bf16 v[110:113], v[142:145], v[172:175], v[110:113]
	v_mfma_f32_16x16x32_bf16 v[106:109], v[150:153], v[172:175], v[106:109]
	v_mfma_f32_16x16x32_bf16 v[94:97], v[142:145], v[194:197], v[94:97]
	v_mfma_f32_16x16x32_bf16 v[90:93], v[150:153], v[194:197], v[90:93]
	v_mfma_f32_16x16x32_bf16 v[78:81], v[142:145], v[202:205], v[78:81]
	v_mfma_f32_16x16x32_bf16 v[74:77], v[150:153], v[202:205], v[74:77]
	v_mfma_f32_16x16x32_bf16 v[126:129], v[146:149], v[168:171], v[126:129]
	v_mfma_f32_16x16x32_bf16 v[122:125], v[154:157], v[168:171], v[122:125]
	v_mfma_f32_16x16x32_bf16 v[110:113], v[146:149], v[190:193], v[110:113]
	v_mfma_f32_16x16x32_bf16 v[106:109], v[154:157], v[190:193], v[106:109]
	v_mfma_f32_16x16x32_bf16 v[94:97], v[146:149], v[198:201], v[94:97]
	v_mfma_f32_16x16x32_bf16 v[90:93], v[154:157], v[198:201], v[90:93]
	v_mfma_f32_16x16x32_bf16 v[78:81], v[146:149], v[206:209], v[78:81]
	v_mfma_f32_16x16x32_bf16 v[74:77], v[154:157], v[206:209], v[74:77]
	s_setprio 0
	s_barrier
	s_add_i32 s50, 0, 0x14000
	v_add_u32_e32 v162, s50, v164
	s_add_i32 s14, s49, s33
	ds_read_b128 v[210:213], v162
	ds_read_b128 v[214:217], v162 offset:1024
	ds_read_b128 v[218:221], v162 offset:2048
	ds_read_b128 v[222:225], v162 offset:3072
	v_lshl_add_u64 v[162:163], s[18:19], 0, v[132:133]
	s_mov_b32 m0, s14
	v_lshl_add_u64 v[176:177], s[18:19], 0, v[136:137]
	global_load_lds_dwordx4 v[162:163], off
	s_add_i32 m0, s14, 0x2000
	s_nop 0
	global_load_lds_dwordx4 v[176:177], off
	s_barrier
	s_waitcnt lgkmcnt(0)
	s_setprio 1
	s_waitcnt lgkmcnt(0)
	v_mfma_f32_16x16x32_bf16 v[118:121], v[210:213], v[158:161], v[118:121]
	v_mfma_f32_16x16x32_bf16 v[114:117], v[218:221], v[158:161], v[114:117]
	v_mfma_f32_16x16x32_bf16 v[102:105], v[210:213], v[172:175], v[102:105]
	v_mfma_f32_16x16x32_bf16 v[98:101], v[218:221], v[172:175], v[98:101]
	v_mfma_f32_16x16x32_bf16 v[86:89], v[210:213], v[194:197], v[86:89]
	v_mfma_f32_16x16x32_bf16 v[82:85], v[218:221], v[194:197], v[82:85]
	v_mfma_f32_16x16x32_bf16 v[70:73], v[210:213], v[202:205], v[70:73]
	v_mfma_f32_16x16x32_bf16 v[66:69], v[218:221], v[202:205], v[66:69]
	v_mfma_f32_16x16x32_bf16 v[118:121], v[214:217], v[168:171], v[118:121]
	v_mfma_f32_16x16x32_bf16 v[114:117], v[222:225], v[168:171], v[114:117]
	v_mfma_f32_16x16x32_bf16 v[102:105], v[214:217], v[190:193], v[102:105]
	v_mfma_f32_16x16x32_bf16 v[98:101], v[222:225], v[190:193], v[98:101]
	v_mfma_f32_16x16x32_bf16 v[86:89], v[214:217], v[198:201], v[86:89]
	v_mfma_f32_16x16x32_bf16 v[82:85], v[222:225], v[198:201], v[82:85]
	v_mfma_f32_16x16x32_bf16 v[70:73], v[214:217], v[206:209], v[70:73]
	v_mfma_f32_16x16x32_bf16 v[66:69], v[222:225], v[206:209], v[66:69]
	s_setprio 0
	s_mov_b32 m0, s34
	v_lshl_add_u64 v[186:187], s[20:21], 0, v[130:131]
	s_barrier
	ds_read_b128 v[158:161], v166 offset:16384
	ds_read_b128 v[168:171], v166 offset:17408
	ds_read_b128 v[172:175], v166 offset:18432
	ds_read_b128 v[190:193], v166 offset:19456
	ds_read_b128 v[194:197], v166 offset:20480
	ds_read_b128 v[198:201], v166 offset:21504
	ds_read_b128 v[202:205], v166 offset:22528
	ds_read_b128 v[206:209], v166 offset:23552
	global_load_lds_dwordx4 v[186:187], off
	v_lshl_add_u64 v[188:189], s[20:21], 0, v[134:135]
	s_mov_b32 m0, s35
	s_nop 0
	global_load_lds_dwordx4 v[188:189], off
	s_barrier
	s_waitcnt lgkmcnt(0)
	s_setprio 1
	s_waitcnt lgkmcnt(0)
	v_mfma_f32_16x16x32_bf16 v[62:65], v[142:145], v[158:161], v[62:65]
	v_mfma_f32_16x16x32_bf16 v[58:61], v[150:153], v[158:161], v[58:61]
	v_mfma_f32_16x16x32_bf16 v[46:49], v[142:145], v[172:175], v[46:49]
	v_mfma_f32_16x16x32_bf16 v[42:45], v[150:153], v[172:175], v[42:45]
	v_mfma_f32_16x16x32_bf16 v[30:33], v[142:145], v[194:197], v[30:33]
	v_mfma_f32_16x16x32_bf16 v[26:29], v[150:153], v[194:197], v[26:29]
	v_mfma_f32_16x16x32_bf16 v[14:17], v[142:145], v[202:205], v[14:17]
	v_mfma_f32_16x16x32_bf16 v[10:13], v[150:153], v[202:205], v[10:13]
	v_mfma_f32_16x16x32_bf16 v[62:65], v[146:149], v[168:171], v[62:65]
	v_mfma_f32_16x16x32_bf16 v[58:61], v[154:157], v[168:171], v[58:61]
	v_mfma_f32_16x16x32_bf16 v[46:49], v[146:149], v[190:193], v[46:49]
	v_mfma_f32_16x16x32_bf16 v[42:45], v[154:157], v[190:193], v[42:45]
	v_mfma_f32_16x16x32_bf16 v[30:33], v[146:149], v[198:201], v[30:33]
	v_mfma_f32_16x16x32_bf16 v[26:29], v[154:157], v[198:201], v[26:29]
	v_mfma_f32_16x16x32_bf16 v[14:17], v[146:149], v[206:209], v[14:17]
	v_mfma_f32_16x16x32_bf16 v[10:13], v[154:157], v[206:209], v[10:13]
	s_setprio 0
	s_barrier
	s_add_u32 s14, s18, 0xb0000
	s_addc_u32 s15, s19, 0
	s_add_i32 s49, s50, s33
	s_mov_b32 m0, s49
	s_nop 0
	global_load_lds_dwordx4 v132, s[14:15]
	s_add_i32 m0, s49, 0x2000
	s_nop 0
	global_load_lds_dwordx4 v136, s[14:15]
	s_waitcnt vmcnt(6)
	s_barrier
	s_setprio 1
	v_mfma_f32_16x16x32_bf16 v[54:57], v[210:213], v[158:161], v[54:57]
	v_mfma_f32_16x16x32_bf16 v[50:53], v[218:221], v[158:161], v[50:53]
	v_mfma_f32_16x16x32_bf16 v[38:41], v[210:213], v[172:175], v[38:41]
	v_mfma_f32_16x16x32_bf16 v[34:37], v[218:221], v[172:175], v[34:37]
	v_mfma_f32_16x16x32_bf16 v[22:25], v[210:213], v[194:197], v[22:25]
	v_mfma_f32_16x16x32_bf16 v[18:21], v[218:221], v[194:197], v[18:21]
	v_mfma_f32_16x16x32_bf16 v[6:9], v[210:213], v[202:205], v[6:9]
	v_mfma_f32_16x16x32_bf16 v[2:5], v[218:221], v[202:205], v[2:5]
	v_mfma_f32_16x16x32_bf16 v[54:57], v[214:217], v[168:171], v[54:57]
	v_mfma_f32_16x16x32_bf16 v[50:53], v[222:225], v[168:171], v[50:53]
	v_mfma_f32_16x16x32_bf16 v[38:41], v[214:217], v[190:193], v[38:41]
	v_mfma_f32_16x16x32_bf16 v[34:37], v[222:225], v[190:193], v[34:37]
	v_mfma_f32_16x16x32_bf16 v[22:25], v[214:217], v[198:201], v[22:25]
	v_mfma_f32_16x16x32_bf16 v[18:21], v[222:225], v[198:201], v[18:21]
	v_mfma_f32_16x16x32_bf16 v[6:9], v[214:217], v[206:209], v[6:9]
	v_mfma_f32_16x16x32_bf16 v[2:5], v[222:225], v[206:209], v[2:5]
	s_setprio 0
	s_add_i32 s49, 0, 0x18000
	v_add_u32_e32 v154, s49, v164
	s_barrier
	ds_read_b128 v[142:145], v154
	ds_read_b128 v[146:149], v154 offset:1024
	ds_read_b128 v[150:153], v154 offset:2048
	ds_read_b128 v[154:157], v154 offset:3072
	s_add_u32 s14, s20, 0xb8000
	s_addc_u32 s15, s21, 0
	s_mov_b32 m0, s36
	ds_read_b128 v[158:161], v166 offset:32768
	ds_read_b128 v[168:171], v166 offset:33792
	ds_read_b128 v[172:175], v166 offset:34816
	ds_read_b128 v[190:193], v166 offset:35840
	ds_read_b128 v[194:197], v166 offset:36864
	ds_read_b128 v[198:201], v166 offset:37888
	ds_read_b128 v[202:205], v166 offset:38912
	ds_read_b128 v[206:209], v166 offset:39936
	global_load_lds_dwordx4 v130, s[14:15]
	s_mov_b32 m0, s37
	s_nop 0
	global_load_lds_dwordx4 v134, s[14:15]
	s_waitcnt lgkmcnt(8)
	s_barrier
	s_waitcnt lgkmcnt(0)
	s_setprio 1
	s_waitcnt lgkmcnt(0)
	v_mfma_f32_16x16x32_bf16 v[126:129], v[142:145], v[158:161], v[126:129]
	v_mfma_f32_16x16x32_bf16 v[122:125], v[150:153], v[158:161], v[122:125]
	v_mfma_f32_16x16x32_bf16 v[110:113], v[142:145], v[172:175], v[110:113]
	v_mfma_f32_16x16x32_bf16 v[106:109], v[150:153], v[172:175], v[106:109]
	v_mfma_f32_16x16x32_bf16 v[94:97], v[142:145], v[194:197], v[94:97]
	v_mfma_f32_16x16x32_bf16 v[90:93], v[150:153], v[194:197], v[90:93]
	v_mfma_f32_16x16x32_bf16 v[78:81], v[142:145], v[202:205], v[78:81]
	v_mfma_f32_16x16x32_bf16 v[74:77], v[150:153], v[202:205], v[74:77]
	v_mfma_f32_16x16x32_bf16 v[126:129], v[146:149], v[168:171], v[126:129]
	v_mfma_f32_16x16x32_bf16 v[122:125], v[154:157], v[168:171], v[122:125]
	v_mfma_f32_16x16x32_bf16 v[110:113], v[146:149], v[190:193], v[110:113]
	v_mfma_f32_16x16x32_bf16 v[106:109], v[154:157], v[190:193], v[106:109]
	v_mfma_f32_16x16x32_bf16 v[94:97], v[146:149], v[198:201], v[94:97]
	v_mfma_f32_16x16x32_bf16 v[90:93], v[154:157], v[198:201], v[90:93]
	v_mfma_f32_16x16x32_bf16 v[78:81], v[146:149], v[206:209], v[78:81]
	v_mfma_f32_16x16x32_bf16 v[74:77], v[154:157], v[206:209], v[74:77]
	s_setprio 0
	s_barrier
	s_add_i32 s20, 0, 0x1c000
	s_add_i32 s14, s49, s33
	v_add_u32_e32 v167, s20, v164
	v_lshl_add_u64 v[162:163], v[162:163], 0, s[0:1]
	s_mov_b32 m0, s14
	ds_read_b128 v[210:213], v167
	ds_read_b128 v[214:217], v167 offset:1024
	ds_read_b128 v[218:221], v167 offset:2048
	ds_read_b128 v[222:225], v167 offset:3072
	global_load_lds_dwordx4 v[162:163], off
	v_lshl_add_u64 v[162:163], v[176:177], 0, s[0:1]
	s_add_i32 m0, s14, 0x2000
	s_nop 0
	global_load_lds_dwordx4 v[162:163], off
	s_barrier
	s_waitcnt lgkmcnt(0)
	s_setprio 1
	s_waitcnt lgkmcnt(0)
	v_mfma_f32_16x16x32_bf16 v[118:121], v[210:213], v[158:161], v[118:121]
	v_mfma_f32_16x16x32_bf16 v[114:117], v[218:221], v[158:161], v[114:117]
	v_mfma_f32_16x16x32_bf16 v[102:105], v[210:213], v[172:175], v[102:105]
	v_mfma_f32_16x16x32_bf16 v[98:101], v[218:221], v[172:175], v[98:101]
	v_mfma_f32_16x16x32_bf16 v[86:89], v[210:213], v[194:197], v[86:89]
	v_mfma_f32_16x16x32_bf16 v[82:85], v[218:221], v[194:197], v[82:85]
	v_mfma_f32_16x16x32_bf16 v[70:73], v[210:213], v[202:205], v[70:73]
	v_mfma_f32_16x16x32_bf16 v[66:69], v[218:221], v[202:205], v[66:69]
	v_mfma_f32_16x16x32_bf16 v[118:121], v[214:217], v[168:171], v[118:121]
	v_mfma_f32_16x16x32_bf16 v[114:117], v[222:225], v[168:171], v[114:117]
	v_mfma_f32_16x16x32_bf16 v[102:105], v[214:217], v[190:193], v[102:105]
	v_mfma_f32_16x16x32_bf16 v[98:101], v[222:225], v[190:193], v[98:101]
	v_mfma_f32_16x16x32_bf16 v[86:89], v[214:217], v[198:201], v[86:89]
	v_mfma_f32_16x16x32_bf16 v[82:85], v[222:225], v[198:201], v[82:85]
	v_mfma_f32_16x16x32_bf16 v[70:73], v[214:217], v[206:209], v[70:73]
	v_mfma_f32_16x16x32_bf16 v[66:69], v[222:225], v[206:209], v[66:69]
	s_setprio 0
	s_mov_b32 m0, s38
	v_lshl_add_u64 v[162:163], v[186:187], 0, s[0:1]
	s_barrier
	ds_read_b128 v[158:161], v166 offset:49152
	ds_read_b128 v[168:171], v166 offset:50176
	ds_read_b128 v[172:175], v166 offset:51200
	ds_read_b128 v[190:193], v166 offset:52224
	ds_read_b128 v[194:197], v166 offset:53248
	ds_read_b128 v[198:201], v166 offset:54272
	ds_read_b128 v[202:205], v166 offset:55296
	ds_read_b128 v[206:209], v166 offset:56320
	global_load_lds_dwordx4 v[162:163], off
	v_lshl_add_u64 v[162:163], v[188:189], 0, s[0:1]
	s_mov_b32 m0, s39
	s_nop 0
	global_load_lds_dwordx4 v[162:163], off
	s_barrier
	s_waitcnt lgkmcnt(0)
	s_setprio 1
	s_waitcnt lgkmcnt(0)
	v_mfma_f32_16x16x32_bf16 v[62:65], v[142:145], v[158:161], v[62:65]
	v_mfma_f32_16x16x32_bf16 v[58:61], v[150:153], v[158:161], v[58:61]
	v_mfma_f32_16x16x32_bf16 v[46:49], v[142:145], v[172:175], v[46:49]
	v_mfma_f32_16x16x32_bf16 v[42:45], v[150:153], v[172:175], v[42:45]
	v_mfma_f32_16x16x32_bf16 v[30:33], v[142:145], v[194:197], v[30:33]
	v_mfma_f32_16x16x32_bf16 v[26:29], v[150:153], v[194:197], v[26:29]
	v_mfma_f32_16x16x32_bf16 v[14:17], v[142:145], v[202:205], v[14:17]
	v_mfma_f32_16x16x32_bf16 v[10:13], v[150:153], v[202:205], v[10:13]
	v_mfma_f32_16x16x32_bf16 v[62:65], v[146:149], v[168:171], v[62:65]
	v_mfma_f32_16x16x32_bf16 v[58:61], v[154:157], v[168:171], v[58:61]
	v_mfma_f32_16x16x32_bf16 v[46:49], v[146:149], v[190:193], v[46:49]
	v_mfma_f32_16x16x32_bf16 v[42:45], v[154:157], v[190:193], v[42:45]
	v_mfma_f32_16x16x32_bf16 v[30:33], v[146:149], v[198:201], v[30:33]
	v_mfma_f32_16x16x32_bf16 v[26:29], v[154:157], v[198:201], v[26:29]
	v_mfma_f32_16x16x32_bf16 v[14:17], v[146:149], v[206:209], v[14:17]
	v_mfma_f32_16x16x32_bf16 v[10:13], v[154:157], v[206:209], v[10:13]
	s_setprio 0
	s_barrier
	s_add_u32 s14, s18, 0xb0080
	s_addc_u32 s15, s19, 0
	s_add_i32 s18, s20, s33
	s_mov_b32 m0, s18
	s_nop 0
	global_load_lds_dwordx4 v132, s[14:15]
	s_add_i32 m0, s18, 0x2000
	s_nop 0
	global_load_lds_dwordx4 v136, s[14:15]
	s_waitcnt vmcnt(6)
	s_barrier
	s_setprio 1
	v_mfma_f32_16x16x32_bf16 v[54:57], v[210:213], v[158:161], v[54:57]
	v_mfma_f32_16x16x32_bf16 v[50:53], v[218:221], v[158:161], v[50:53]
	v_mfma_f32_16x16x32_bf16 v[38:41], v[210:213], v[172:175], v[38:41]
	v_mfma_f32_16x16x32_bf16 v[34:37], v[218:221], v[172:175], v[34:37]
	v_mfma_f32_16x16x32_bf16 v[22:25], v[210:213], v[194:197], v[22:25]
	v_mfma_f32_16x16x32_bf16 v[18:21], v[218:221], v[194:197], v[18:21]
	v_mfma_f32_16x16x32_bf16 v[6:9], v[210:213], v[202:205], v[6:9]
	v_mfma_f32_16x16x32_bf16 v[2:5], v[218:221], v[202:205], v[2:5]
	v_mfma_f32_16x16x32_bf16 v[54:57], v[214:217], v[168:171], v[54:57]
	v_mfma_f32_16x16x32_bf16 v[50:53], v[222:225], v[168:171], v[50:53]
	v_mfma_f32_16x16x32_bf16 v[38:41], v[214:217], v[190:193], v[38:41]
	v_mfma_f32_16x16x32_bf16 v[34:37], v[222:225], v[190:193], v[34:37]
	v_mfma_f32_16x16x32_bf16 v[22:25], v[214:217], v[198:201], v[22:25]
	v_mfma_f32_16x16x32_bf16 v[18:21], v[222:225], v[198:201], v[18:21]
	v_mfma_f32_16x16x32_bf16 v[6:9], v[214:217], v[206:209], v[6:9]
	v_mfma_f32_16x16x32_bf16 v[2:5], v[222:225], v[206:209], v[2:5]
	s_setprio 0
	s_add_i32 s48, s48, 2
	s_add_u32 s46, s46, 0x100
	s_addc_u32 s47, s47, 0
	s_cmp_gt_u32 s48, 41
	s_mov_b64 s[14:15], s[16:17]
	s_barrier
	s_cbranch_scc0 .LBB0_400
	s_ashr_i32 s14, s44, 5
	v_lshl_or_b32 v176, s45, 8, v165
	s_mul_hi_i32 s15, s14, 0x9000
	s_mul_i32 s14, s14, 0x9000
	s_add_u32 s14, s26, s14
	v_ashrrev_i32_e32 v177, 31, v176
	s_addc_u32 s15, s27, s15
	v_lshlrev_b64 v[158:159], 2, v[176:177]
	v_lshl_add_u64 v[160:161], s[14:15], 0, v[158:159]
	global_load_dwordx4 v[142:145], v[160:161], off offset:16
	global_load_dwordx4 v[146:149], v[160:161], off
	v_lshl_add_u32 v162, s44, 8, v1
	v_ashrrev_i32_e32 v163, 31, v162
	s_mov_b64 s[14:15], 0x80000
	s_and_b64 vcc, exec, s[4:5]
	s_mov_b32 s45, s42
	s_mov_b32 s44, s43
	s_mov_b64 s[16:17], s[8:9]
	s_waitcnt vmcnt(0)
	v_pk_add_f32 v[144:145], v[144:145], 1.0 op_sel_hi:[1,0]
	v_pk_add_f32 v[148:149], v[148:149], 1.0 op_sel_hi:[1,0]
	v_pk_add_f32 v[146:147], v[146:147], 1.0 op_sel_hi:[1,0]
	v_pk_add_f32 v[142:143], v[142:143], 1.0 op_sel_hi:[1,0]
	v_pk_mul_f32 v[150:151], v[148:149], 0.5 op_sel_hi:[1,0]
	v_pk_mul_f32 v[152:153], v[146:147], 0.5 op_sel_hi:[1,0]
	v_pk_mul_f32 v[154:155], v[144:145], 0.5 op_sel_hi:[1,0]
	v_pk_mul_f32 v[156:157], v[142:143], 0.5 op_sel_hi:[1,0]
	global_load_dwordx4 v[146:149], v[160:161], off offset:528
	global_load_dwordx4 v[142:145], v[160:161], off offset:512
	s_waitcnt vmcnt(0)
	v_pk_add_f32 v[148:149], v[148:149], 1.0 op_sel_hi:[1,0]
	v_pk_add_f32 v[144:145], v[144:145], 1.0 op_sel_hi:[1,0]
	v_pk_add_f32 v[160:161], v[142:143], 1.0 op_sel_hi:[1,0]
	v_pk_mul_f32 v[142:143], v[144:145], 0.5 op_sel_hi:[1,0]
	v_pk_mul_f32 v[144:145], v[160:161], 0.5 op_sel_hi:[1,0]
	v_pk_add_f32 v[160:161], v[146:147], 1.0 op_sel_hi:[1,0]
	v_pk_mul_f32 v[146:147], v[148:149], 0.5 op_sel_hi:[1,0]
	v_pk_mul_f32 v[148:149], v[160:161], 0.5 op_sel_hi:[1,0]
	v_lshlrev_b64 v[160:161], 12, v[162:163]
	v_lshl_add_u64 v[168:169], s[2:3], 0, v[160:161]
	v_lshl_add_u64 v[186:187], v[168:169], 0, v[158:159]
	global_load_dwordx4 v[168:171], v[186:187], off offset:16
	global_load_dwordx4 v[172:175], v[186:187], off
	s_waitcnt vmcnt(0)
	v_pk_fma_f32 v[122:123], v[122:123], v[156:157], v[168:169]
	v_pk_fma_f32 v[128:129], v[128:129], v[150:151], v[174:175]
	v_pk_fma_f32 v[126:127], v[126:127], v[152:153], v[172:173]
	v_pk_fma_f32 v[170:171], v[124:125], v[154:155], v[170:171]
	v_cvt_pk_bf16_f32 v124, v126, v127
	v_cvt_pk_bf16_f32 v125, v128, v129
	v_cvt_pk_bf16_f32 v126, v122, v123
	v_lshl_add_u64 v[128:129], s[12:13], 0, v[160:161]
	v_lshlrev_b64 v[122:123], 1, v[176:177]
	v_cvt_pk_bf16_f32 v127, v170, v171
	v_lshl_add_u64 v[128:129], v[128:129], 0, v[122:123]
	global_store_dwordx4 v[128:129], v[124:127], off offset:2048
	global_load_dwordx4 v[124:127], v[186:187], off offset:528
	s_nop 0
	global_load_dwordx4 v[168:171], v[186:187], off offset:512
	s_waitcnt vmcnt(0)
	v_pk_fma_f32 v[126:127], v[116:117], v[146:147], v[126:127]
	v_pk_fma_f32 v[120:121], v[120:121], v[142:143], v[170:171]
	v_pk_fma_f32 v[118:119], v[118:119], v[144:145], v[168:169]
	v_pk_fma_f32 v[116:117], v[114:115], v[148:149], v[124:125]
	v_cvt_pk_bf16_f32 v114, v118, v119
	v_cvt_pk_bf16_f32 v115, v120, v121
	v_cvt_pk_bf16_f32 v116, v116, v117
	v_cvt_pk_bf16_f32 v117, v126, v127
	global_store_dwordx4 v[128:129], v[114:117], off offset:2304
	s_nop 1
	v_or_b32_e32 v114, 16, v162
	v_ashrrev_i32_e32 v115, 31, v114
	v_lshlrev_b64 v[124:125], 12, v[114:115]
	v_lshl_add_u64 v[114:115], s[2:3], 0, v[124:125]
	v_lshl_add_u64 v[126:127], v[114:115], 0, v[158:159]
	global_load_dwordx4 v[114:117], v[126:127], off offset:16
	global_load_dwordx4 v[118:121], v[126:127], off
	s_waitcnt vmcnt(0)
	v_pk_fma_f32 v[116:117], v[108:109], v[154:155], v[116:117]
	v_pk_fma_f32 v[110:111], v[110:111], v[152:153], v[118:119]
	v_pk_fma_f32 v[112:113], v[112:113], v[150:151], v[120:121]
	v_pk_fma_f32 v[108:109], v[106:107], v[156:157], v[114:115]
	v_cvt_pk_bf16_f32 v106, v110, v111
	v_lshl_add_u64 v[110:111], s[12:13], 0, v[124:125]
	v_cvt_pk_bf16_f32 v107, v112, v113
	v_cvt_pk_bf16_f32 v108, v108, v109
	v_cvt_pk_bf16_f32 v109, v116, v117
	v_lshl_add_u64 v[114:115], v[110:111], 0, v[122:123]
	global_store_dwordx4 v[114:115], v[106:109], off offset:2048
	global_load_dwordx4 v[106:109], v[126:127], off offset:528
	s_nop 0
	global_load_dwordx4 v[110:113], v[126:127], off offset:512
	s_waitcnt vmcnt(0)
	v_pk_fma_f32 v[108:109], v[100:101], v[146:147], v[108:109]
	v_pk_fma_f32 v[104:105], v[104:105], v[142:143], v[112:113]
	v_pk_fma_f32 v[102:103], v[102:103], v[144:145], v[110:111]
	v_pk_fma_f32 v[100:101], v[98:99], v[148:149], v[106:107]
	v_cvt_pk_bf16_f32 v98, v102, v103
	v_cvt_pk_bf16_f32 v99, v104, v105
	v_cvt_pk_bf16_f32 v100, v100, v101
	v_cvt_pk_bf16_f32 v101, v108, v109
	global_store_dwordx4 v[114:115], v[98:101], off offset:2304
	s_nop 1
	v_or_b32_e32 v98, 32, v162
	v_ashrrev_i32_e32 v99, 31, v98
	v_lshlrev_b64 v[106:107], 12, v[98:99]
	v_lshl_add_u64 v[98:99], s[2:3], 0, v[106:107]
	v_lshl_add_u64 v[108:109], v[98:99], 0, v[158:159]
	global_load_dwordx4 v[98:101], v[108:109], off offset:16
	global_load_dwordx4 v[102:105], v[108:109], off
	s_waitcnt vmcnt(0)
	v_pk_fma_f32 v[100:101], v[92:93], v[154:155], v[100:101]
	v_pk_fma_f32 v[94:95], v[94:95], v[152:153], v[102:103]
	v_pk_fma_f32 v[96:97], v[96:97], v[150:151], v[104:105]
	v_pk_fma_f32 v[92:93], v[90:91], v[156:157], v[98:99]
	v_cvt_pk_bf16_f32 v90, v94, v95
	v_lshl_add_u64 v[94:95], s[12:13], 0, v[106:107]
	v_cvt_pk_bf16_f32 v91, v96, v97
	v_cvt_pk_bf16_f32 v92, v92, v93
	v_cvt_pk_bf16_f32 v93, v100, v101
	v_lshl_add_u64 v[98:99], v[94:95], 0, v[122:123]
	global_store_dwordx4 v[98:99], v[90:93], off offset:2048
	global_load_dwordx4 v[90:93], v[108:109], off offset:528
	s_nop 0
	global_load_dwordx4 v[94:97], v[108:109], off offset:512
	s_waitcnt vmcnt(0)
	v_pk_fma_f32 v[92:93], v[84:85], v[146:147], v[92:93]
	v_pk_fma_f32 v[88:89], v[88:89], v[142:143], v[96:97]
	v_pk_fma_f32 v[86:87], v[86:87], v[144:145], v[94:95]
	v_pk_fma_f32 v[84:85], v[82:83], v[148:149], v[90:91]
	v_cvt_pk_bf16_f32 v82, v86, v87
	v_cvt_pk_bf16_f32 v83, v88, v89
	v_cvt_pk_bf16_f32 v84, v84, v85
	v_cvt_pk_bf16_f32 v85, v92, v93
	global_store_dwordx4 v[98:99], v[82:85], off offset:2304
	s_nop 1
	v_or_b32_e32 v82, 48, v162
	v_ashrrev_i32_e32 v83, 31, v82
	v_lshlrev_b64 v[90:91], 12, v[82:83]
	v_lshl_add_u64 v[82:83], s[2:3], 0, v[90:91]
	v_lshl_add_u64 v[92:93], v[82:83], 0, v[158:159]
	global_load_dwordx4 v[82:85], v[92:93], off offset:16
	global_load_dwordx4 v[86:89], v[92:93], off
	s_waitcnt vmcnt(0)
	v_pk_fma_f32 v[84:85], v[76:77], v[154:155], v[84:85]
	v_pk_fma_f32 v[78:79], v[78:79], v[152:153], v[86:87]
	v_pk_fma_f32 v[80:81], v[80:81], v[150:151], v[88:89]
	v_pk_fma_f32 v[76:77], v[74:75], v[156:157], v[82:83]
	v_cvt_pk_bf16_f32 v74, v78, v79
	v_lshl_add_u64 v[78:79], s[12:13], 0, v[90:91]
	v_cvt_pk_bf16_f32 v75, v80, v81
	v_cvt_pk_bf16_f32 v76, v76, v77
	v_cvt_pk_bf16_f32 v77, v84, v85
	v_lshl_add_u64 v[82:83], v[78:79], 0, v[122:123]
	global_store_dwordx4 v[82:83], v[74:77], off offset:2048
	global_load_dwordx4 v[74:77], v[92:93], off offset:528
	s_nop 0
	global_load_dwordx4 v[78:81], v[92:93], off offset:512
	s_waitcnt vmcnt(0)
	v_pk_fma_f32 v[76:77], v[68:69], v[146:147], v[76:77]
	v_pk_fma_f32 v[72:73], v[72:73], v[142:143], v[80:81]
	v_pk_fma_f32 v[70:71], v[70:71], v[144:145], v[78:79]
	v_pk_fma_f32 v[68:69], v[66:67], v[148:149], v[74:75]
	v_cvt_pk_bf16_f32 v66, v70, v71
	v_cvt_pk_bf16_f32 v67, v72, v73
	v_cvt_pk_bf16_f32 v68, v68, v69
	v_cvt_pk_bf16_f32 v69, v76, v77
	v_lshl_add_u64 v[74:75], v[160:161], 0, s[14:15]
	global_store_dwordx4 v[82:83], v[66:69], off offset:2304
	s_mov_b64 s[14:15], 0x90000
	s_nop 0
	v_lshl_add_u64 v[66:67], s[2:3], 0, v[74:75]
	v_lshl_add_u64 v[76:77], v[66:67], 0, v[158:159]
	global_load_dwordx4 v[66:69], v[76:77], off offset:16
	global_load_dwordx4 v[70:73], v[76:77], off
	s_waitcnt vmcnt(0)
	v_pk_fma_f32 v[68:69], v[60:61], v[154:155], v[68:69]
	v_pk_fma_f32 v[62:63], v[62:63], v[152:153], v[70:71]
	v_pk_fma_f32 v[64:65], v[64:65], v[150:151], v[72:73]
	v_pk_fma_f32 v[60:61], v[58:59], v[156:157], v[66:67]
	v_cvt_pk_bf16_f32 v58, v62, v63
	v_lshl_add_u64 v[62:63], s[12:13], 0, v[74:75]
	v_cvt_pk_bf16_f32 v59, v64, v65
	v_cvt_pk_bf16_f32 v60, v60, v61
	v_cvt_pk_bf16_f32 v61, v68, v69
	v_lshl_add_u64 v[66:67], v[62:63], 0, v[122:123]
	global_store_dwordx4 v[66:67], v[58:61], off offset:2048
	global_load_dwordx4 v[58:61], v[76:77], off offset:528
	s_nop 0
	global_load_dwordx4 v[62:65], v[76:77], off offset:512
	s_waitcnt vmcnt(0)
	v_pk_fma_f32 v[60:61], v[52:53], v[146:147], v[60:61]
	v_pk_fma_f32 v[56:57], v[56:57], v[142:143], v[64:65]
	v_pk_fma_f32 v[54:55], v[54:55], v[144:145], v[62:63]
	v_pk_fma_f32 v[52:53], v[50:51], v[148:149], v[58:59]
	v_cvt_pk_bf16_f32 v50, v54, v55
	v_cvt_pk_bf16_f32 v51, v56, v57
	v_cvt_pk_bf16_f32 v52, v52, v53
	v_cvt_pk_bf16_f32 v53, v60, v61
	v_lshl_add_u64 v[58:59], v[160:161], 0, s[14:15]
	global_store_dwordx4 v[66:67], v[50:53], off offset:2304
	s_mov_b64 s[14:15], 0xa0000
	s_nop 0
	v_lshl_add_u64 v[50:51], s[2:3], 0, v[58:59]
	v_lshl_add_u64 v[60:61], v[50:51], 0, v[158:159]
	global_load_dwordx4 v[50:53], v[60:61], off offset:16
	global_load_dwordx4 v[54:57], v[60:61], off
	s_waitcnt vmcnt(0)
	v_pk_fma_f32 v[52:53], v[44:45], v[154:155], v[52:53]
	v_pk_fma_f32 v[46:47], v[46:47], v[152:153], v[54:55]
	v_pk_fma_f32 v[48:49], v[48:49], v[150:151], v[56:57]
	v_pk_fma_f32 v[44:45], v[42:43], v[156:157], v[50:51]
	v_cvt_pk_bf16_f32 v42, v46, v47
	v_lshl_add_u64 v[46:47], s[12:13], 0, v[58:59]
	v_cvt_pk_bf16_f32 v43, v48, v49
	v_cvt_pk_bf16_f32 v44, v44, v45
	v_cvt_pk_bf16_f32 v45, v52, v53
	v_lshl_add_u64 v[50:51], v[46:47], 0, v[122:123]
	global_store_dwordx4 v[50:51], v[42:45], off offset:2048
	global_load_dwordx4 v[42:45], v[60:61], off offset:528
	s_nop 0
	global_load_dwordx4 v[46:49], v[60:61], off offset:512
	s_waitcnt vmcnt(0)
	v_pk_fma_f32 v[44:45], v[36:37], v[146:147], v[44:45]
	v_pk_fma_f32 v[40:41], v[40:41], v[142:143], v[48:49]
	v_pk_fma_f32 v[38:39], v[38:39], v[144:145], v[46:47]
	v_pk_fma_f32 v[36:37], v[34:35], v[148:149], v[42:43]
	v_cvt_pk_bf16_f32 v34, v38, v39
	v_cvt_pk_bf16_f32 v35, v40, v41
	v_cvt_pk_bf16_f32 v36, v36, v37
	v_cvt_pk_bf16_f32 v37, v44, v45
	v_lshl_add_u64 v[42:43], v[160:161], 0, s[14:15]
	global_store_dwordx4 v[50:51], v[34:37], off offset:2304
	s_mov_b64 s[14:15], 0xb0000
	s_nop 0
	v_lshl_add_u64 v[34:35], s[2:3], 0, v[42:43]
	v_lshl_add_u64 v[44:45], v[34:35], 0, v[158:159]
	global_load_dwordx4 v[34:37], v[44:45], off offset:16
	global_load_dwordx4 v[38:41], v[44:45], off
	s_waitcnt vmcnt(0)
	v_pk_fma_f32 v[36:37], v[28:29], v[154:155], v[36:37]
	v_pk_fma_f32 v[30:31], v[30:31], v[152:153], v[38:39]
	v_pk_fma_f32 v[32:33], v[32:33], v[150:151], v[40:41]
	v_pk_fma_f32 v[28:29], v[26:27], v[156:157], v[34:35]
	v_cvt_pk_bf16_f32 v26, v30, v31
	v_lshl_add_u64 v[30:31], s[12:13], 0, v[42:43]
	v_cvt_pk_bf16_f32 v27, v32, v33
	v_cvt_pk_bf16_f32 v28, v28, v29
	v_cvt_pk_bf16_f32 v29, v36, v37
	v_lshl_add_u64 v[34:35], v[30:31], 0, v[122:123]
	global_store_dwordx4 v[34:35], v[26:29], off offset:2048
	global_load_dwordx4 v[26:29], v[44:45], off offset:528
	s_nop 0
	global_load_dwordx4 v[30:33], v[44:45], off offset:512
	s_waitcnt vmcnt(0)
	v_pk_fma_f32 v[28:29], v[20:21], v[146:147], v[28:29]
	v_pk_fma_f32 v[24:25], v[24:25], v[142:143], v[32:33]
	v_pk_fma_f32 v[22:23], v[22:23], v[144:145], v[30:31]
	v_pk_fma_f32 v[20:21], v[18:19], v[148:149], v[26:27]
	v_cvt_pk_bf16_f32 v18, v22, v23
	v_cvt_pk_bf16_f32 v19, v24, v25
	v_cvt_pk_bf16_f32 v20, v20, v21
	v_cvt_pk_bf16_f32 v21, v28, v29
	v_lshl_add_u64 v[26:27], v[160:161], 0, s[14:15]
	global_store_dwordx4 v[34:35], v[18:21], off offset:2304
	s_mov_b64 s[14:15], s[6:7]
	s_nop 0
	v_lshl_add_u64 v[18:19], s[2:3], 0, v[26:27]
	v_lshl_add_u64 v[28:29], v[18:19], 0, v[158:159]
	global_load_dwordx4 v[18:21], v[28:29], off offset:16
	global_load_dwordx4 v[22:25], v[28:29], off
	s_waitcnt vmcnt(0)
	v_pk_fma_f32 v[20:21], v[12:13], v[154:155], v[20:21]
	v_pk_fma_f32 v[14:15], v[14:15], v[152:153], v[22:23]
	v_pk_fma_f32 v[16:17], v[16:17], v[150:151], v[24:25]
	v_pk_fma_f32 v[12:13], v[10:11], v[156:157], v[18:19]
	v_cvt_pk_bf16_f32 v10, v14, v15
	v_lshl_add_u64 v[14:15], s[12:13], 0, v[26:27]
	v_cvt_pk_bf16_f32 v11, v16, v17
	v_cvt_pk_bf16_f32 v12, v12, v13
	v_cvt_pk_bf16_f32 v13, v20, v21
	v_lshl_add_u64 v[18:19], v[14:15], 0, v[122:123]
	global_store_dwordx4 v[18:19], v[10:13], off offset:2048
	global_load_dwordx4 v[10:13], v[28:29], off offset:528
	s_nop 0
	global_load_dwordx4 v[14:17], v[28:29], off offset:512
	s_waitcnt vmcnt(0)
	v_pk_fma_f32 v[12:13], v[4:5], v[146:147], v[12:13]
	v_pk_fma_f32 v[8:9], v[8:9], v[142:143], v[16:17]
	v_pk_fma_f32 v[6:7], v[6:7], v[144:145], v[14:15]
	v_pk_fma_f32 v[4:5], v[2:3], v[148:149], v[10:11]
	v_cvt_pk_bf16_f32 v2, v6, v7
	v_cvt_pk_bf16_f32 v3, v8, v9
	v_cvt_pk_bf16_f32 v4, v4, v5
	v_cvt_pk_bf16_f32 v5, v12, v13
	global_store_dwordx4 v[18:19], v[2:5], off offset:2304
	s_cbranch_vccz .LBB0_389
	s_waitcnt vmcnt(0)
	s_cmpk_gt_u32 s30, 0xff
	s_cbranch_scc1 .LBB0_404
	s_barrier

.LBB0_528:
	s_add_u32 s22, s20, 0xfffc0080
	s_addc_u32 s23, s21, -1
	s_add_i32 s55, 0, 0x10000
	v_add_u32_e32 v144, s55, v146
	ds_read_b128 v[150:153], v144
	ds_read_b128 v[154:157], v144 offset:1024
	ds_read_b128 v[158:161], v144 offset:2048
	ds_read_b128 v[162:165], v144 offset:3072
	s_cmp_eq_u32 s54, 12
	s_cselect_b32 s25, s11, s23
	s_cselect_b32 s24, s15, s22
	s_cselect_b32 s23, s13, s53
	s_cselect_b32 s22, s51, s52
	s_add_i32 m0, s41, 0xc000
	ds_read_b128 v[166:169], v148
	ds_read_b128 v[170:173], v148 offset:1024
	ds_read_b128 v[174:177], v148 offset:2048
	ds_read_b128 v[190:193], v148 offset:3072
	ds_read_b128 v[194:197], v148 offset:4096
	ds_read_b128 v[198:201], v148 offset:5120
	ds_read_b128 v[202:205], v148 offset:6144
	ds_read_b128 v[206:209], v148 offset:7168
	global_load_lds_dwordx4 v140, s[20:21]
	v_lshl_add_u64 v[144:145], s[20:21], 0, v[142:143]
	s_add_i32 m0, s41, 0xe000
	s_nop 0
	global_load_lds_dwordx4 v[144:145], off
	s_waitcnt lgkmcnt(8)
	s_barrier
	s_waitcnt lgkmcnt(0)
	s_setprio 1
	s_waitcnt lgkmcnt(0)
	v_mfma_f32_16x16x32_bf16 v[86:89], v[150:153], v[166:169], v[86:89]
	v_mfma_f32_16x16x32_bf16 v[82:85], v[158:161], v[166:169], v[82:85]
	v_mfma_f32_16x16x32_bf16 v[78:81], v[150:153], v[174:177], v[78:81]
	v_mfma_f32_16x16x32_bf16 v[74:77], v[158:161], v[174:177], v[74:77]
	v_mfma_f32_16x16x32_bf16 v[62:65], v[150:153], v[194:197], v[62:65]
	v_mfma_f32_16x16x32_bf16 v[58:61], v[158:161], v[194:197], v[58:61]
	v_mfma_f32_16x16x32_bf16 v[54:57], v[150:153], v[202:205], v[54:57]
	v_mfma_f32_16x16x32_bf16 v[50:53], v[158:161], v[202:205], v[50:53]
	v_mfma_f32_16x16x32_bf16 v[86:89], v[154:157], v[170:173], v[86:89]
	v_mfma_f32_16x16x32_bf16 v[82:85], v[162:165], v[170:173], v[82:85]
	v_mfma_f32_16x16x32_bf16 v[78:81], v[154:157], v[190:193], v[78:81]
	v_mfma_f32_16x16x32_bf16 v[74:77], v[162:165], v[190:193], v[74:77]
	v_mfma_f32_16x16x32_bf16 v[62:65], v[154:157], v[198:201], v[62:65]
	v_mfma_f32_16x16x32_bf16 v[58:61], v[162:165], v[198:201], v[58:61]
	v_mfma_f32_16x16x32_bf16 v[54:57], v[154:157], v[206:209], v[54:57]
	v_mfma_f32_16x16x32_bf16 v[50:53], v[162:165], v[206:209], v[50:53]
	s_setprio 0
	s_barrier
	s_add_i32 s58, 0, 0x14000
	v_add_u32_e32 v144, s58, v146
	s_add_i32 s55, s55, s35
	ds_read_b128 v[210:213], v144
	ds_read_b128 v[214:217], v144 offset:1024
	ds_read_b128 v[218:221], v144 offset:2048
	ds_read_b128 v[222:225], v144 offset:3072
	v_lshl_add_u64 v[144:145], s[22:23], 0, v[134:135]
	s_mov_b32 m0, s55
	v_lshl_add_u64 v[186:187], s[22:23], 0, v[130:131]
	global_load_lds_dwordx4 v[144:145], off
	s_add_i32 m0, s55, 0x2000
	s_nop 0
	global_load_lds_dwordx4 v[186:187], off
	s_barrier
	s_waitcnt lgkmcnt(0)
	s_setprio 1
	s_waitcnt lgkmcnt(0)
	v_mfma_f32_16x16x32_bf16 v[126:129], v[210:213], v[166:169], v[126:129]
	v_mfma_f32_16x16x32_bf16 v[122:125], v[218:221], v[166:169], v[122:125]
	v_mfma_f32_16x16x32_bf16 v[118:121], v[210:213], v[174:177], v[118:121]
	v_mfma_f32_16x16x32_bf16 v[114:117], v[218:221], v[174:177], v[114:117]
	v_mfma_f32_16x16x32_bf16 v[110:113], v[210:213], v[194:197], v[110:113]
	v_mfma_f32_16x16x32_bf16 v[106:109], v[218:221], v[194:197], v[106:109]
	v_mfma_f32_16x16x32_bf16 v[102:105], v[210:213], v[202:205], v[102:105]
	v_mfma_f32_16x16x32_bf16 v[98:101], v[218:221], v[202:205], v[98:101]
	v_mfma_f32_16x16x32_bf16 v[126:129], v[214:217], v[170:173], v[126:129]
	v_mfma_f32_16x16x32_bf16 v[122:125], v[222:225], v[170:173], v[122:125]
	v_mfma_f32_16x16x32_bf16 v[118:121], v[214:217], v[190:193], v[118:121]
	v_mfma_f32_16x16x32_bf16 v[114:117], v[222:225], v[190:193], v[114:117]
	v_mfma_f32_16x16x32_bf16 v[110:113], v[214:217], v[198:201], v[110:113]
	v_mfma_f32_16x16x32_bf16 v[106:109], v[222:225], v[198:201], v[106:109]
	v_mfma_f32_16x16x32_bf16 v[102:105], v[214:217], v[206:209], v[102:105]
	v_mfma_f32_16x16x32_bf16 v[98:101], v[222:225], v[206:209], v[98:101]
	s_setprio 0
	s_mov_b32 m0, s41
	v_lshl_add_u64 v[188:189], s[24:25], 0, v[136:137]
	s_barrier
	ds_read_b128 v[166:169], v148 offset:16384
	ds_read_b128 v[170:173], v148 offset:17408
	ds_read_b128 v[174:177], v148 offset:18432
	ds_read_b128 v[190:193], v148 offset:19456
	ds_read_b128 v[194:197], v148 offset:20480
	ds_read_b128 v[198:201], v148 offset:21504
	ds_read_b128 v[202:205], v148 offset:22528
	ds_read_b128 v[206:209], v148 offset:23552
	global_load_lds_dwordx4 v[188:189], off
	v_lshl_add_u64 v[226:227], s[24:25], 0, v[132:133]
	s_mov_b32 m0, s42
	s_nop 0
	global_load_lds_dwordx4 v[226:227], off
	s_barrier
	s_waitcnt lgkmcnt(0)
	s_setprio 1
	s_waitcnt lgkmcnt(0)
	v_mfma_f32_16x16x32_bf16 v[34:37], v[150:153], v[166:169], v[34:37]
	v_mfma_f32_16x16x32_bf16 v[26:29], v[158:161], v[166:169], v[26:29]
	v_mfma_f32_16x16x32_bf16 v[22:25], v[150:153], v[174:177], v[22:25]
	v_mfma_f32_16x16x32_bf16 v[18:21], v[158:161], v[174:177], v[18:21]
	v_mfma_f32_16x16x32_bf16 v[14:17], v[150:153], v[194:197], v[14:17]
	v_mfma_f32_16x16x32_bf16 v[10:13], v[158:161], v[194:197], v[10:13]
	v_mfma_f32_16x16x32_bf16 v[6:9], v[150:153], v[202:205], v[6:9]
	v_mfma_f32_16x16x32_bf16 v[2:5], v[158:161], v[202:205], v[2:5]
	v_mfma_f32_16x16x32_bf16 v[34:37], v[154:157], v[170:173], v[34:37]
	v_mfma_f32_16x16x32_bf16 v[26:29], v[162:165], v[170:173], v[26:29]
	v_mfma_f32_16x16x32_bf16 v[22:25], v[154:157], v[190:193], v[22:25]
	v_mfma_f32_16x16x32_bf16 v[18:21], v[162:165], v[190:193], v[18:21]
	v_mfma_f32_16x16x32_bf16 v[14:17], v[154:157], v[198:201], v[14:17]
	v_mfma_f32_16x16x32_bf16 v[10:13], v[162:165], v[198:201], v[10:13]
	v_mfma_f32_16x16x32_bf16 v[6:9], v[154:157], v[206:209], v[6:9]
	v_mfma_f32_16x16x32_bf16 v[2:5], v[162:165], v[206:209], v[2:5]
	s_setprio 0
	s_barrier
	s_add_u32 s56, s22, 0x40000
	s_addc_u32 s57, s23, 0
	s_add_i32 s55, s58, s35
	s_mov_b32 m0, s55
	s_nop 0
	global_load_lds_dwordx4 v134, s[56:57]
	s_add_i32 m0, s55, 0x2000
	s_nop 0
	global_load_lds_dwordx4 v130, s[56:57]
	s_waitcnt vmcnt(6)
	s_barrier
	s_setprio 1
	v_mfma_f32_16x16x32_bf16 v[94:97], v[210:213], v[166:169], v[94:97]
	v_mfma_f32_16x16x32_bf16 v[90:93], v[218:221], v[166:169], v[90:93]
	v_mfma_f32_16x16x32_bf16 v[70:73], v[210:213], v[174:177], v[70:73]
	v_mfma_f32_16x16x32_bf16 v[66:69], v[218:221], v[174:177], v[66:69]
	v_mfma_f32_16x16x32_bf16 v[46:49], v[210:213], v[194:197], v[46:49]
	v_mfma_f32_16x16x32_bf16 v[42:45], v[218:221], v[194:197], v[42:45]
	v_mfma_f32_16x16x32_bf16 v[38:41], v[210:213], v[202:205], v[38:41]
	v_mfma_f32_16x16x32_bf16 v[30:33], v[218:221], v[202:205], v[30:33]
	v_mfma_f32_16x16x32_bf16 v[94:97], v[214:217], v[170:173], v[94:97]
	v_mfma_f32_16x16x32_bf16 v[90:93], v[222:225], v[170:173], v[90:93]
	v_mfma_f32_16x16x32_bf16 v[70:73], v[214:217], v[190:193], v[70:73]
	v_mfma_f32_16x16x32_bf16 v[66:69], v[222:225], v[190:193], v[66:69]
	v_mfma_f32_16x16x32_bf16 v[46:49], v[214:217], v[198:201], v[46:49]
	v_mfma_f32_16x16x32_bf16 v[42:45], v[222:225], v[198:201], v[42:45]
	v_mfma_f32_16x16x32_bf16 v[38:41], v[214:217], v[206:209], v[38:41]
	v_mfma_f32_16x16x32_bf16 v[30:33], v[222:225], v[206:209], v[30:33]
	s_setprio 0
	s_add_i32 s55, 0, 0x18000
	v_add_u32_e32 v149, s55, v146
	s_barrier
	ds_read_b128 v[150:153], v149
	ds_read_b128 v[154:157], v149 offset:1024
	ds_read_b128 v[158:161], v149 offset:2048
	ds_read_b128 v[162:165], v149 offset:3072
	s_add_u32 s24, s24, 0x40000
	s_addc_u32 s25, s25, 0
	s_mov_b32 m0, s43
	ds_read_b128 v[166:169], v148 offset:32768
	ds_read_b128 v[170:173], v148 offset:33792
	ds_read_b128 v[174:177], v148 offset:34816
	ds_read_b128 v[190:193], v148 offset:35840
	ds_read_b128 v[194:197], v148 offset:36864
	ds_read_b128 v[198:201], v148 offset:37888
	ds_read_b128 v[202:205], v148 offset:38912
	ds_read_b128 v[206:209], v148 offset:39936
	global_load_lds_dwordx4 v136, s[24:25]
	s_mov_b32 m0, s44
	s_nop 0
	global_load_lds_dwordx4 v132, s[24:25]
	s_waitcnt lgkmcnt(8)
	s_barrier
	s_waitcnt lgkmcnt(0)
	s_setprio 1
	s_waitcnt lgkmcnt(0)
	v_mfma_f32_16x16x32_bf16 v[86:89], v[150:153], v[166:169], v[86:89]
	v_mfma_f32_16x16x32_bf16 v[82:85], v[158:161], v[166:169], v[82:85]
	v_mfma_f32_16x16x32_bf16 v[78:81], v[150:153], v[174:177], v[78:81]
	v_mfma_f32_16x16x32_bf16 v[74:77], v[158:161], v[174:177], v[74:77]
	v_mfma_f32_16x16x32_bf16 v[62:65], v[150:153], v[194:197], v[62:65]
	v_mfma_f32_16x16x32_bf16 v[58:61], v[158:161], v[194:197], v[58:61]
	v_mfma_f32_16x16x32_bf16 v[54:57], v[150:153], v[202:205], v[54:57]
	v_mfma_f32_16x16x32_bf16 v[50:53], v[158:161], v[202:205], v[50:53]
	v_mfma_f32_16x16x32_bf16 v[86:89], v[154:157], v[170:173], v[86:89]
	v_mfma_f32_16x16x32_bf16 v[82:85], v[162:165], v[170:173], v[82:85]
	v_mfma_f32_16x16x32_bf16 v[78:81], v[154:157], v[190:193], v[78:81]
	v_mfma_f32_16x16x32_bf16 v[74:77], v[162:165], v[190:193], v[74:77]
	v_mfma_f32_16x16x32_bf16 v[62:65], v[154:157], v[198:201], v[62:65]
	v_mfma_f32_16x16x32_bf16 v[58:61], v[162:165], v[198:201], v[58:61]
	v_mfma_f32_16x16x32_bf16 v[54:57], v[154:157], v[206:209], v[54:57]
	v_mfma_f32_16x16x32_bf16 v[50:53], v[162:165], v[206:209], v[50:53]
	s_setprio 0
	s_barrier
	s_add_i32 s24, 0, 0x1c000
	s_add_i32 s25, s55, s35
	v_add_u32_e32 v149, s24, v146
	v_lshl_add_u64 v[144:145], v[144:145], 0, s[0:1]
	s_mov_b32 m0, s25
	ds_read_b128 v[210:213], v149
	ds_read_b128 v[214:217], v149 offset:1024
	ds_read_b128 v[218:221], v149 offset:2048
	ds_read_b128 v[222:225], v149 offset:3072
	global_load_lds_dwordx4 v[144:145], off
	v_lshl_add_u64 v[144:145], v[186:187], 0, s[0:1]
	s_add_i32 m0, s25, 0x2000
	s_nop 0
	global_load_lds_dwordx4 v[144:145], off
	s_barrier
	s_waitcnt lgkmcnt(0)
	s_setprio 1
	s_waitcnt lgkmcnt(0)
	v_mfma_f32_16x16x32_bf16 v[126:129], v[210:213], v[166:169], v[126:129]
	v_mfma_f32_16x16x32_bf16 v[122:125], v[218:221], v[166:169], v[122:125]
	v_mfma_f32_16x16x32_bf16 v[118:121], v[210:213], v[174:177], v[118:121]
	v_mfma_f32_16x16x32_bf16 v[114:117], v[218:221], v[174:177], v[114:117]
	v_mfma_f32_16x16x32_bf16 v[110:113], v[210:213], v[194:197], v[110:113]
	v_mfma_f32_16x16x32_bf16 v[106:109], v[218:221], v[194:197], v[106:109]
	v_mfma_f32_16x16x32_bf16 v[102:105], v[210:213], v[202:205], v[102:105]
	v_mfma_f32_16x16x32_bf16 v[98:101], v[218:221], v[202:205], v[98:101]
	v_mfma_f32_16x16x32_bf16 v[126:129], v[214:217], v[170:173], v[126:129]
	v_mfma_f32_16x16x32_bf16 v[122:125], v[222:225], v[170:173], v[122:125]
	v_mfma_f32_16x16x32_bf16 v[118:121], v[214:217], v[190:193], v[118:121]
	v_mfma_f32_16x16x32_bf16 v[114:117], v[222:225], v[190:193], v[114:117]
	v_mfma_f32_16x16x32_bf16 v[110:113], v[214:217], v[198:201], v[110:113]
	v_mfma_f32_16x16x32_bf16 v[106:109], v[222:225], v[198:201], v[106:109]
	v_mfma_f32_16x16x32_bf16 v[102:105], v[214:217], v[206:209], v[102:105]
	v_mfma_f32_16x16x32_bf16 v[98:101], v[222:225], v[206:209], v[98:101]
	s_setprio 0
	s_mov_b32 m0, s46
	v_lshl_add_u64 v[144:145], v[188:189], 0, s[0:1]
	s_barrier
	ds_read_b128 v[166:169], v148 offset:49152
	ds_read_b128 v[170:173], v148 offset:50176
	ds_read_b128 v[174:177], v148 offset:51200
	ds_read_b128 v[190:193], v148 offset:52224
	ds_read_b128 v[194:197], v148 offset:53248
	ds_read_b128 v[198:201], v148 offset:54272
	ds_read_b128 v[202:205], v148 offset:55296
	ds_read_b128 v[206:209], v148 offset:56320
	global_load_lds_dwordx4 v[144:145], off
	v_lshl_add_u64 v[144:145], v[226:227], 0, s[0:1]
	s_mov_b32 m0, s47
	s_nop 0
	global_load_lds_dwordx4 v[144:145], off
	s_barrier
	s_waitcnt lgkmcnt(0)
	s_setprio 1
	s_waitcnt lgkmcnt(0)
	v_mfma_f32_16x16x32_bf16 v[34:37], v[150:153], v[166:169], v[34:37]
	v_mfma_f32_16x16x32_bf16 v[26:29], v[158:161], v[166:169], v[26:29]
	v_mfma_f32_16x16x32_bf16 v[22:25], v[150:153], v[174:177], v[22:25]
	v_mfma_f32_16x16x32_bf16 v[18:21], v[158:161], v[174:177], v[18:21]
	v_mfma_f32_16x16x32_bf16 v[14:17], v[150:153], v[194:197], v[14:17]
	v_mfma_f32_16x16x32_bf16 v[10:13], v[158:161], v[194:197], v[10:13]
	v_mfma_f32_16x16x32_bf16 v[6:9], v[150:153], v[202:205], v[6:9]
	v_mfma_f32_16x16x32_bf16 v[2:5], v[158:161], v[202:205], v[2:5]
	v_mfma_f32_16x16x32_bf16 v[34:37], v[154:157], v[170:173], v[34:37]
	v_mfma_f32_16x16x32_bf16 v[26:29], v[162:165], v[170:173], v[26:29]
	v_mfma_f32_16x16x32_bf16 v[22:25], v[154:157], v[190:193], v[22:25]
	v_mfma_f32_16x16x32_bf16 v[18:21], v[162:165], v[190:193], v[18:21]
	v_mfma_f32_16x16x32_bf16 v[14:17], v[154:157], v[198:201], v[14:17]
	v_mfma_f32_16x16x32_bf16 v[10:13], v[162:165], v[198:201], v[10:13]
	v_mfma_f32_16x16x32_bf16 v[6:9], v[154:157], v[206:209], v[6:9]
	v_mfma_f32_16x16x32_bf16 v[2:5], v[162:165], v[206:209], v[2:5]
	s_setprio 0
	s_barrier
	s_add_u32 s22, s22, 0x40080
	s_addc_u32 s23, s23, 0
	s_add_i32 s24, s24, s35
	s_mov_b32 m0, s24
	s_nop 0
	global_load_lds_dwordx4 v134, s[22:23]
	v_lshl_add_u64 v[144:145], s[22:23], 0, v[130:131]
	s_add_i32 m0, s24, 0x2000
	s_nop 0
	global_load_lds_dwordx4 v[144:145], off
	s_waitcnt vmcnt(6)
	s_barrier
	s_setprio 1
	v_mfma_f32_16x16x32_bf16 v[94:97], v[210:213], v[166:169], v[94:97]
	v_mfma_f32_16x16x32_bf16 v[90:93], v[218:221], v[166:169], v[90:93]
	v_mfma_f32_16x16x32_bf16 v[70:73], v[210:213], v[174:177], v[70:73]
	v_mfma_f32_16x16x32_bf16 v[66:69], v[218:221], v[174:177], v[66:69]
	v_mfma_f32_16x16x32_bf16 v[46:49], v[210:213], v[194:197], v[46:49]
	v_mfma_f32_16x16x32_bf16 v[42:45], v[218:221], v[194:197], v[42:45]
	v_mfma_f32_16x16x32_bf16 v[38:41], v[210:213], v[202:205], v[38:41]
	v_mfma_f32_16x16x32_bf16 v[30:33], v[218:221], v[202:205], v[30:33]
	v_mfma_f32_16x16x32_bf16 v[94:97], v[214:217], v[170:173], v[94:97]
	v_mfma_f32_16x16x32_bf16 v[90:93], v[222:225], v[170:173], v[90:93]
	v_mfma_f32_16x16x32_bf16 v[70:73], v[214:217], v[190:193], v[70:73]
	v_mfma_f32_16x16x32_bf16 v[66:69], v[222:225], v[190:193], v[66:69]
	v_mfma_f32_16x16x32_bf16 v[46:49], v[214:217], v[198:201], v[46:49]
	v_mfma_f32_16x16x32_bf16 v[42:45], v[222:225], v[198:201], v[42:45]
	v_mfma_f32_16x16x32_bf16 v[38:41], v[214:217], v[206:209], v[38:41]
	v_mfma_f32_16x16x32_bf16 v[30:33], v[222:225], v[206:209], v[30:33]
	s_setprio 0
	s_add_i32 s54, s54, 2
	s_add_u32 s20, s20, 0x100
	s_addc_u32 s21, s21, 0
	s_add_u32 s52, s52, 0x100
	s_addc_u32 s53, s53, 0
	s_cmp_gt_u32 s54, 13
	s_barrier
	s_cbranch_scc0 .LBB0_528
	v_lshl_add_u32 v144, s10, 8, v1
	s_cmp_lg_u32 s50, s45
	s_mov_b64 s[10:11], -1
	s_cbranch_scc0 .LBB0_531
	v_lshl_or_b32 v154, s50, 8, v147
	v_readlane_b32 s13, v255, 32
	v_ashrrev_i32_e32 v155, 31, v154
	v_lshlrev_b64 v[154:155], 1, v[154:155]
	v_mad_i64_i32 v[156:157], s[10:11], v144, s13, 0
	v_lshl_add_u64 v[156:157], v[156:157], 1, s[6:7]
	v_lshl_add_u64 v[156:157], v[156:157], 0, v[154:155]
	v_cvt_pk_bf16_f32 v126, v126, v127
	v_cvt_pk_bf16_f32 v127, v128, v129
	v_cvt_pk_bf16_f32 v128, v122, v123
	v_cvt_pk_bf16_f32 v129, v124, v125
	global_store_dwordx4 v[156:157], v[126:129], off offset:256
	v_cvt_pk_bf16_f32 v150, v86, v87
	v_cvt_pk_bf16_f32 v151, v88, v89
	v_or_b32_e32 v126, 16, v144
	v_mad_i64_i32 v[126:127], s[10:11], v126, s13, 0
	v_lshl_add_u64 v[126:127], v[126:127], 1, s[6:7]
	v_cvt_pk_bf16_f32 v152, v82, v83
	v_cvt_pk_bf16_f32 v153, v84, v85
	v_lshl_add_u64 v[126:127], v[126:127], 0, v[154:155]
	v_cvt_pk_bf16_f32 v118, v118, v119
	v_cvt_pk_bf16_f32 v119, v120, v121
	v_cvt_pk_bf16_f32 v120, v114, v115
	v_cvt_pk_bf16_f32 v121, v116, v117
	global_store_dwordx4 v[156:157], v[150:153], off
	global_store_dwordx4 v[126:127], v[118:121], off offset:256
	v_cvt_pk_bf16_f32 v122, v78, v79
	v_cvt_pk_bf16_f32 v123, v80, v81
	v_or_b32_e32 v118, 32, v144
	v_mad_i64_i32 v[118:119], s[10:11], v118, s13, 0
	v_lshl_add_u64 v[118:119], v[118:119], 1, s[6:7]
	v_cvt_pk_bf16_f32 v124, v74, v75
	v_cvt_pk_bf16_f32 v125, v76, v77
	v_lshl_add_u64 v[118:119], v[118:119], 0, v[154:155]
	v_cvt_pk_bf16_f32 v110, v110, v111
	v_cvt_pk_bf16_f32 v111, v112, v113
	v_cvt_pk_bf16_f32 v112, v106, v107
	v_cvt_pk_bf16_f32 v113, v108, v109
	global_store_dwordx4 v[126:127], v[122:125], off
	global_store_dwordx4 v[118:119], v[110:113], off offset:256
	v_cvt_pk_bf16_f32 v114, v62, v63
	v_cvt_pk_bf16_f32 v115, v64, v65
	v_or_b32_e32 v110, 48, v144
	v_mad_i64_i32 v[110:111], s[10:11], v110, s13, 0
	v_lshl_add_u64 v[110:111], v[110:111], 1, s[6:7]
	v_cvt_pk_bf16_f32 v116, v58, v59
	v_cvt_pk_bf16_f32 v117, v60, v61
	v_lshl_add_u64 v[110:111], v[110:111], 0, v[154:155]
	v_cvt_pk_bf16_f32 v102, v102, v103
	v_cvt_pk_bf16_f32 v103, v104, v105
	v_cvt_pk_bf16_f32 v104, v98, v99
	v_cvt_pk_bf16_f32 v105, v100, v101
	global_store_dwordx4 v[118:119], v[114:117], off
	global_store_dwordx4 v[110:111], v[102:105], off offset:256
	v_cvt_pk_bf16_f32 v106, v54, v55
	v_cvt_pk_bf16_f32 v107, v56, v57
	v_add_u32_e32 v102, 0x80, v144
	v_mad_i64_i32 v[102:103], s[10:11], v102, s13, 0
	v_lshl_add_u64 v[102:103], v[102:103], 1, s[6:7]
	v_cvt_pk_bf16_f32 v108, v50, v51
	v_cvt_pk_bf16_f32 v109, v52, v53
	v_lshl_add_u64 v[102:103], v[102:103], 0, v[154:155]
	v_cvt_pk_bf16_f32 v94, v94, v95
	v_cvt_pk_bf16_f32 v95, v96, v97
	v_cvt_pk_bf16_f32 v96, v90, v91
	v_cvt_pk_bf16_f32 v97, v92, v93
	global_store_dwordx4 v[110:111], v[106:109], off
	global_store_dwordx4 v[102:103], v[94:97], off offset:256
	v_cvt_pk_bf16_f32 v98, v34, v35
	v_cvt_pk_bf16_f32 v99, v36, v37
	v_add_u32_e32 v94, 0x90, v144
	v_mad_i64_i32 v[94:95], s[10:11], v94, s13, 0
	v_lshl_add_u64 v[94:95], v[94:95], 1, s[6:7]
	v_cvt_pk_bf16_f32 v100, v26, v27
	v_cvt_pk_bf16_f32 v101, v28, v29
	v_lshl_add_u64 v[94:95], v[94:95], 0, v[154:155]
	v_cvt_pk_bf16_f32 v70, v70, v71
	v_cvt_pk_bf16_f32 v71, v72, v73
	v_cvt_pk_bf16_f32 v72, v66, v67
	v_cvt_pk_bf16_f32 v73, v68, v69
	global_store_dwordx4 v[102:103], v[98:101], off
	global_store_dwordx4 v[94:95], v[70:73], off offset:256
	v_cvt_pk_bf16_f32 v90, v22, v23
	v_cvt_pk_bf16_f32 v91, v24, v25
	v_add_u32_e32 v70, 0xa0, v144
	v_mad_i64_i32 v[70:71], s[10:11], v70, s13, 0
	v_lshl_add_u64 v[70:71], v[70:71], 1, s[6:7]
	v_cvt_pk_bf16_f32 v92, v18, v19
	v_cvt_pk_bf16_f32 v93, v20, v21
	v_lshl_add_u64 v[70:71], v[70:71], 0, v[154:155]
	v_cvt_pk_bf16_f32 v46, v46, v47
	v_cvt_pk_bf16_f32 v47, v48, v49
	v_cvt_pk_bf16_f32 v48, v42, v43
	v_cvt_pk_bf16_f32 v49, v44, v45
	global_store_dwordx4 v[94:95], v[90:93], off
	global_store_dwordx4 v[70:71], v[46:49], off offset:256
	v_cvt_pk_bf16_f32 v66, v14, v15
	v_cvt_pk_bf16_f32 v67, v16, v17
	v_add_u32_e32 v46, 0xb0, v144
	v_mad_i64_i32 v[46:47], s[10:11], v46, s13, 0
	v_lshl_add_u64 v[46:47], v[46:47], 1, s[6:7]
	v_cvt_pk_bf16_f32 v68, v10, v11
	v_cvt_pk_bf16_f32 v69, v12, v13
	v_cvt_pk_bf16_f32 v42, v6, v7
	v_cvt_pk_bf16_f32 v43, v8, v9
	v_cvt_pk_bf16_f32 v44, v2, v3
	v_cvt_pk_bf16_f32 v45, v4, v5
	v_lshl_add_u64 v[46:47], v[46:47], 0, v[154:155]
	v_cvt_pk_bf16_f32 v38, v38, v39
	v_cvt_pk_bf16_f32 v39, v40, v41
	v_cvt_pk_bf16_f32 v40, v30, v31
	v_cvt_pk_bf16_f32 v41, v32, v33
	global_store_dwordx4 v[70:71], v[66:69], off
	global_store_dwordx4 v[46:47], v[42:45], off
	global_store_dwordx4 v[46:47], v[38:41], off offset:256
	s_mov_b64 s[10:11], 0

.LBB0_1408:
	s_add_u32 s16, s14, s6
	s_addc_u32 s17, s15, s7
	s_add_u32 s16, s16, 0x100
	s_addc_u32 s17, s17, 0
	s_add_u32 s48, s45, s6
	s_addc_u32 s49, s46, s7
	s_add_i32 s50, 0, 0x10000
	v_add_u32_e32 v158, s50, v164
	ds_read_b128 v[146:149], v158
	ds_read_b128 v[150:153], v158 offset:1024
	ds_read_b128 v[154:157], v158 offset:2048
	ds_read_b128 v[158:161], v158 offset:3072
	s_cmpk_eq_i32 s6, 0xf00
	s_cselect_b32 s19, s11, s17
	s_cselect_b32 s18, s10, s16
	s_cselect_b32 s17, s3, s49
	s_cselect_b32 s16, s44, s48
	v_lshl_add_u64 v[162:163], v[142:143], 0, s[6:7]
	s_add_i32 m0, s30, 0xc000
	ds_read_b128 v[168:171], v166
	ds_read_b128 v[172:175], v166 offset:1024
	ds_read_b128 v[186:189], v166 offset:2048
	ds_read_b128 v[190:193], v166 offset:3072
	ds_read_b128 v[194:197], v166 offset:4096
	ds_read_b128 v[198:201], v166 offset:5120
	ds_read_b128 v[202:205], v166 offset:6144
	ds_read_b128 v[206:209], v166 offset:7168
	global_load_lds_dwordx4 v[162:163], off
	v_lshl_add_u64 v[162:163], v[144:145], 0, s[6:7]
	s_add_i32 m0, s30, 0xe000
	s_nop 0
	global_load_lds_dwordx4 v[162:163], off
	s_waitcnt lgkmcnt(8)
	s_barrier
	s_waitcnt lgkmcnt(0)
	s_setprio 1
	s_waitcnt lgkmcnt(0)
	v_mfma_f32_16x16x32_bf16 v[126:129], v[146:149], v[168:171], v[126:129]
	v_mfma_f32_16x16x32_bf16 v[122:125], v[154:157], v[168:171], v[122:125]
	v_mfma_f32_16x16x32_bf16 v[110:113], v[146:149], v[186:189], v[110:113]
	v_mfma_f32_16x16x32_bf16 v[106:109], v[154:157], v[186:189], v[106:109]
	v_mfma_f32_16x16x32_bf16 v[94:97], v[146:149], v[194:197], v[94:97]
	v_mfma_f32_16x16x32_bf16 v[90:93], v[154:157], v[194:197], v[90:93]
	v_mfma_f32_16x16x32_bf16 v[78:81], v[146:149], v[202:205], v[78:81]
	v_mfma_f32_16x16x32_bf16 v[74:77], v[154:157], v[202:205], v[74:77]
	v_mfma_f32_16x16x32_bf16 v[126:129], v[150:153], v[172:175], v[126:129]
	v_mfma_f32_16x16x32_bf16 v[122:125], v[158:161], v[172:175], v[122:125]
	v_mfma_f32_16x16x32_bf16 v[110:113], v[150:153], v[190:193], v[110:113]
	v_mfma_f32_16x16x32_bf16 v[106:109], v[158:161], v[190:193], v[106:109]
	v_mfma_f32_16x16x32_bf16 v[94:97], v[150:153], v[198:201], v[94:97]
	v_mfma_f32_16x16x32_bf16 v[90:93], v[158:161], v[198:201], v[90:93]
	v_mfma_f32_16x16x32_bf16 v[78:81], v[150:153], v[206:209], v[78:81]
	v_mfma_f32_16x16x32_bf16 v[74:77], v[158:161], v[206:209], v[74:77]
	s_setprio 0
	s_barrier
	s_add_i32 s51, 0, 0x14000
	v_add_u32_e32 v162, s51, v164
	s_add_i32 s48, s50, s29
	ds_read_b128 v[210:213], v162
	ds_read_b128 v[214:217], v162 offset:1024
	ds_read_b128 v[218:221], v162 offset:2048
	ds_read_b128 v[222:225], v162 offset:3072
	v_lshl_add_u64 v[162:163], s[16:17], 0, v[132:133]
	s_mov_b32 m0, s48
	v_lshl_add_u64 v[176:177], s[16:17], 0, v[136:137]
	global_load_lds_dwordx4 v[162:163], off
	s_add_i32 m0, s48, 0x2000
	s_nop 0
	global_load_lds_dwordx4 v[176:177], off
	s_barrier
	s_waitcnt lgkmcnt(0)
	s_setprio 1
	s_waitcnt lgkmcnt(0)
	v_mfma_f32_16x16x32_bf16 v[118:121], v[210:213], v[168:171], v[118:121]
	v_mfma_f32_16x16x32_bf16 v[114:117], v[218:221], v[168:171], v[114:117]
	v_mfma_f32_16x16x32_bf16 v[102:105], v[210:213], v[186:189], v[102:105]
	v_mfma_f32_16x16x32_bf16 v[98:101], v[218:221], v[186:189], v[98:101]
	v_mfma_f32_16x16x32_bf16 v[86:89], v[210:213], v[194:197], v[86:89]
	v_mfma_f32_16x16x32_bf16 v[82:85], v[218:221], v[194:197], v[82:85]
	v_mfma_f32_16x16x32_bf16 v[70:73], v[210:213], v[202:205], v[70:73]
	v_mfma_f32_16x16x32_bf16 v[66:69], v[218:221], v[202:205], v[66:69]
	v_mfma_f32_16x16x32_bf16 v[118:121], v[214:217], v[172:175], v[118:121]
	v_mfma_f32_16x16x32_bf16 v[114:117], v[222:225], v[172:175], v[114:117]
	v_mfma_f32_16x16x32_bf16 v[102:105], v[214:217], v[190:193], v[102:105]
	v_mfma_f32_16x16x32_bf16 v[98:101], v[222:225], v[190:193], v[98:101]
	v_mfma_f32_16x16x32_bf16 v[86:89], v[214:217], v[198:201], v[86:89]
	v_mfma_f32_16x16x32_bf16 v[82:85], v[222:225], v[198:201], v[82:85]
	v_mfma_f32_16x16x32_bf16 v[70:73], v[214:217], v[206:209], v[70:73]
	v_mfma_f32_16x16x32_bf16 v[66:69], v[222:225], v[206:209], v[66:69]
	s_setprio 0
	s_mov_b32 m0, s30
	v_lshl_add_u64 v[226:227], s[18:19], 0, v[130:131]
	s_barrier
	ds_read_b128 v[168:171], v166 offset:16384
	ds_read_b128 v[172:175], v166 offset:17408
	ds_read_b128 v[186:189], v166 offset:18432
	ds_read_b128 v[190:193], v166 offset:19456
	ds_read_b128 v[194:197], v166 offset:20480
	ds_read_b128 v[198:201], v166 offset:21504
	ds_read_b128 v[202:205], v166 offset:22528
	ds_read_b128 v[206:209], v166 offset:23552
	global_load_lds_dwordx4 v[226:227], off
	v_lshl_add_u64 v[228:229], s[18:19], 0, v[134:135]
	s_mov_b32 m0, s31
	s_nop 0
	global_load_lds_dwordx4 v[228:229], off
	s_barrier
	s_waitcnt lgkmcnt(0)
	s_setprio 1
	s_waitcnt lgkmcnt(0)
	v_mfma_f32_16x16x32_bf16 v[62:65], v[146:149], v[168:171], v[62:65]
	v_mfma_f32_16x16x32_bf16 v[58:61], v[154:157], v[168:171], v[58:61]
	v_mfma_f32_16x16x32_bf16 v[46:49], v[146:149], v[186:189], v[46:49]
	v_mfma_f32_16x16x32_bf16 v[42:45], v[154:157], v[186:189], v[42:45]
	v_mfma_f32_16x16x32_bf16 v[30:33], v[146:149], v[194:197], v[30:33]
	v_mfma_f32_16x16x32_bf16 v[26:29], v[154:157], v[194:197], v[26:29]
	v_mfma_f32_16x16x32_bf16 v[14:17], v[146:149], v[202:205], v[14:17]
	v_mfma_f32_16x16x32_bf16 v[10:13], v[154:157], v[202:205], v[10:13]
	v_mfma_f32_16x16x32_bf16 v[62:65], v[150:153], v[172:175], v[62:65]
	v_mfma_f32_16x16x32_bf16 v[58:61], v[158:161], v[172:175], v[58:61]
	v_mfma_f32_16x16x32_bf16 v[46:49], v[150:153], v[190:193], v[46:49]
	v_mfma_f32_16x16x32_bf16 v[42:45], v[158:161], v[190:193], v[42:45]
	v_mfma_f32_16x16x32_bf16 v[30:33], v[150:153], v[198:201], v[30:33]
	v_mfma_f32_16x16x32_bf16 v[26:29], v[158:161], v[198:201], v[26:29]
	v_mfma_f32_16x16x32_bf16 v[14:17], v[150:153], v[206:209], v[14:17]
	v_mfma_f32_16x16x32_bf16 v[10:13], v[158:161], v[206:209], v[10:13]
	s_setprio 0
	s_barrier
	s_add_u32 s48, s16, 0x80000
	s_addc_u32 s49, s17, 0
	s_add_i32 s50, s51, s29
	s_mov_b32 m0, s50
	s_nop 0
	global_load_lds_dwordx4 v132, s[48:49]
	s_add_i32 m0, s50, 0x2000
	s_nop 0
	global_load_lds_dwordx4 v136, s[48:49]
	s_waitcnt vmcnt(6)
	s_barrier
	s_setprio 1
	v_mfma_f32_16x16x32_bf16 v[54:57], v[210:213], v[168:171], v[54:57]
	v_mfma_f32_16x16x32_bf16 v[50:53], v[218:221], v[168:171], v[50:53]
	v_mfma_f32_16x16x32_bf16 v[38:41], v[210:213], v[186:189], v[38:41]
	v_mfma_f32_16x16x32_bf16 v[34:37], v[218:221], v[186:189], v[34:37]
	v_mfma_f32_16x16x32_bf16 v[22:25], v[210:213], v[194:197], v[22:25]
	v_mfma_f32_16x16x32_bf16 v[18:21], v[218:221], v[194:197], v[18:21]
	v_mfma_f32_16x16x32_bf16 v[6:9], v[210:213], v[202:205], v[6:9]
	v_mfma_f32_16x16x32_bf16 v[2:5], v[218:221], v[202:205], v[2:5]
	v_mfma_f32_16x16x32_bf16 v[54:57], v[214:217], v[172:175], v[54:57]
	v_mfma_f32_16x16x32_bf16 v[50:53], v[222:225], v[172:175], v[50:53]
	v_mfma_f32_16x16x32_bf16 v[38:41], v[214:217], v[190:193], v[38:41]
	v_mfma_f32_16x16x32_bf16 v[34:37], v[222:225], v[190:193], v[34:37]
	v_mfma_f32_16x16x32_bf16 v[22:25], v[214:217], v[198:201], v[22:25]
	v_mfma_f32_16x16x32_bf16 v[18:21], v[222:225], v[198:201], v[18:21]
	v_mfma_f32_16x16x32_bf16 v[6:9], v[214:217], v[206:209], v[6:9]
	v_mfma_f32_16x16x32_bf16 v[2:5], v[222:225], v[206:209], v[2:5]
	s_setprio 0
	s_add_i32 s48, 0, 0x18000
	v_add_u32_e32 v158, s48, v164
	s_barrier
	ds_read_b128 v[146:149], v158
	ds_read_b128 v[150:153], v158 offset:1024
	ds_read_b128 v[154:157], v158 offset:2048
	ds_read_b128 v[158:161], v158 offset:3072
	s_add_u32 s18, s18, s80
	s_addc_u32 s19, s19, 0
	s_mov_b32 m0, s34
	ds_read_b128 v[168:171], v166 offset:32768
	ds_read_b128 v[172:175], v166 offset:33792
	ds_read_b128 v[186:189], v166 offset:34816
	ds_read_b128 v[190:193], v166 offset:35840
	ds_read_b128 v[194:197], v166 offset:36864
	ds_read_b128 v[198:201], v166 offset:37888
	ds_read_b128 v[202:205], v166 offset:38912
	ds_read_b128 v[206:209], v166 offset:39936
	global_load_lds_dwordx4 v130, s[18:19]
	s_mov_b32 m0, s35
	s_nop 0
	global_load_lds_dwordx4 v134, s[18:19]
	s_waitcnt lgkmcnt(8)
	s_barrier
	s_waitcnt lgkmcnt(0)
	s_setprio 1
	s_waitcnt lgkmcnt(0)
	v_mfma_f32_16x16x32_bf16 v[126:129], v[146:149], v[168:171], v[126:129]
	v_mfma_f32_16x16x32_bf16 v[122:125], v[154:157], v[168:171], v[122:125]
	v_mfma_f32_16x16x32_bf16 v[110:113], v[146:149], v[186:189], v[110:113]
	v_mfma_f32_16x16x32_bf16 v[106:109], v[154:157], v[186:189], v[106:109]
	v_mfma_f32_16x16x32_bf16 v[94:97], v[146:149], v[194:197], v[94:97]
	v_mfma_f32_16x16x32_bf16 v[90:93], v[154:157], v[194:197], v[90:93]
	v_mfma_f32_16x16x32_bf16 v[78:81], v[146:149], v[202:205], v[78:81]
	v_mfma_f32_16x16x32_bf16 v[74:77], v[154:157], v[202:205], v[74:77]
	v_mfma_f32_16x16x32_bf16 v[126:129], v[150:153], v[172:175], v[126:129]
	v_mfma_f32_16x16x32_bf16 v[122:125], v[158:161], v[172:175], v[122:125]
	v_mfma_f32_16x16x32_bf16 v[110:113], v[150:153], v[190:193], v[110:113]
	v_mfma_f32_16x16x32_bf16 v[106:109], v[158:161], v[190:193], v[106:109]
	v_mfma_f32_16x16x32_bf16 v[94:97], v[150:153], v[198:201], v[94:97]
	v_mfma_f32_16x16x32_bf16 v[90:93], v[158:161], v[198:201], v[90:93]
	v_mfma_f32_16x16x32_bf16 v[78:81], v[150:153], v[206:209], v[78:81]
	v_mfma_f32_16x16x32_bf16 v[74:77], v[158:161], v[206:209], v[74:77]
	s_setprio 0
	s_barrier
	s_add_i32 s18, 0, 0x1c000
	s_add_i32 s19, s48, s29
	v_add_u32_e32 v167, s18, v164
	v_lshl_add_u64 v[162:163], v[162:163], 0, s[0:1]
	s_mov_b32 m0, s19
	ds_read_b128 v[210:213], v167
	ds_read_b128 v[214:217], v167 offset:1024
	ds_read_b128 v[218:221], v167 offset:2048
	ds_read_b128 v[222:225], v167 offset:3072
	global_load_lds_dwordx4 v[162:163], off
	v_lshl_add_u64 v[162:163], v[176:177], 0, s[0:1]
	s_add_i32 m0, s19, 0x2000
	s_nop 0
	global_load_lds_dwordx4 v[162:163], off
	s_barrier
	s_waitcnt lgkmcnt(0)
	s_setprio 1
	s_waitcnt lgkmcnt(0)
	v_mfma_f32_16x16x32_bf16 v[118:121], v[210:213], v[168:171], v[118:121]
	v_mfma_f32_16x16x32_bf16 v[114:117], v[218:221], v[168:171], v[114:117]
	v_mfma_f32_16x16x32_bf16 v[102:105], v[210:213], v[186:189], v[102:105]
	v_mfma_f32_16x16x32_bf16 v[98:101], v[218:221], v[186:189], v[98:101]
	v_mfma_f32_16x16x32_bf16 v[86:89], v[210:213], v[194:197], v[86:89]
	v_mfma_f32_16x16x32_bf16 v[82:85], v[218:221], v[194:197], v[82:85]
	v_mfma_f32_16x16x32_bf16 v[70:73], v[210:213], v[202:205], v[70:73]
	v_mfma_f32_16x16x32_bf16 v[66:69], v[218:221], v[202:205], v[66:69]
	v_mfma_f32_16x16x32_bf16 v[118:121], v[214:217], v[172:175], v[118:121]
	v_mfma_f32_16x16x32_bf16 v[114:117], v[222:225], v[172:175], v[114:117]
	v_mfma_f32_16x16x32_bf16 v[102:105], v[214:217], v[190:193], v[102:105]
	v_mfma_f32_16x16x32_bf16 v[98:101], v[222:225], v[190:193], v[98:101]
	v_mfma_f32_16x16x32_bf16 v[86:89], v[214:217], v[198:201], v[86:89]
	v_mfma_f32_16x16x32_bf16 v[82:85], v[222:225], v[198:201], v[82:85]
	v_mfma_f32_16x16x32_bf16 v[70:73], v[214:217], v[206:209], v[70:73]
	v_mfma_f32_16x16x32_bf16 v[66:69], v[222:225], v[206:209], v[66:69]
	s_setprio 0
	s_mov_b32 m0, s38
	v_lshl_add_u64 v[162:163], v[226:227], 0, s[0:1]
	s_barrier
	ds_read_b128 v[168:171], v166 offset:49152
	ds_read_b128 v[172:175], v166 offset:50176
	ds_read_b128 v[186:189], v166 offset:51200
	ds_read_b128 v[190:193], v166 offset:52224
	ds_read_b128 v[194:197], v166 offset:53248
	ds_read_b128 v[198:201], v166 offset:54272
	ds_read_b128 v[202:205], v166 offset:55296
	ds_read_b128 v[206:209], v166 offset:56320
	global_load_lds_dwordx4 v[162:163], off
	v_lshl_add_u64 v[162:163], v[228:229], 0, s[0:1]
	s_mov_b32 m0, s39
	s_nop 0
	global_load_lds_dwordx4 v[162:163], off
	s_barrier
	s_waitcnt lgkmcnt(0)
	s_setprio 1
	s_waitcnt lgkmcnt(0)
	v_mfma_f32_16x16x32_bf16 v[62:65], v[146:149], v[168:171], v[62:65]
	v_mfma_f32_16x16x32_bf16 v[58:61], v[154:157], v[168:171], v[58:61]
	v_mfma_f32_16x16x32_bf16 v[46:49], v[146:149], v[186:189], v[46:49]
	v_mfma_f32_16x16x32_bf16 v[42:45], v[154:157], v[186:189], v[42:45]
	v_mfma_f32_16x16x32_bf16 v[30:33], v[146:149], v[194:197], v[30:33]
	v_mfma_f32_16x16x32_bf16 v[26:29], v[154:157], v[194:197], v[26:29]
	v_mfma_f32_16x16x32_bf16 v[14:17], v[146:149], v[202:205], v[14:17]
	v_mfma_f32_16x16x32_bf16 v[10:13], v[154:157], v[202:205], v[10:13]
	v_mfma_f32_16x16x32_bf16 v[62:65], v[150:153], v[172:175], v[62:65]
	v_mfma_f32_16x16x32_bf16 v[58:61], v[158:161], v[172:175], v[58:61]
	v_mfma_f32_16x16x32_bf16 v[46:49], v[150:153], v[190:193], v[46:49]
	v_mfma_f32_16x16x32_bf16 v[42:45], v[158:161], v[190:193], v[42:45]
	v_mfma_f32_16x16x32_bf16 v[30:33], v[150:153], v[198:201], v[30:33]
	v_mfma_f32_16x16x32_bf16 v[26:29], v[158:161], v[198:201], v[26:29]
	v_mfma_f32_16x16x32_bf16 v[14:17], v[150:153], v[206:209], v[14:17]
	v_mfma_f32_16x16x32_bf16 v[10:13], v[158:161], v[206:209], v[10:13]
	s_setprio 0
	s_barrier
	s_add_u32 s16, s16, 0x80080
	s_addc_u32 s17, s17, 0
	s_add_i32 s18, s18, s29
	s_mov_b32 m0, s18
	s_nop 0
	global_load_lds_dwordx4 v132, s[16:17]
	s_add_i32 m0, s18, 0x2000
	s_nop 0
	global_load_lds_dwordx4 v136, s[16:17]
	s_waitcnt vmcnt(6)
	s_barrier
	s_setprio 1
	v_mfma_f32_16x16x32_bf16 v[54:57], v[210:213], v[168:171], v[54:57]
	v_mfma_f32_16x16x32_bf16 v[50:53], v[218:221], v[168:171], v[50:53]
	v_mfma_f32_16x16x32_bf16 v[38:41], v[210:213], v[186:189], v[38:41]
	v_mfma_f32_16x16x32_bf16 v[34:37], v[218:221], v[186:189], v[34:37]
	v_mfma_f32_16x16x32_bf16 v[22:25], v[210:213], v[194:197], v[22:25]
	v_mfma_f32_16x16x32_bf16 v[18:21], v[218:221], v[194:197], v[18:21]
	v_mfma_f32_16x16x32_bf16 v[6:9], v[210:213], v[202:205], v[6:9]
	v_mfma_f32_16x16x32_bf16 v[2:5], v[218:221], v[202:205], v[2:5]
	v_mfma_f32_16x16x32_bf16 v[54:57], v[214:217], v[172:175], v[54:57]
	v_mfma_f32_16x16x32_bf16 v[50:53], v[222:225], v[172:175], v[50:53]
	v_mfma_f32_16x16x32_bf16 v[38:41], v[214:217], v[190:193], v[38:41]
	v_mfma_f32_16x16x32_bf16 v[34:37], v[222:225], v[190:193], v[34:37]
	v_mfma_f32_16x16x32_bf16 v[22:25], v[214:217], v[198:201], v[22:25]
	v_mfma_f32_16x16x32_bf16 v[18:21], v[222:225], v[198:201], v[18:21]
	v_mfma_f32_16x16x32_bf16 v[6:9], v[214:217], v[206:209], v[6:9]
	v_mfma_f32_16x16x32_bf16 v[2:5], v[222:225], v[206:209], v[2:5]
	s_setprio 0
	s_add_i32 s47, s47, 2
	s_add_u32 s6, s6, 0x100
	s_addc_u32 s7, s7, 0
	s_cmp_gt_u32 s47, 29
	s_barrier
	s_cbranch_scc0 .LBB0_1408
	s_ashr_i32 s3, s33, 5
	s_mul_hi_i32 s7, s3, 0x9000
	s_mul_i32 s3, s3, 0x9000
	v_lshl_or_b32 v168, s43, 8, v165
	s_add_u32 s6, s36, s3
	s_addc_u32 s7, s37, s7
	v_ashrrev_i32_e32 v169, 31, v168
	v_lshl_add_u64 v[162:163], v[168:169], 2, s[6:7]
	global_load_dwordx4 v[142:145], v[162:163], off offset:16
	global_load_dwordx4 v[146:149], v[162:163], off
	s_mov_b64 s[6:7], 0x80000
	s_and_b64 vcc, exec, s[4:5]
	s_mov_b32 s43, s2
	s_mov_b64 s[16:17], s[12:13]
	s_mov_b64 s[14:15], s[10:11]
	s_waitcnt vmcnt(0)
	v_pk_add_f32 v[150:151], v[144:145], 1.0 op_sel_hi:[1,0]
	v_pk_add_f32 v[154:155], v[142:143], 1.0 op_sel_hi:[1,0]
	global_load_dwordx4 v[158:161], v[162:163], off offset:528
	global_load_dwordx4 v[142:145], v[162:163], off offset:512
	v_lshl_add_u32 v162, s33, 8, v1
	v_ashrrev_i32_e32 v163, 31, v162
	v_pk_add_f32 v[156:157], v[146:147], 1.0 op_sel_hi:[1,0]
	v_pk_add_f32 v[152:153], v[148:149], 1.0 op_sel_hi:[1,0]
	s_mov_b32 s33, s42
	s_waitcnt vmcnt(0)
	v_pk_add_f32 v[146:147], v[144:145], 1.0 op_sel_hi:[1,0]
	v_pk_add_f32 v[144:145], v[158:159], 1.0 op_sel_hi:[1,0]
	v_lshlrev_b64 v[158:159], 12, v[162:163]
	v_pk_add_f32 v[148:149], v[142:143], 1.0 op_sel_hi:[1,0]
	v_pk_add_f32 v[142:143], v[160:161], 1.0 op_sel_hi:[1,0]
	v_lshl_add_u64 v[158:159], s[8:9], 0, v[158:159]
	v_lshlrev_b64 v[160:161], 1, v[168:169]
	v_lshl_add_u64 v[158:159], v[158:159], 0, v[160:161]
	global_load_dwordx4 v[168:171], v[158:159], off offset:2048
	s_waitcnt vmcnt(0)
	v_lshlrev_b32_e32 v172, 16, v168
	v_and_b32_e32 v173, 0xffff0000, v168
	v_lshlrev_b32_e32 v168, 16, v169
	v_and_b32_e32 v169, 0xffff0000, v169
	v_pk_fma_f32 v[128:129], v[128:129], v[152:153], v[168:169]
	v_lshlrev_b32_e32 v168, 16, v170
	v_and_b32_e32 v169, 0xffff0000, v170
	v_pk_fma_f32 v[168:169], v[122:123], v[154:155], v[168:169]
	v_lshlrev_b32_e32 v122, 16, v171
	v_and_b32_e32 v123, 0xffff0000, v171
	v_pk_fma_f32 v[126:127], v[126:127], v[156:157], v[172:173]
	v_pk_fma_f32 v[170:171], v[124:125], v[150:151], v[122:123]
	v_cvt_pk_bf16_f32 v122, v126, v127
	v_cvt_pk_bf16_f32 v123, v128, v129
	v_cvt_pk_bf16_f32 v124, v168, v169
	v_cvt_pk_bf16_f32 v125, v170, v171
	global_store_dwordx4 v[158:159], v[122:125], off offset:2048
	global_load_dwordx4 v[122:125], v[158:159], off offset:2304
	s_waitcnt vmcnt(0)
	v_lshlrev_b32_e32 v126, 16, v122
	v_and_b32_e32 v127, 0xffff0000, v122
	v_lshlrev_b32_e32 v122, 16, v123
	v_and_b32_e32 v123, 0xffff0000, v123
	v_pk_fma_f32 v[120:121], v[120:121], v[146:147], v[122:123]
	v_lshlrev_b32_e32 v122, 16, v124
	v_and_b32_e32 v123, 0xffff0000, v124
	v_pk_fma_f32 v[122:123], v[114:115], v[144:145], v[122:123]
	v_lshlrev_b32_e32 v114, 16, v125
	v_and_b32_e32 v115, 0xffff0000, v125
	v_pk_fma_f32 v[118:119], v[118:119], v[148:149], v[126:127]
	v_pk_fma_f32 v[124:125], v[116:117], v[142:143], v[114:115]
	v_cvt_pk_bf16_f32 v114, v118, v119
	v_cvt_pk_bf16_f32 v115, v120, v121
	v_cvt_pk_bf16_f32 v116, v122, v123
	v_cvt_pk_bf16_f32 v117, v124, v125
	global_store_dwordx4 v[158:159], v[114:117], off offset:2304
	s_nop 1
	v_or_b32_e32 v114, 16, v162
	v_ashrrev_i32_e32 v115, 31, v114
	v_lshlrev_b64 v[114:115], 12, v[114:115]
	v_lshl_add_u64 v[114:115], s[8:9], 0, v[114:115]
	v_lshl_add_u64 v[118:119], v[114:115], 0, v[160:161]
	global_load_dwordx4 v[114:117], v[118:119], off offset:2048
	s_waitcnt vmcnt(0)
	v_lshlrev_b32_e32 v120, 16, v114
	v_and_b32_e32 v121, 0xffff0000, v114
	v_lshlrev_b32_e32 v114, 16, v115
	v_and_b32_e32 v115, 0xffff0000, v115
	v_pk_fma_f32 v[112:113], v[112:113], v[152:153], v[114:115]
	v_lshlrev_b32_e32 v114, 16, v116
	v_and_b32_e32 v115, 0xffff0000, v116
	v_pk_fma_f32 v[114:115], v[106:107], v[154:155], v[114:115]
	v_lshlrev_b32_e32 v106, 16, v117
	v_and_b32_e32 v107, 0xffff0000, v117
	v_pk_fma_f32 v[110:111], v[110:111], v[156:157], v[120:121]
	v_pk_fma_f32 v[116:117], v[108:109], v[150:151], v[106:107]
	v_cvt_pk_bf16_f32 v106, v110, v111
	v_cvt_pk_bf16_f32 v107, v112, v113
	v_cvt_pk_bf16_f32 v108, v114, v115
	v_cvt_pk_bf16_f32 v109, v116, v117
	global_store_dwordx4 v[118:119], v[106:109], off offset:2048
	global_load_dwordx4 v[106:109], v[118:119], off offset:2304
	s_waitcnt vmcnt(0)
	v_lshlrev_b32_e32 v110, 16, v106
	v_and_b32_e32 v111, 0xffff0000, v106
	v_lshlrev_b32_e32 v106, 16, v107
	v_and_b32_e32 v107, 0xffff0000, v107
	v_pk_fma_f32 v[104:105], v[104:105], v[146:147], v[106:107]
	v_lshlrev_b32_e32 v106, 16, v108
	v_and_b32_e32 v107, 0xffff0000, v108
	v_pk_fma_f32 v[106:107], v[98:99], v[144:145], v[106:107]
	v_lshlrev_b32_e32 v98, 16, v109
	v_and_b32_e32 v99, 0xffff0000, v109
	v_pk_fma_f32 v[102:103], v[102:103], v[148:149], v[110:111]
	v_pk_fma_f32 v[108:109], v[100:101], v[142:143], v[98:99]
	v_cvt_pk_bf16_f32 v98, v102, v103
	v_cvt_pk_bf16_f32 v99, v104, v105
	v_cvt_pk_bf16_f32 v100, v106, v107
	v_cvt_pk_bf16_f32 v101, v108, v109
	global_store_dwordx4 v[118:119], v[98:101], off offset:2304
	s_nop 1
	v_or_b32_e32 v98, 32, v162
	v_ashrrev_i32_e32 v99, 31, v98
	v_lshlrev_b64 v[98:99], 12, v[98:99]
	v_lshl_add_u64 v[98:99], s[8:9], 0, v[98:99]
	v_lshl_add_u64 v[102:103], v[98:99], 0, v[160:161]
	global_load_dwordx4 v[98:101], v[102:103], off offset:2048
	s_waitcnt vmcnt(0)
	v_lshlrev_b32_e32 v104, 16, v98
	v_and_b32_e32 v105, 0xffff0000, v98
	v_lshlrev_b32_e32 v98, 16, v99
	v_and_b32_e32 v99, 0xffff0000, v99
	v_pk_fma_f32 v[96:97], v[96:97], v[152:153], v[98:99]
	v_lshlrev_b32_e32 v98, 16, v100
	v_and_b32_e32 v99, 0xffff0000, v100
	v_pk_fma_f32 v[98:99], v[90:91], v[154:155], v[98:99]
	v_lshlrev_b32_e32 v90, 16, v101
	v_and_b32_e32 v91, 0xffff0000, v101
	v_pk_fma_f32 v[94:95], v[94:95], v[156:157], v[104:105]
	v_pk_fma_f32 v[100:101], v[92:93], v[150:151], v[90:91]
	v_cvt_pk_bf16_f32 v90, v94, v95
	v_cvt_pk_bf16_f32 v91, v96, v97
	v_cvt_pk_bf16_f32 v92, v98, v99
	v_cvt_pk_bf16_f32 v93, v100, v101
	global_store_dwordx4 v[102:103], v[90:93], off offset:2048
	global_load_dwordx4 v[90:93], v[102:103], off offset:2304
	s_waitcnt vmcnt(0)
	v_lshlrev_b32_e32 v94, 16, v90
	v_and_b32_e32 v95, 0xffff0000, v90
	v_lshlrev_b32_e32 v90, 16, v91
	v_and_b32_e32 v91, 0xffff0000, v91
	v_pk_fma_f32 v[88:89], v[88:89], v[146:147], v[90:91]
	v_lshlrev_b32_e32 v90, 16, v92
	v_and_b32_e32 v91, 0xffff0000, v92
	v_pk_fma_f32 v[90:91], v[82:83], v[144:145], v[90:91]
	v_lshlrev_b32_e32 v82, 16, v93
	v_and_b32_e32 v83, 0xffff0000, v93
	v_pk_fma_f32 v[86:87], v[86:87], v[148:149], v[94:95]
	v_pk_fma_f32 v[92:93], v[84:85], v[142:143], v[82:83]
	v_cvt_pk_bf16_f32 v82, v86, v87
	v_cvt_pk_bf16_f32 v83, v88, v89
	v_cvt_pk_bf16_f32 v84, v90, v91
	v_cvt_pk_bf16_f32 v85, v92, v93
	global_store_dwordx4 v[102:103], v[82:85], off offset:2304
	s_nop 1
	v_or_b32_e32 v82, 48, v162
	v_ashrrev_i32_e32 v83, 31, v82
	v_lshlrev_b64 v[82:83], 12, v[82:83]
	v_lshl_add_u64 v[82:83], s[8:9], 0, v[82:83]
	v_lshl_add_u64 v[82:83], v[82:83], 0, v[160:161]
	global_load_dwordx4 v[84:87], v[82:83], off offset:2048
	s_waitcnt vmcnt(0)
	v_lshlrev_b32_e32 v88, 16, v84
	v_and_b32_e32 v89, 0xffff0000, v84
	v_lshlrev_b32_e32 v84, 16, v85
	v_and_b32_e32 v85, 0xffff0000, v85
	v_pk_fma_f32 v[80:81], v[80:81], v[152:153], v[84:85]
	v_lshlrev_b32_e32 v84, 16, v86
	v_and_b32_e32 v85, 0xffff0000, v86
	v_pk_fma_f32 v[84:85], v[74:75], v[154:155], v[84:85]
	v_lshlrev_b32_e32 v74, 16, v87
	v_and_b32_e32 v75, 0xffff0000, v87
	v_pk_fma_f32 v[78:79], v[78:79], v[156:157], v[88:89]
	v_pk_fma_f32 v[86:87], v[76:77], v[150:151], v[74:75]
	v_cvt_pk_bf16_f32 v74, v78, v79
	v_cvt_pk_bf16_f32 v75, v80, v81
	v_cvt_pk_bf16_f32 v76, v84, v85
	v_cvt_pk_bf16_f32 v77, v86, v87
	global_store_dwordx4 v[82:83], v[74:77], off offset:2048
	global_load_dwordx4 v[74:77], v[82:83], off offset:2304
	s_waitcnt vmcnt(0)
	v_lshlrev_b32_e32 v78, 16, v74
	v_and_b32_e32 v79, 0xffff0000, v74
	v_lshlrev_b32_e32 v74, 16, v75
	v_and_b32_e32 v75, 0xffff0000, v75
	v_pk_fma_f32 v[72:73], v[72:73], v[146:147], v[74:75]
	v_lshlrev_b32_e32 v74, 16, v76
	v_and_b32_e32 v75, 0xffff0000, v76
	v_pk_fma_f32 v[74:75], v[66:67], v[144:145], v[74:75]
	v_lshlrev_b32_e32 v66, 16, v77
	v_and_b32_e32 v67, 0xffff0000, v77
	v_pk_fma_f32 v[70:71], v[70:71], v[148:149], v[78:79]
	v_pk_fma_f32 v[76:77], v[68:69], v[142:143], v[66:67]
	v_cvt_pk_bf16_f32 v66, v70, v71
	v_cvt_pk_bf16_f32 v67, v72, v73
	v_cvt_pk_bf16_f32 v68, v74, v75
	v_cvt_pk_bf16_f32 v69, v76, v77
	v_lshl_add_u64 v[70:71], v[158:159], 0, s[6:7]
	global_store_dwordx4 v[82:83], v[66:69], off offset:2304
	global_load_dwordx4 v[66:69], v[70:71], off offset:2048
	s_mov_b64 s[6:7], 0x90000
	s_waitcnt vmcnt(0)
	v_lshlrev_b32_e32 v72, 16, v66
	v_and_b32_e32 v73, 0xffff0000, v66
	v_lshlrev_b32_e32 v66, 16, v67
	v_and_b32_e32 v67, 0xffff0000, v67
	v_pk_fma_f32 v[64:65], v[64:65], v[152:153], v[66:67]
	v_lshlrev_b32_e32 v66, 16, v68
	v_and_b32_e32 v67, 0xffff0000, v68
	v_pk_fma_f32 v[66:67], v[58:59], v[154:155], v[66:67]
	v_lshlrev_b32_e32 v58, 16, v69
	v_and_b32_e32 v59, 0xffff0000, v69
	v_pk_fma_f32 v[62:63], v[62:63], v[156:157], v[72:73]
	v_pk_fma_f32 v[68:69], v[60:61], v[150:151], v[58:59]
	v_cvt_pk_bf16_f32 v58, v62, v63
	v_cvt_pk_bf16_f32 v59, v64, v65
	v_cvt_pk_bf16_f32 v60, v66, v67
	v_cvt_pk_bf16_f32 v61, v68, v69
	global_store_dwordx4 v[70:71], v[58:61], off offset:2048
	global_load_dwordx4 v[58:61], v[70:71], off offset:2304
	s_waitcnt vmcnt(0)
	v_lshlrev_b32_e32 v62, 16, v58
	v_and_b32_e32 v63, 0xffff0000, v58
	v_lshlrev_b32_e32 v58, 16, v59
	v_and_b32_e32 v59, 0xffff0000, v59
	v_pk_fma_f32 v[56:57], v[56:57], v[146:147], v[58:59]
	v_lshlrev_b32_e32 v58, 16, v60
	v_and_b32_e32 v59, 0xffff0000, v60
	v_pk_fma_f32 v[58:59], v[50:51], v[144:145], v[58:59]
	v_lshlrev_b32_e32 v50, 16, v61
	v_and_b32_e32 v51, 0xffff0000, v61
	v_pk_fma_f32 v[54:55], v[54:55], v[148:149], v[62:63]
	v_pk_fma_f32 v[60:61], v[52:53], v[142:143], v[50:51]
	v_cvt_pk_bf16_f32 v50, v54, v55
	v_cvt_pk_bf16_f32 v51, v56, v57
	v_cvt_pk_bf16_f32 v52, v58, v59
	v_cvt_pk_bf16_f32 v53, v60, v61
	v_lshl_add_u64 v[54:55], v[158:159], 0, s[6:7]
	global_store_dwordx4 v[70:71], v[50:53], off offset:2304
	global_load_dwordx4 v[50:53], v[54:55], off offset:2048
	s_mov_b64 s[6:7], 0xa0000
	s_waitcnt vmcnt(0)
	v_lshlrev_b32_e32 v56, 16, v50
	v_and_b32_e32 v57, 0xffff0000, v50
	v_lshlrev_b32_e32 v50, 16, v51
	v_and_b32_e32 v51, 0xffff0000, v51
	v_pk_fma_f32 v[48:49], v[48:49], v[152:153], v[50:51]
	v_lshlrev_b32_e32 v50, 16, v52
	v_and_b32_e32 v51, 0xffff0000, v52
	v_pk_fma_f32 v[50:51], v[42:43], v[154:155], v[50:51]
	v_lshlrev_b32_e32 v42, 16, v53
	v_and_b32_e32 v43, 0xffff0000, v53
	v_pk_fma_f32 v[46:47], v[46:47], v[156:157], v[56:57]
	v_pk_fma_f32 v[52:53], v[44:45], v[150:151], v[42:43]
	v_cvt_pk_bf16_f32 v42, v46, v47
	v_cvt_pk_bf16_f32 v43, v48, v49
	v_cvt_pk_bf16_f32 v44, v50, v51
	v_cvt_pk_bf16_f32 v45, v52, v53
	global_store_dwordx4 v[54:55], v[42:45], off offset:2048
	global_load_dwordx4 v[42:45], v[54:55], off offset:2304
	s_waitcnt vmcnt(0)
	v_lshlrev_b32_e32 v46, 16, v42
	v_and_b32_e32 v47, 0xffff0000, v42
	v_lshlrev_b32_e32 v42, 16, v43
	v_and_b32_e32 v43, 0xffff0000, v43
	v_pk_fma_f32 v[40:41], v[40:41], v[146:147], v[42:43]
	v_lshlrev_b32_e32 v42, 16, v44
	v_and_b32_e32 v43, 0xffff0000, v44
	v_pk_fma_f32 v[42:43], v[34:35], v[144:145], v[42:43]
	v_lshlrev_b32_e32 v34, 16, v45
	v_and_b32_e32 v35, 0xffff0000, v45
	v_pk_fma_f32 v[38:39], v[38:39], v[148:149], v[46:47]
	v_pk_fma_f32 v[44:45], v[36:37], v[142:143], v[34:35]
	v_cvt_pk_bf16_f32 v34, v38, v39
	v_cvt_pk_bf16_f32 v35, v40, v41
	v_cvt_pk_bf16_f32 v36, v42, v43
	v_cvt_pk_bf16_f32 v37, v44, v45
	v_lshl_add_u64 v[38:39], v[158:159], 0, s[6:7]
	global_store_dwordx4 v[54:55], v[34:37], off offset:2304
	global_load_dwordx4 v[34:37], v[38:39], off offset:2048
	s_mov_b64 s[6:7], 0xb0000
	s_waitcnt vmcnt(0)
	v_lshlrev_b32_e32 v40, 16, v34
	v_and_b32_e32 v41, 0xffff0000, v34
	v_lshlrev_b32_e32 v34, 16, v35
	v_and_b32_e32 v35, 0xffff0000, v35
	v_pk_fma_f32 v[32:33], v[32:33], v[152:153], v[34:35]
	v_lshlrev_b32_e32 v34, 16, v36
	v_and_b32_e32 v35, 0xffff0000, v36
	v_pk_fma_f32 v[34:35], v[26:27], v[154:155], v[34:35]
	v_lshlrev_b32_e32 v26, 16, v37
	v_and_b32_e32 v27, 0xffff0000, v37
	v_pk_fma_f32 v[30:31], v[30:31], v[156:157], v[40:41]
	v_pk_fma_f32 v[36:37], v[28:29], v[150:151], v[26:27]
	v_cvt_pk_bf16_f32 v26, v30, v31
	v_cvt_pk_bf16_f32 v27, v32, v33
	v_cvt_pk_bf16_f32 v28, v34, v35
	v_cvt_pk_bf16_f32 v29, v36, v37
	global_store_dwordx4 v[38:39], v[26:29], off offset:2048
	global_load_dwordx4 v[26:29], v[38:39], off offset:2304
	s_waitcnt vmcnt(0)
	v_lshlrev_b32_e32 v30, 16, v26
	v_and_b32_e32 v31, 0xffff0000, v26
	v_lshlrev_b32_e32 v26, 16, v27
	v_and_b32_e32 v27, 0xffff0000, v27
	v_pk_fma_f32 v[24:25], v[24:25], v[146:147], v[26:27]
	v_lshlrev_b32_e32 v26, 16, v28
	v_and_b32_e32 v27, 0xffff0000, v28
	v_pk_fma_f32 v[26:27], v[18:19], v[144:145], v[26:27]
	v_lshlrev_b32_e32 v18, 16, v29
	v_and_b32_e32 v19, 0xffff0000, v29
	v_pk_fma_f32 v[22:23], v[22:23], v[148:149], v[30:31]
	v_pk_fma_f32 v[28:29], v[20:21], v[142:143], v[18:19]
	v_cvt_pk_bf16_f32 v18, v22, v23
	v_cvt_pk_bf16_f32 v19, v24, v25
	v_cvt_pk_bf16_f32 v20, v26, v27
	v_cvt_pk_bf16_f32 v21, v28, v29
	global_store_dwordx4 v[38:39], v[18:21], off offset:2304
	s_nop 1
	v_lshl_add_u64 v[18:19], v[158:159], 0, s[6:7]
	global_load_dwordx4 v[20:23], v[18:19], off offset:2048
	s_waitcnt vmcnt(0)
	v_lshlrev_b32_e32 v24, 16, v20
	v_and_b32_e32 v25, 0xffff0000, v20
	v_lshlrev_b32_e32 v20, 16, v21
	v_and_b32_e32 v21, 0xffff0000, v21
	v_pk_fma_f32 v[16:17], v[16:17], v[152:153], v[20:21]
	v_lshlrev_b32_e32 v20, 16, v22
	v_and_b32_e32 v21, 0xffff0000, v22
	v_pk_fma_f32 v[20:21], v[10:11], v[154:155], v[20:21]
	v_lshlrev_b32_e32 v10, 16, v23
	v_and_b32_e32 v11, 0xffff0000, v23
	v_pk_fma_f32 v[14:15], v[14:15], v[156:157], v[24:25]
	v_pk_fma_f32 v[22:23], v[12:13], v[150:151], v[10:11]
	v_cvt_pk_bf16_f32 v10, v14, v15
	v_cvt_pk_bf16_f32 v11, v16, v17
	v_cvt_pk_bf16_f32 v12, v20, v21
	v_cvt_pk_bf16_f32 v13, v22, v23
	global_store_dwordx4 v[18:19], v[10:13], off offset:2048
	global_load_dwordx4 v[10:13], v[18:19], off offset:2304
	s_waitcnt vmcnt(0)
	v_lshlrev_b32_e32 v14, 16, v10
	v_and_b32_e32 v15, 0xffff0000, v10
	v_lshlrev_b32_e32 v10, 16, v11
	v_and_b32_e32 v11, 0xffff0000, v11
	v_pk_fma_f32 v[8:9], v[8:9], v[146:147], v[10:11]
	v_lshlrev_b32_e32 v10, 16, v12
	v_and_b32_e32 v11, 0xffff0000, v12
	v_pk_fma_f32 v[10:11], v[2:3], v[144:145], v[10:11]
	v_lshlrev_b32_e32 v2, 16, v13
	v_and_b32_e32 v3, 0xffff0000, v13
	v_pk_fma_f32 v[6:7], v[6:7], v[148:149], v[14:15]
	v_pk_fma_f32 v[12:13], v[4:5], v[142:143], v[2:3]
	v_cvt_pk_bf16_f32 v2, v6, v7
	v_cvt_pk_bf16_f32 v3, v8, v9
	v_cvt_pk_bf16_f32 v4, v10, v11
	v_cvt_pk_bf16_f32 v5, v12, v13
	global_store_dwordx4 v[18:19], v[2:5], off offset:2304
	s_cbranch_vccz .LBB0_1399
	s_waitcnt vmcnt(0)
	s_cmpk_gt_u32 s22, 0xff
	s_cbranch_scc1 .LBB0_1412
	s_barrier
